# v13: v12 + first 19 key-row loads of a sample item issued before the q-partial loads
# baseline (speedup 1.0000x reference)
; DI void attn_sample_item(const Params& p, int item, ldsp lds, int tid_) {
;     ...
;   for (int t = 0; t < 4; ++t) { f32x4 a = {0.f, 0.f, 0.f, 0.f}; const float* pp = (const float*)(p.ws + B_PART) + (size_t)(b * 4 + t) * 1024 + h * 256 + lane * 4;
; #pragma unroll
;     for (int kp = 0; kp < 4; ++kp) a += *(const f32x4*)(pp + (size_t)kp * 512 * 1024);
;     q[t][0] = a[0] * 0.0625f; q[t][1] = a[1] * 0.0625f; q[t][2] = a[2] * 0.0625f; q[t][3] = a[3] * 0.0625f; }
;   const bool b0 = lane & 1, b1 = lane & 2;
;   f32x4 kvA[16], kvB[16];
; #pragma unroll
;   for (int j = 0; j < 16; ++j) kvA[j] = __builtin_nontemporal_load((const f32x4*)(ck + (size_t)(wid * 32 + j) * 1024 + lane * 4));
; #pragma unroll
;   for (int j = 0; j < 16; ++j) kvB[j] = __builtin_nontemporal_load((const f32x4*)(ck + (size_t)(wid * 32 + 16 + j) * 1024 + lane * 4));
.LBB0_1604:
	s_ashr_i32 s4, s40, 2
	s_ashr_i32 s5, s4, 31
	s_lshl_b64 s[4:5], s[4:5], 18
	s_and_b32 s26, s0, 0x300
	v_mov_b32_e32 v222, v212
	s_or_b32 s4, s4, s26
	s_and_b32 s28, s40, -4
	s_lshl_b32 s6, s26, 2
	s_add_u32 s6, s36, s6
	v_and_b32_e32 v223, 63, v222
	s_addc_u32 s7, s37, 0
	v_lshlrev_b32_e32 v144, 4, v223
	s_lshl_b64 s[60:61], s[4:5], 2
	s_add_u32 s60, s12, s60
	s_addc_u32 s61, s13, s61
	v_ashrrev_i32_e32 v244, 6, v222
	v_lshlrev_b32_e32 v236, 5, v244
	v_lshlrev_b32_e32 v162, 12, v236
	v_mov_b32_e32 v163, 0
	v_add_u32_e32 v124, v162, v144
	global_load_dwordx4 v[124:127], v124, s[60:61] nt
	v_or_b32_e32 v240, 1, v236
	v_lshlrev_b32_e32 v166, 12, v240
	v_mov_b32_e32 v167, 0
	v_add_u32_e32 v120, v166, v144
	global_load_dwordx4 v[120:123], v120, s[60:61] nt
	v_or_b32_e32 v240, 2, v236
	v_lshlrev_b32_e32 v168, 12, v240
	v_mov_b32_e32 v169, 0
	v_add_u32_e32 v116, v168, v144
	global_load_dwordx4 v[116:119], v116, s[60:61] nt
	v_or_b32_e32 v240, 3, v236
	v_lshlrev_b32_e32 v172, 12, v240
	v_mov_b32_e32 v173, 0
	v_add_u32_e32 v112, v172, v144
	global_load_dwordx4 v[112:115], v112, s[60:61] nt
	v_or_b32_e32 v240, 4, v236
	v_lshlrev_b32_e32 v176, 12, v240
	v_mov_b32_e32 v177, 0
	v_add_u32_e32 v108, v176, v144
	global_load_dwordx4 v[108:111], v108, s[60:61] nt
	v_or_b32_e32 v240, 5, v236
	v_lshlrev_b32_e32 v180, 12, v240
	v_mov_b32_e32 v181, 0
	v_add_u32_e32 v104, v180, v144
	global_load_dwordx4 v[104:107], v104, s[60:61] nt
	v_or_b32_e32 v240, 6, v236
	v_lshlrev_b32_e32 v182, 12, v240
	v_mov_b32_e32 v183, 0
	v_add_u32_e32 v100, v182, v144
	global_load_dwordx4 v[100:103], v100, s[60:61] nt
	v_or_b32_e32 v240, 7, v236
	v_lshlrev_b32_e32 v186, 12, v240
	v_mov_b32_e32 v187, 0
	v_add_u32_e32 v96, v186, v144
	global_load_dwordx4 v[96:99], v96, s[60:61] nt
	v_or_b32_e32 v240, 8, v236
	v_lshlrev_b32_e32 v190, 12, v240
	v_mov_b32_e32 v191, 0
	v_add_u32_e32 v92, v190, v144
	global_load_dwordx4 v[92:95], v92, s[60:61] nt
	v_or_b32_e32 v240, 9, v236
	v_lshlrev_b32_e32 v194, 12, v240
	v_mov_b32_e32 v195, 0
	v_add_u32_e32 v88, v194, v144
	global_load_dwordx4 v[88:91], v88, s[60:61] nt
	v_or_b32_e32 v240, 10, v236
	v_lshlrev_b32_e32 v198, 12, v240
	v_mov_b32_e32 v199, 0
	v_add_u32_e32 v84, v198, v144
	global_load_dwordx4 v[84:87], v84, s[60:61] nt
	v_or_b32_e32 v240, 11, v236
	v_lshlrev_b32_e32 v200, 12, v240
	v_mov_b32_e32 v201, 0
	v_add_u32_e32 v80, v200, v144
	global_load_dwordx4 v[80:83], v80, s[60:61] nt
	v_or_b32_e32 v240, 12, v236
	v_lshlrev_b32_e32 v202, 12, v240
	v_mov_b32_e32 v203, 0
	v_add_u32_e32 v76, v202, v144
	global_load_dwordx4 v[76:79], v76, s[60:61] nt
	v_or_b32_e32 v240, 13, v236
	v_lshlrev_b32_e32 v204, 12, v240
	v_mov_b32_e32 v205, 0
	v_add_u32_e32 v72, v204, v144
	global_load_dwordx4 v[72:75], v72, s[60:61] nt
	v_or_b32_e32 v240, 14, v236
	v_lshlrev_b32_e32 v206, 12, v240
	v_mov_b32_e32 v207, 0
	v_add_u32_e32 v68, v206, v144
	global_load_dwordx4 v[68:71], v68, s[60:61] nt
	v_or_b32_e32 v240, 15, v236
	v_lshlrev_b32_e32 v208, 12, v240
	v_mov_b32_e32 v209, 0
	v_add_u32_e32 v64, v208, v144
	global_load_dwordx4 v[64:67], v64, s[60:61] nt
	v_or_b32_e32 v240, 16, v236
	v_lshlrev_b32_e32 v146, 12, v240
	v_mov_b32_e32 v147, 0
	v_add_u32_e32 v60, v146, v144
	global_load_dwordx4 v[60:63], v60, s[60:61] nt
	v_or_b32_e32 v240, 17, v236
	v_lshlrev_b32_e32 v148, 12, v240
	v_mov_b32_e32 v149, 0
	v_add_u32_e32 v56, v148, v144
	global_load_dwordx4 v[56:59], v56, s[60:61] nt
	v_or_b32_e32 v240, 18, v236
	v_lshlrev_b32_e32 v150, 12, v240
	v_mov_b32_e32 v151, 0
	v_add_u32_e32 v52, v150, v144
	global_load_dwordx4 v[52:55], v52, s[60:61] nt
	s_ashr_i32 s29, s28, 31
	v_lshl_add_u64 v[48:49], s[6:7], 0, v[144:145]
	s_lshl_b64 s[6:7], s[28:29], 12
	v_lshl_add_u64 v[8:9], v[48:49], 0, s[6:7]
	v_add_co_u32_e32 v4, vcc, s3, v8
	s_or_b32 s6, s28, 1
	s_nop 0
	v_addc_co_u32_e32 v5, vcc, 0, v9, vcc
	v_add_co_u32_e32 v10, vcc, s33, v8
	s_ashr_i32 s7, s6, 31
	s_nop 0
	v_addc_co_u32_e32 v11, vcc, 0, v9, vcc
	v_add_co_u32_e32 v12, vcc, s38, v8
	s_lshl_b64 s[6:7], s[6:7], 12
	s_nop 0
	v_addc_co_u32_e32 v13, vcc, 0, v9, vcc
	v_lshl_add_u64 v[24:25], v[48:49], 0, s[6:7]
	v_add_co_u32_e32 v20, vcc, s3, v24
	s_or_b32 s6, s28, 2
	s_nop 0
	v_addc_co_u32_e32 v21, vcc, 0, v25, vcc
	v_add_co_u32_e32 v26, vcc, s33, v24
	s_ashr_i32 s7, s6, 31
	s_nop 0
	v_addc_co_u32_e32 v27, vcc, 0, v25, vcc
	v_add_co_u32_e32 v28, vcc, s38, v24
	s_lshl_b64 s[6:7], s[6:7], 12
	global_load_dwordx4 v[0:3], v[8:9], off
	s_nop 0
	global_load_dwordx4 v[4:7], v[4:5], off
	v_addc_co_u32_e32 v29, vcc, 0, v25, vcc
	v_lshl_add_u64 v[44:45], v[48:49], 0, s[6:7]
	global_load_dwordx4 v[8:11], v[10:11], off
	s_nop 0
	global_load_dwordx4 v[12:15], v[12:13], off
	s_nop 0
	global_load_dwordx4 v[16:19], v[24:25], off
	s_nop 0
	global_load_dwordx4 v[20:23], v[20:21], off
	v_add_co_u32_e32 v36, vcc, s3, v44
	global_load_dwordx4 v[24:27], v[26:27], off
	s_nop 0
	global_load_dwordx4 v[28:31], v[28:29], off
	v_addc_co_u32_e32 v37, vcc, 0, v45, vcc
	v_add_co_u32_e32 v40, vcc, s33, v44
	global_load_dwordx4 v[32:35], v[44:45], off
	s_nop 0
	global_load_dwordx4 v[36:39], v[36:37], off
	v_addc_co_u32_e32 v41, vcc, 0, v45, vcc
	v_add_co_u32_e32 v44, vcc, s38, v44
	global_load_dwordx4 v[40:43], v[40:41], off
	s_nop 0
	v_addc_co_u32_e32 v45, vcc, 0, v45, vcc
	global_load_dwordx4 v[44:47], v[44:45], off
	s_or_b32 s6, s40, 3
	s_ashr_i32 s7, s6, 31
	s_lshl_b64 s[6:7], s[6:7], 12
	s_lshl_b64 s[30:31], s[4:5], 2
	s_add_u32 s4, s12, s30
	s_addc_u32 s5, s13, s31
	s_waitcnt vmcnt(11)
	v_pk_add_f32 v[2:3], v[2:3], 0 op_sel_hi:[1,0]
	v_pk_add_f32 v[0:1], v[0:1], 0 op_sel_hi:[1,0]
	s_waitcnt vmcnt(10)
; DI void attn_sample_item(const Params& p, int item, ldsp lds, int tid_) {
;     ...
;   for (int t = 0; t < 4; ++t) { f32x4 a = {0.f, 0.f, 0.f, 0.f}; const float* pp = (const float*)(p.ws + B_PART) + (size_t)(b * 4 + t) * 1024 + h * 256 + lane * 4;
; #pragma unroll
;     for (int kp = 0; kp < 4; ++kp) a += *(const f32x4*)(pp + (size_t)kp * 512 * 1024);
;     q[t][0] = a[0] * 0.0625f; q[t][1] = a[1] * 0.0625f; q[t][2] = a[2] * 0.0625f; q[t][3] = a[3] * 0.0625f; }
;   const bool b0 = lane & 1, b1 = lane & 2;
;   f32x4 kvA[16], kvB[16];
; #pragma unroll
;   for (int j = 0; j < 16; ++j) kvA[j] = __builtin_nontemporal_load((const f32x4*)(ck + (size_t)(wid * 32 + j) * 1024 + lane * 4));
; #pragma unroll
;   for (int j = 0; j < 16; ++j) kvB[j] = __builtin_nontemporal_load((const f32x4*)(ck + (size_t)(wid * 32 + 16 + j) * 1024 + lane * 4));
	v_pk_add_f32 v[2:3], v[2:3], v[6:7]
	v_pk_add_f32 v[0:1], v[0:1], v[4:5]
	s_waitcnt vmcnt(9)
	v_pk_add_f32 v[2:3], v[2:3], v[10:11]
	s_waitcnt vmcnt(7)
	v_pk_add_f32 v[4:5], v[18:19], 0 op_sel_hi:[1,0]
	v_pk_add_f32 v[6:7], v[16:17], 0 op_sel_hi:[1,0]
	v_pk_add_f32 v[0:1], v[0:1], v[8:9]
	s_waitcnt vmcnt(6)
	v_pk_add_f32 v[4:5], v[4:5], v[22:23]
	v_pk_add_f32 v[6:7], v[6:7], v[20:21]
	v_pk_add_f32 v[2:3], v[2:3], v[14:15]
	v_pk_add_f32 v[0:1], v[0:1], v[12:13]
	s_waitcnt vmcnt(5)
	v_pk_add_f32 v[4:5], v[4:5], v[26:27]
	v_pk_add_f32 v[6:7], v[6:7], v[24:25]
	v_mul_f32_e32 v228, 0x3d800000, v0
	v_mul_f32_e32 v231, 0x3d800000, v1
	v_mul_f32_e32 v229, 0x3d800000, v2
	v_mul_f32_e32 v225, 0x3d800000, v3
	s_waitcnt vmcnt(4)
	v_pk_add_f32 v[0:1], v[4:5], v[30:31]
	v_pk_add_f32 v[2:3], v[6:7], v[28:29]
	v_mul_f32_e32 v227, 0x3d800000, v0
	v_mul_f32_e32 v226, 0x3d800000, v2
	v_mul_f32_e32 v230, 0x3d800000, v3
	v_mul_f32_e32 v224, 0x3d800000, v1
	s_waitcnt vmcnt(3)
	v_pk_add_f32 v[0:1], v[34:35], 0 op_sel_hi:[1,0]
	v_pk_add_f32 v[2:3], v[32:33], 0 op_sel_hi:[1,0]
	s_waitcnt vmcnt(2)
	v_pk_add_f32 v[0:1], v[0:1], v[38:39]
	v_pk_add_f32 v[2:3], v[2:3], v[36:37]
	s_waitcnt vmcnt(1)
	v_pk_add_f32 v[0:1], v[0:1], v[42:43]
	v_pk_add_f32 v[2:3], v[2:3], v[40:41]
	s_waitcnt vmcnt(0)
	v_pk_add_f32 v[210:211], v[0:1], v[46:47]
	v_pk_add_f32 v[0:1], v[2:3], v[44:45]
	v_mul_f32_e32 v233, 0x3d800000, v210
	v_mul_f32_e32 v232, 0x3d800000, v0
	v_mul_f32_e32 v234, 0x3d800000, v1
	v_lshl_add_u64 v[0:1], v[48:49], 0, s[6:7]
	v_add_co_u32_e32 v2, vcc, s3, v0
	v_ashrrev_i32_e32 v210, 6, v222
	s_nop 0
	v_addc_co_u32_e32 v3, vcc, 0, v1, vcc
	global_load_dwordx4 v[128:131], v[0:1], off
	global_load_dwordx4 v[132:135], v[2:3], off
	v_add_co_u32_e32 v2, vcc, s33, v0
	v_mul_f32_e32 v211, 0x3d800000, v211
	s_nop 0
	v_addc_co_u32_e32 v3, vcc, 0, v1, vcc
	v_add_co_u32_e32 v0, vcc, s38, v0
	v_cmp_lt_i32_e64 s[6:7], v218, v216
	s_nop 0
	v_addc_co_u32_e32 v1, vcc, 0, v1, vcc
	global_load_dwordx4 v[136:139], v[2:3], off
	global_load_dwordx4 v[140:143], v[0:1], off
	v_or_b32_e32 v240, 19, v236
	v_lshlrev_b32_e32 v152, 12, v240
	v_mov_b32_e32 v153, 0
	v_add_u32_e32 v48, v152, v144
	global_load_dwordx4 v[48:51], v48, s[60:61] nt
	v_or_b32_e32 v240, 20, v236
	v_lshlrev_b32_e32 v154, 12, v240
	v_mov_b32_e32 v155, 0
	v_add_u32_e32 v44, v154, v144
	global_load_dwordx4 v[44:47], v44, s[60:61] nt
	v_or_b32_e32 v240, 21, v236
	v_lshlrev_b32_e32 v156, 12, v240
	v_mov_b32_e32 v157, 0
	v_add_u32_e32 v40, v156, v144
	global_load_dwordx4 v[40:43], v40, s[60:61] nt
	v_or_b32_e32 v240, 22, v236
	v_lshlrev_b32_e32 v158, 12, v240
	v_mov_b32_e32 v159, 0
	v_add_u32_e32 v36, v158, v144
	global_load_dwordx4 v[36:39], v36, s[60:61] nt
	v_or_b32_e32 v240, 23, v236
	v_lshlrev_b32_e32 v160, 12, v240
	v_mov_b32_e32 v161, 0
	v_add_u32_e32 v32, v160, v144
	global_load_dwordx4 v[32:35], v32, s[60:61] nt
	v_or_b32_e32 v240, 24, v236
	v_lshlrev_b32_e32 v164, 12, v240
	v_mov_b32_e32 v165, 0
	v_add_u32_e32 v28, v164, v144
	global_load_dwordx4 v[28:31], v28, s[60:61] nt
	v_or_b32_e32 v240, 25, v236
	v_lshlrev_b32_e32 v170, 12, v240
	v_mov_b32_e32 v171, 0
	v_add_u32_e32 v24, v170, v144
	global_load_dwordx4 v[24:27], v24, s[60:61] nt
	v_or_b32_e32 v240, 26, v236
	v_lshlrev_b32_e32 v174, 12, v240
	v_mov_b32_e32 v175, 0
	v_add_u32_e32 v20, v174, v144
	global_load_dwordx4 v[20:23], v20, s[60:61] nt
	v_or_b32_e32 v240, 27, v236
	v_lshlrev_b32_e32 v178, 12, v240
	v_mov_b32_e32 v179, 0
	v_add_u32_e32 v16, v178, v144
	global_load_dwordx4 v[16:19], v16, s[60:61] nt
	v_or_b32_e32 v240, 28, v236
	v_lshlrev_b32_e32 v184, 12, v240
	v_mov_b32_e32 v185, 0
	v_add_u32_e32 v12, v184, v144
	global_load_dwordx4 v[12:15], v12, s[60:61] nt
	v_or_b32_e32 v240, 29, v236
	v_lshlrev_b32_e32 v188, 12, v240
	v_mov_b32_e32 v189, 0
	v_add_u32_e32 v8, v188, v144
	global_load_dwordx4 v[8:11], v8, s[60:61] nt
	v_or_b32_e32 v240, 30, v236
	v_lshlrev_b32_e32 v192, 12, v240
	v_mov_b32_e32 v193, 0
	v_add_u32_e32 v4, v192, v144
	global_load_dwordx4 v[4:7], v4, s[60:61] nt
	v_or_b32_e32 v240, 31, v236
	v_lshlrev_b32_e32 v196, 12, v240
	v_mov_b32_e32 v197, 0
	v_add_u32_e32 v0, v196, v144
	global_load_dwordx4 v[0:3], v0, s[60:61] nt
	s_waitcnt vmcnt(16)
	v_pk_add_f32 v[128:129], v[128:129], 0 op_sel_hi:[1,0]
	v_pk_add_f32 v[130:131], v[130:131], 0 op_sel_hi:[1,0]
	s_waitcnt vmcnt(15)
	v_pk_add_f32 v[128:129], v[128:129], v[132:133]
	v_pk_add_f32 v[130:131], v[130:131], v[134:135]
	s_waitcnt vmcnt(14)
	v_pk_add_f32 v[128:129], v[128:129], v[136:137]
	v_pk_add_f32 v[130:131], v[130:131], v[138:139]
	s_waitcnt vmcnt(13)
	v_pk_add_f32 v[128:129], v[128:129], v[140:141]
	v_pk_add_f32 v[130:131], v[130:131], v[142:143]
	v_mul_f32_e32 v138, 0x3d800000, v129
	v_mul_f32_e32 v135, 0x3d800000, v128
	v_mul_f32_e32 v134, 0x3d800000, v131
	s_add_u32 s66, s14, s30
	s_addc_u32 s67, s15, s31
	v_mul_f32_e32 v137, 0x3d800000, v130
	v_lshlrev_b32_e32 v128, 2, v215
	v_lshlrev_b32_e32 v129, 2, v217
	v_lshlrev_b32_e32 v130, 2, v218
	v_lshlrev_b32_e32 v131, 2, v219
	v_lshlrev_b32_e32 v132, 2, v220
	v_lshlrev_b32_e32 v133, 2, v221
	v_lshl_add_u32 v136, v210, 7, 16
	v_and_b32_e32 v139, 3, v223
	v_bfrev_b32_e32 v139, v139
	v_lshrrev_b32_e32 v139, 20, v139
	v_and_b32_e32 v235, -4, v223
	v_add3_u32 v235, v136, v139, v235
	v_mov_b32_e32 v236, v228
	v_mov_b32_e32 v237, v226
	v_mov_b32_e32 v238, v231
	v_mov_b32_e32 v239, v230
	v_mov_b32_e32 v240, v229
	v_mov_b32_e32 v241, v227
	v_mov_b32_e32 v242, v225
	v_mov_b32_e32 v243, v224
	v_mov_b32_e32 v244, v232
	v_mov_b32_e32 v245, v135
	v_mov_b32_e32 v246, v234
	v_mov_b32_e32 v247, v138
	v_mov_b32_e32 v248, v233
	v_mov_b32_e32 v249, v137
	v_mov_b32_e32 v250, v211
	v_mov_b32_e32 v251, v134
	s_mov_b32 vcc_lo, 0x55555555
	s_mov_b32 vcc_hi, 0x55555555
	s_mov_b32 s4, 0x33333333
	s_mov_b32 s5, 0x33333333
	s_mov_b32 s6, 0x0f0f0f0f
	s_mov_b32 s7, 0x0f0f0f0f
	s_mov_b32 s64, 0x00ff00ff
	s_mov_b32 s65, 0x00ff00ff
	s_waitcnt vmcnt(31)
; DI void attn_sample_item(const Params& p, int item, ldsp lds, int tid_) {
;     ...
;   SC_SCORE(kvA, 0)
;   SC_SCORE(kvB, 1)
	v_pk_mul_f32 v[252:253], v[236:237], v[124:125] op_sel_hi:[1,0]
	v_pk_mul_f32 v[254:255], v[244:245], v[124:125] op_sel_hi:[1,0]
	v_pk_fma_f32 v[252:253], v[238:239], v[124:125], v[252:253] op_sel:[0,1,0]
	v_pk_fma_f32 v[254:255], v[246:247], v[124:125], v[254:255] op_sel:[0,1,0]
	v_pk_fma_f32 v[252:253], v[240:241], v[126:127], v[252:253] op_sel_hi:[1,0,1]
	v_pk_fma_f32 v[254:255], v[248:249], v[126:127], v[254:255] op_sel_hi:[1,0,1]
	v_pk_fma_f32 v[252:253], v[242:243], v[126:127], v[252:253] op_sel:[0,1,0]
	v_pk_fma_f32 v[254:255], v[250:251], v[126:127], v[254:255] op_sel:[0,1,0]
	s_waitcnt vmcnt(30)
	v_pk_mul_f32 v[140:141], v[236:237], v[120:121] op_sel_hi:[1,0]
	v_pk_mul_f32 v[142:143], v[244:245], v[120:121] op_sel_hi:[1,0]
	v_pk_fma_f32 v[140:141], v[238:239], v[120:121], v[140:141] op_sel:[0,1,0]
	v_pk_fma_f32 v[142:143], v[246:247], v[120:121], v[142:143] op_sel:[0,1,0]
	v_pk_fma_f32 v[140:141], v[240:241], v[122:123], v[140:141] op_sel_hi:[1,0,1]
	v_pk_fma_f32 v[142:143], v[248:249], v[122:123], v[142:143] op_sel_hi:[1,0,1]
	v_pk_fma_f32 v[140:141], v[242:243], v[122:123], v[140:141] op_sel:[0,1,0]
	v_pk_fma_f32 v[142:143], v[250:251], v[122:123], v[142:143] op_sel:[0,1,0]
	v_add_f32_dpp v124, v252, v252 quad_perm:[1,0,3,2] row_mask:0xf bank_mask:0xf
	v_add_f32_dpp v125, v253, v253 quad_perm:[1,0,3,2] row_mask:0xf bank_mask:0xf
	v_add_f32_dpp v126, v254, v254 quad_perm:[1,0,3,2] row_mask:0xf bank_mask:0xf
	v_add_f32_dpp v127, v255, v255 quad_perm:[1,0,3,2] row_mask:0xf bank_mask:0xf
	v_cndmask_b32_e32 v124, v126, v124, vcc
	v_cndmask_b32_e32 v125, v127, v125, vcc
	s_waitcnt vmcnt(29)
	v_pk_mul_f32 v[252:253], v[236:237], v[116:117] op_sel_hi:[1,0]
	v_pk_mul_f32 v[254:255], v[244:245], v[116:117] op_sel_hi:[1,0]
	v_pk_fma_f32 v[252:253], v[238:239], v[116:117], v[252:253] op_sel:[0,1,0]
	v_pk_fma_f32 v[254:255], v[246:247], v[116:117], v[254:255] op_sel:[0,1,0]
	v_pk_fma_f32 v[252:253], v[240:241], v[118:119], v[252:253] op_sel_hi:[1,0,1]
	v_pk_fma_f32 v[254:255], v[248:249], v[118:119], v[254:255] op_sel_hi:[1,0,1]
	v_pk_fma_f32 v[252:253], v[242:243], v[118:119], v[252:253] op_sel:[0,1,0]
	v_pk_fma_f32 v[254:255], v[250:251], v[118:119], v[254:255] op_sel:[0,1,0]
	v_add_f32_dpp v120, v140, v140 quad_perm:[1,0,3,2] row_mask:0xf bank_mask:0xf
	v_add_f32_dpp v121, v141, v141 quad_perm:[1,0,3,2] row_mask:0xf bank_mask:0xf
	v_add_f32_dpp v122, v142, v142 quad_perm:[1,0,3,2] row_mask:0xf bank_mask:0xf
	v_add_f32_dpp v123, v143, v143 quad_perm:[1,0,3,2] row_mask:0xf bank_mask:0xf
	v_cndmask_b32_e32 v120, v122, v120, vcc
	v_cndmask_b32_e32 v121, v123, v121, vcc
	v_add_f32_dpp v126, v124, v124 quad_perm:[2,3,0,1] row_mask:0xf bank_mask:0xf
	v_add_f32_dpp v127, v125, v125 quad_perm:[2,3,0,1] row_mask:0xf bank_mask:0xf
	v_cndmask_b32_e64 v124, v127, v126, s[4:5]
	s_waitcnt vmcnt(28)
	v_pk_mul_f32 v[140:141], v[236:237], v[112:113] op_sel_hi:[1,0]
	v_pk_mul_f32 v[142:143], v[244:245], v[112:113] op_sel_hi:[1,0]
	v_pk_fma_f32 v[140:141], v[238:239], v[112:113], v[140:141] op_sel:[0,1,0]
	v_pk_fma_f32 v[142:143], v[246:247], v[112:113], v[142:143] op_sel:[0,1,0]
	v_pk_fma_f32 v[140:141], v[240:241], v[114:115], v[140:141] op_sel_hi:[1,0,1]
	v_pk_fma_f32 v[142:143], v[248:249], v[114:115], v[142:143] op_sel_hi:[1,0,1]
	v_pk_fma_f32 v[140:141], v[242:243], v[114:115], v[140:141] op_sel:[0,1,0]
	v_pk_fma_f32 v[142:143], v[250:251], v[114:115], v[142:143] op_sel:[0,1,0]
	v_add_f32_dpp v116, v252, v252 quad_perm:[1,0,3,2] row_mask:0xf bank_mask:0xf
	v_add_f32_dpp v117, v253, v253 quad_perm:[1,0,3,2] row_mask:0xf bank_mask:0xf
	v_add_f32_dpp v118, v254, v254 quad_perm:[1,0,3,2] row_mask:0xf bank_mask:0xf
	v_add_f32_dpp v119, v255, v255 quad_perm:[1,0,3,2] row_mask:0xf bank_mask:0xf
	v_cndmask_b32_e32 v116, v118, v116, vcc
	v_cndmask_b32_e32 v117, v119, v117, vcc
	v_add_f32_dpp v122, v120, v120 quad_perm:[2,3,0,1] row_mask:0xf bank_mask:0xf
	v_add_f32_dpp v123, v121, v121 quad_perm:[2,3,0,1] row_mask:0xf bank_mask:0xf
	v_cndmask_b32_e64 v120, v123, v122, s[4:5]
	v_cndmask_b32_e64 v125, v120, v124, s[6:7]
	v_cndmask_b32_e64 v126, v124, v120, s[6:7]
	s_waitcnt vmcnt(27)
	v_pk_mul_f32 v[252:253], v[236:237], v[108:109] op_sel_hi:[1,0]
	v_pk_mul_f32 v[254:255], v[244:245], v[108:109] op_sel_hi:[1,0]
	v_pk_fma_f32 v[252:253], v[238:239], v[108:109], v[252:253] op_sel:[0,1,0]
	v_pk_fma_f32 v[254:255], v[246:247], v[108:109], v[254:255] op_sel:[0,1,0]
	v_pk_fma_f32 v[252:253], v[240:241], v[110:111], v[252:253] op_sel_hi:[1,0,1]
	v_pk_fma_f32 v[254:255], v[248:249], v[110:111], v[254:255] op_sel_hi:[1,0,1]
	v_pk_fma_f32 v[252:253], v[242:243], v[110:111], v[252:253] op_sel:[0,1,0]
	v_pk_fma_f32 v[254:255], v[250:251], v[110:111], v[254:255] op_sel:[0,1,0]
	v_add_f32_dpp v124, v126, v125 row_ror:4 row_mask:0xf bank_mask:0xf
	v_add_f32_dpp v112, v140, v140 quad_perm:[1,0,3,2] row_mask:0xf bank_mask:0xf
	v_add_f32_dpp v113, v141, v141 quad_perm:[1,0,3,2] row_mask:0xf bank_mask:0xf
	v_add_f32_dpp v114, v142, v142 quad_perm:[1,0,3,2] row_mask:0xf bank_mask:0xf
	v_add_f32_dpp v115, v143, v143 quad_perm:[1,0,3,2] row_mask:0xf bank_mask:0xf
	v_cndmask_b32_e32 v112, v114, v112, vcc
	v_cndmask_b32_e32 v113, v115, v113, vcc
	v_add_f32_dpp v118, v116, v116 quad_perm:[2,3,0,1] row_mask:0xf bank_mask:0xf
	v_add_f32_dpp v119, v117, v117 quad_perm:[2,3,0,1] row_mask:0xf bank_mask:0xf
	v_cndmask_b32_e64 v116, v119, v118, s[4:5]
	s_waitcnt vmcnt(26)
; DI void attn_sample_item(const Params& p, int item, ldsp lds, int tid_) {
;     ...
;   SC_SCORE(kvA, 0)
;   SC_SCORE(kvB, 1)
	v_pk_mul_f32 v[140:141], v[236:237], v[104:105] op_sel_hi:[1,0]
	v_pk_mul_f32 v[142:143], v[244:245], v[104:105] op_sel_hi:[1,0]
	v_pk_fma_f32 v[140:141], v[238:239], v[104:105], v[140:141] op_sel:[0,1,0]
	v_pk_fma_f32 v[142:143], v[246:247], v[104:105], v[142:143] op_sel:[0,1,0]
	v_pk_fma_f32 v[140:141], v[240:241], v[106:107], v[140:141] op_sel_hi:[1,0,1]
	v_pk_fma_f32 v[142:143], v[248:249], v[106:107], v[142:143] op_sel_hi:[1,0,1]
	v_pk_fma_f32 v[140:141], v[242:243], v[106:107], v[140:141] op_sel:[0,1,0]
	v_pk_fma_f32 v[142:143], v[250:251], v[106:107], v[142:143] op_sel:[0,1,0]
	v_add_f32_dpp v108, v252, v252 quad_perm:[1,0,3,2] row_mask:0xf bank_mask:0xf
	v_add_f32_dpp v109, v253, v253 quad_perm:[1,0,3,2] row_mask:0xf bank_mask:0xf
	v_add_f32_dpp v110, v254, v254 quad_perm:[1,0,3,2] row_mask:0xf bank_mask:0xf
	v_add_f32_dpp v111, v255, v255 quad_perm:[1,0,3,2] row_mask:0xf bank_mask:0xf
	v_cndmask_b32_e32 v108, v110, v108, vcc
	v_cndmask_b32_e32 v109, v111, v109, vcc
	v_add_f32_dpp v114, v112, v112 quad_perm:[2,3,0,1] row_mask:0xf bank_mask:0xf
	v_add_f32_dpp v115, v113, v113 quad_perm:[2,3,0,1] row_mask:0xf bank_mask:0xf
	v_cndmask_b32_e64 v112, v115, v114, s[4:5]
	v_cndmask_b32_e64 v117, v112, v116, s[6:7]
	v_cndmask_b32_e64 v118, v116, v112, s[6:7]
	s_waitcnt vmcnt(25)
	v_pk_mul_f32 v[252:253], v[236:237], v[100:101] op_sel_hi:[1,0]
	v_pk_mul_f32 v[254:255], v[244:245], v[100:101] op_sel_hi:[1,0]
	v_pk_fma_f32 v[252:253], v[238:239], v[100:101], v[252:253] op_sel:[0,1,0]
	v_pk_fma_f32 v[254:255], v[246:247], v[100:101], v[254:255] op_sel:[0,1,0]
	v_pk_fma_f32 v[252:253], v[240:241], v[102:103], v[252:253] op_sel_hi:[1,0,1]
	v_pk_fma_f32 v[254:255], v[248:249], v[102:103], v[254:255] op_sel_hi:[1,0,1]
	v_pk_fma_f32 v[252:253], v[242:243], v[102:103], v[252:253] op_sel:[0,1,0]
	v_pk_fma_f32 v[254:255], v[250:251], v[102:103], v[254:255] op_sel:[0,1,0]
	v_add_f32_dpp v116, v118, v117 row_ror:4 row_mask:0xf bank_mask:0xf
	v_cndmask_b32_e64 v125, v116, v124, s[64:65]
	v_cndmask_b32_e64 v126, v124, v116, s[64:65]
	v_add_f32_dpp v104, v140, v140 quad_perm:[1,0,3,2] row_mask:0xf bank_mask:0xf
	v_add_f32_dpp v105, v141, v141 quad_perm:[1,0,3,2] row_mask:0xf bank_mask:0xf
	v_add_f32_dpp v106, v142, v142 quad_perm:[1,0,3,2] row_mask:0xf bank_mask:0xf
	v_add_f32_dpp v107, v143, v143 quad_perm:[1,0,3,2] row_mask:0xf bank_mask:0xf
	v_cndmask_b32_e32 v104, v106, v104, vcc
	v_cndmask_b32_e32 v105, v107, v105, vcc
	v_add_f32_dpp v110, v108, v108 quad_perm:[2,3,0,1] row_mask:0xf bank_mask:0xf
	v_add_f32_dpp v111, v109, v109 quad_perm:[2,3,0,1] row_mask:0xf bank_mask:0xf
	v_cndmask_b32_e64 v108, v111, v110, s[4:5]
	s_waitcnt vmcnt(24)
	v_pk_mul_f32 v[140:141], v[236:237], v[96:97] op_sel_hi:[1,0]
	v_pk_mul_f32 v[142:143], v[244:245], v[96:97] op_sel_hi:[1,0]
	v_pk_fma_f32 v[140:141], v[238:239], v[96:97], v[140:141] op_sel:[0,1,0]
	v_pk_fma_f32 v[142:143], v[246:247], v[96:97], v[142:143] op_sel:[0,1,0]
	v_pk_fma_f32 v[140:141], v[240:241], v[98:99], v[140:141] op_sel_hi:[1,0,1]
	v_pk_fma_f32 v[142:143], v[248:249], v[98:99], v[142:143] op_sel_hi:[1,0,1]
	v_pk_fma_f32 v[140:141], v[242:243], v[98:99], v[140:141] op_sel:[0,1,0]
	v_pk_fma_f32 v[142:143], v[250:251], v[98:99], v[142:143] op_sel:[0,1,0]
	v_add_f32_dpp v124, v126, v125 row_ror:8 row_mask:0xf bank_mask:0xf
	v_add_f32_dpp v100, v252, v252 quad_perm:[1,0,3,2] row_mask:0xf bank_mask:0xf
	v_add_f32_dpp v101, v253, v253 quad_perm:[1,0,3,2] row_mask:0xf bank_mask:0xf
	v_add_f32_dpp v102, v254, v254 quad_perm:[1,0,3,2] row_mask:0xf bank_mask:0xf
	v_add_f32_dpp v103, v255, v255 quad_perm:[1,0,3,2] row_mask:0xf bank_mask:0xf
	v_cndmask_b32_e32 v100, v102, v100, vcc
	v_cndmask_b32_e32 v101, v103, v101, vcc
	v_add_f32_dpp v106, v104, v104 quad_perm:[2,3,0,1] row_mask:0xf bank_mask:0xf
	v_add_f32_dpp v107, v105, v105 quad_perm:[2,3,0,1] row_mask:0xf bank_mask:0xf
	v_cndmask_b32_e64 v104, v107, v106, s[4:5]
	v_cndmask_b32_e64 v109, v104, v108, s[6:7]
	v_cndmask_b32_e64 v110, v108, v104, s[6:7]
	s_waitcnt vmcnt(23)
	v_pk_mul_f32 v[252:253], v[236:237], v[92:93] op_sel_hi:[1,0]
	v_pk_mul_f32 v[254:255], v[244:245], v[92:93] op_sel_hi:[1,0]
	v_pk_fma_f32 v[252:253], v[238:239], v[92:93], v[252:253] op_sel:[0,1,0]
	v_pk_fma_f32 v[254:255], v[246:247], v[92:93], v[254:255] op_sel:[0,1,0]
	v_pk_fma_f32 v[252:253], v[240:241], v[94:95], v[252:253] op_sel_hi:[1,0,1]
	v_pk_fma_f32 v[254:255], v[248:249], v[94:95], v[254:255] op_sel_hi:[1,0,1]
	v_pk_fma_f32 v[252:253], v[242:243], v[94:95], v[252:253] op_sel:[0,1,0]
	v_pk_fma_f32 v[254:255], v[250:251], v[94:95], v[254:255] op_sel:[0,1,0]
	v_add_f32_dpp v108, v110, v109 row_ror:4 row_mask:0xf bank_mask:0xf
	v_add_f32_dpp v96, v140, v140 quad_perm:[1,0,3,2] row_mask:0xf bank_mask:0xf
	v_add_f32_dpp v97, v141, v141 quad_perm:[1,0,3,2] row_mask:0xf bank_mask:0xf
	v_add_f32_dpp v98, v142, v142 quad_perm:[1,0,3,2] row_mask:0xf bank_mask:0xf
	v_add_f32_dpp v99, v143, v143 quad_perm:[1,0,3,2] row_mask:0xf bank_mask:0xf
	v_cndmask_b32_e32 v96, v98, v96, vcc
	v_cndmask_b32_e32 v97, v99, v97, vcc
	v_add_f32_dpp v102, v100, v100 quad_perm:[2,3,0,1] row_mask:0xf bank_mask:0xf
	v_add_f32_dpp v103, v101, v101 quad_perm:[2,3,0,1] row_mask:0xf bank_mask:0xf
	v_cndmask_b32_e64 v100, v103, v102, s[4:5]
	s_waitcnt vmcnt(22)
; DI void attn_sample_item(const Params& p, int item, ldsp lds, int tid_) {
;     ...
;   SC_SCORE(kvA, 0)
;   SC_SCORE(kvB, 1)
	v_pk_mul_f32 v[140:141], v[236:237], v[88:89] op_sel_hi:[1,0]
	v_pk_mul_f32 v[142:143], v[244:245], v[88:89] op_sel_hi:[1,0]
	v_pk_fma_f32 v[140:141], v[238:239], v[88:89], v[140:141] op_sel:[0,1,0]
	v_pk_fma_f32 v[142:143], v[246:247], v[88:89], v[142:143] op_sel:[0,1,0]
	v_pk_fma_f32 v[140:141], v[240:241], v[90:91], v[140:141] op_sel_hi:[1,0,1]
	v_pk_fma_f32 v[142:143], v[248:249], v[90:91], v[142:143] op_sel_hi:[1,0,1]
	v_pk_fma_f32 v[140:141], v[242:243], v[90:91], v[140:141] op_sel:[0,1,0]
	v_pk_fma_f32 v[142:143], v[250:251], v[90:91], v[142:143] op_sel:[0,1,0]
	v_add_f32_dpp v92, v252, v252 quad_perm:[1,0,3,2] row_mask:0xf bank_mask:0xf
	v_add_f32_dpp v93, v253, v253 quad_perm:[1,0,3,2] row_mask:0xf bank_mask:0xf
	v_add_f32_dpp v94, v254, v254 quad_perm:[1,0,3,2] row_mask:0xf bank_mask:0xf
	v_add_f32_dpp v95, v255, v255 quad_perm:[1,0,3,2] row_mask:0xf bank_mask:0xf
	v_cndmask_b32_e32 v92, v94, v92, vcc
	v_cndmask_b32_e32 v93, v95, v93, vcc
	v_add_f32_dpp v98, v96, v96 quad_perm:[2,3,0,1] row_mask:0xf bank_mask:0xf
	v_add_f32_dpp v99, v97, v97 quad_perm:[2,3,0,1] row_mask:0xf bank_mask:0xf
	v_cndmask_b32_e64 v96, v99, v98, s[4:5]
	v_cndmask_b32_e64 v101, v96, v100, s[6:7]
	v_cndmask_b32_e64 v102, v100, v96, s[6:7]
	s_waitcnt vmcnt(21)
	v_pk_mul_f32 v[252:253], v[236:237], v[84:85] op_sel_hi:[1,0]
	v_pk_mul_f32 v[254:255], v[244:245], v[84:85] op_sel_hi:[1,0]
	v_pk_fma_f32 v[252:253], v[238:239], v[84:85], v[252:253] op_sel:[0,1,0]
	v_pk_fma_f32 v[254:255], v[246:247], v[84:85], v[254:255] op_sel:[0,1,0]
	v_pk_fma_f32 v[252:253], v[240:241], v[86:87], v[252:253] op_sel_hi:[1,0,1]
	v_pk_fma_f32 v[254:255], v[248:249], v[86:87], v[254:255] op_sel_hi:[1,0,1]
	v_pk_fma_f32 v[252:253], v[242:243], v[86:87], v[252:253] op_sel:[0,1,0]
	v_pk_fma_f32 v[254:255], v[250:251], v[86:87], v[254:255] op_sel:[0,1,0]
	v_add_f32_dpp v100, v102, v101 row_ror:4 row_mask:0xf bank_mask:0xf
	v_cndmask_b32_e64 v109, v100, v108, s[64:65]
	v_cndmask_b32_e64 v110, v108, v100, s[64:65]
	v_add_f32_dpp v88, v140, v140 quad_perm:[1,0,3,2] row_mask:0xf bank_mask:0xf
	v_add_f32_dpp v89, v141, v141 quad_perm:[1,0,3,2] row_mask:0xf bank_mask:0xf
	v_add_f32_dpp v90, v142, v142 quad_perm:[1,0,3,2] row_mask:0xf bank_mask:0xf
	v_add_f32_dpp v91, v143, v143 quad_perm:[1,0,3,2] row_mask:0xf bank_mask:0xf
	v_cndmask_b32_e32 v88, v90, v88, vcc
	v_cndmask_b32_e32 v89, v91, v89, vcc
	v_add_f32_dpp v94, v92, v92 quad_perm:[2,3,0,1] row_mask:0xf bank_mask:0xf
	v_add_f32_dpp v95, v93, v93 quad_perm:[2,3,0,1] row_mask:0xf bank_mask:0xf
	v_cndmask_b32_e64 v92, v95, v94, s[4:5]
	s_waitcnt vmcnt(20)
	v_pk_mul_f32 v[140:141], v[236:237], v[80:81] op_sel_hi:[1,0]
	v_pk_mul_f32 v[142:143], v[244:245], v[80:81] op_sel_hi:[1,0]
	v_pk_fma_f32 v[140:141], v[238:239], v[80:81], v[140:141] op_sel:[0,1,0]
	v_pk_fma_f32 v[142:143], v[246:247], v[80:81], v[142:143] op_sel:[0,1,0]
	v_pk_fma_f32 v[140:141], v[240:241], v[82:83], v[140:141] op_sel_hi:[1,0,1]
	v_pk_fma_f32 v[142:143], v[248:249], v[82:83], v[142:143] op_sel_hi:[1,0,1]
	v_pk_fma_f32 v[140:141], v[242:243], v[82:83], v[140:141] op_sel:[0,1,0]
	v_pk_fma_f32 v[142:143], v[250:251], v[82:83], v[142:143] op_sel:[0,1,0]
	v_add_f32_dpp v108, v110, v109 row_ror:8 row_mask:0xf bank_mask:0xf
	v_add_f32_dpp v84, v252, v252 quad_perm:[1,0,3,2] row_mask:0xf bank_mask:0xf
	v_add_f32_dpp v85, v253, v253 quad_perm:[1,0,3,2] row_mask:0xf bank_mask:0xf
	v_add_f32_dpp v86, v254, v254 quad_perm:[1,0,3,2] row_mask:0xf bank_mask:0xf
	v_add_f32_dpp v87, v255, v255 quad_perm:[1,0,3,2] row_mask:0xf bank_mask:0xf
	v_cndmask_b32_e32 v84, v86, v84, vcc
	v_cndmask_b32_e32 v85, v87, v85, vcc
	v_add_f32_dpp v90, v88, v88 quad_perm:[2,3,0,1] row_mask:0xf bank_mask:0xf
	v_add_f32_dpp v91, v89, v89 quad_perm:[2,3,0,1] row_mask:0xf bank_mask:0xf
	v_cndmask_b32_e64 v88, v91, v90, s[4:5]
	v_cndmask_b32_e64 v93, v88, v92, s[6:7]
	v_cndmask_b32_e64 v94, v92, v88, s[6:7]
	s_waitcnt vmcnt(19)
	v_pk_mul_f32 v[252:253], v[236:237], v[76:77] op_sel_hi:[1,0]
	v_pk_mul_f32 v[254:255], v[244:245], v[76:77] op_sel_hi:[1,0]
	v_pk_fma_f32 v[252:253], v[238:239], v[76:77], v[252:253] op_sel:[0,1,0]
	v_pk_fma_f32 v[254:255], v[246:247], v[76:77], v[254:255] op_sel:[0,1,0]
	v_pk_fma_f32 v[252:253], v[240:241], v[78:79], v[252:253] op_sel_hi:[1,0,1]
	v_pk_fma_f32 v[254:255], v[248:249], v[78:79], v[254:255] op_sel_hi:[1,0,1]
	v_pk_fma_f32 v[252:253], v[242:243], v[78:79], v[252:253] op_sel:[0,1,0]
	v_pk_fma_f32 v[254:255], v[250:251], v[78:79], v[254:255] op_sel:[0,1,0]
	v_permlane16_swap_b32_e32 v124, v108
	v_add_f32_e32 v124, v124, v108
	v_add_f32_dpp v92, v94, v93 row_ror:4 row_mask:0xf bank_mask:0xf
	v_add_f32_dpp v80, v140, v140 quad_perm:[1,0,3,2] row_mask:0xf bank_mask:0xf
	v_add_f32_dpp v81, v141, v141 quad_perm:[1,0,3,2] row_mask:0xf bank_mask:0xf
	v_add_f32_dpp v82, v142, v142 quad_perm:[1,0,3,2] row_mask:0xf bank_mask:0xf
	v_add_f32_dpp v83, v143, v143 quad_perm:[1,0,3,2] row_mask:0xf bank_mask:0xf
	v_cndmask_b32_e32 v80, v82, v80, vcc
	v_cndmask_b32_e32 v81, v83, v81, vcc
	v_add_f32_dpp v86, v84, v84 quad_perm:[2,3,0,1] row_mask:0xf bank_mask:0xf
	v_add_f32_dpp v87, v85, v85 quad_perm:[2,3,0,1] row_mask:0xf bank_mask:0xf
	v_cndmask_b32_e64 v84, v87, v86, s[4:5]
	s_waitcnt vmcnt(18)
; DI void attn_sample_item(const Params& p, int item, ldsp lds, int tid_) {
;     ...
;   SC_SCORE(kvA, 0)
;   SC_SCORE(kvB, 1)
	v_pk_mul_f32 v[140:141], v[236:237], v[72:73] op_sel_hi:[1,0]
	v_pk_mul_f32 v[142:143], v[244:245], v[72:73] op_sel_hi:[1,0]
	v_pk_fma_f32 v[140:141], v[238:239], v[72:73], v[140:141] op_sel:[0,1,0]
	v_pk_fma_f32 v[142:143], v[246:247], v[72:73], v[142:143] op_sel:[0,1,0]
	v_pk_fma_f32 v[140:141], v[240:241], v[74:75], v[140:141] op_sel_hi:[1,0,1]
	v_pk_fma_f32 v[142:143], v[248:249], v[74:75], v[142:143] op_sel_hi:[1,0,1]
	v_pk_fma_f32 v[140:141], v[242:243], v[74:75], v[140:141] op_sel:[0,1,0]
	v_pk_fma_f32 v[142:143], v[250:251], v[74:75], v[142:143] op_sel:[0,1,0]
	v_add_f32_dpp v76, v252, v252 quad_perm:[1,0,3,2] row_mask:0xf bank_mask:0xf
	v_add_f32_dpp v77, v253, v253 quad_perm:[1,0,3,2] row_mask:0xf bank_mask:0xf
	v_add_f32_dpp v78, v254, v254 quad_perm:[1,0,3,2] row_mask:0xf bank_mask:0xf
	v_add_f32_dpp v79, v255, v255 quad_perm:[1,0,3,2] row_mask:0xf bank_mask:0xf
	v_cndmask_b32_e32 v76, v78, v76, vcc
	v_cndmask_b32_e32 v77, v79, v77, vcc
	v_add_f32_dpp v82, v80, v80 quad_perm:[2,3,0,1] row_mask:0xf bank_mask:0xf
	v_add_f32_dpp v83, v81, v81 quad_perm:[2,3,0,1] row_mask:0xf bank_mask:0xf
	v_cndmask_b32_e64 v80, v83, v82, s[4:5]
	v_cndmask_b32_e64 v85, v80, v84, s[6:7]
	v_cndmask_b32_e64 v86, v84, v80, s[6:7]
	s_waitcnt vmcnt(17)
	v_pk_mul_f32 v[252:253], v[236:237], v[68:69] op_sel_hi:[1,0]
	v_pk_mul_f32 v[254:255], v[244:245], v[68:69] op_sel_hi:[1,0]
	v_pk_fma_f32 v[252:253], v[238:239], v[68:69], v[252:253] op_sel:[0,1,0]
	v_pk_fma_f32 v[254:255], v[246:247], v[68:69], v[254:255] op_sel:[0,1,0]
	v_pk_fma_f32 v[252:253], v[240:241], v[70:71], v[252:253] op_sel_hi:[1,0,1]
	v_pk_fma_f32 v[254:255], v[248:249], v[70:71], v[254:255] op_sel_hi:[1,0,1]
	v_pk_fma_f32 v[252:253], v[242:243], v[70:71], v[252:253] op_sel:[0,1,0]
	v_pk_fma_f32 v[254:255], v[250:251], v[70:71], v[254:255] op_sel:[0,1,0]
	v_add_f32_dpp v84, v86, v85 row_ror:4 row_mask:0xf bank_mask:0xf
	v_cndmask_b32_e64 v93, v84, v92, s[64:65]
	v_cndmask_b32_e64 v94, v92, v84, s[64:65]
	v_add_f32_dpp v72, v140, v140 quad_perm:[1,0,3,2] row_mask:0xf bank_mask:0xf
	v_add_f32_dpp v73, v141, v141 quad_perm:[1,0,3,2] row_mask:0xf bank_mask:0xf
	v_add_f32_dpp v74, v142, v142 quad_perm:[1,0,3,2] row_mask:0xf bank_mask:0xf
	v_add_f32_dpp v75, v143, v143 quad_perm:[1,0,3,2] row_mask:0xf bank_mask:0xf
	v_cndmask_b32_e32 v72, v74, v72, vcc
	v_cndmask_b32_e32 v73, v75, v73, vcc
	v_add_f32_dpp v78, v76, v76 quad_perm:[2,3,0,1] row_mask:0xf bank_mask:0xf
	v_add_f32_dpp v79, v77, v77 quad_perm:[2,3,0,1] row_mask:0xf bank_mask:0xf
	v_cndmask_b32_e64 v76, v79, v78, s[4:5]
	s_waitcnt vmcnt(16)
	v_pk_mul_f32 v[140:141], v[236:237], v[64:65] op_sel_hi:[1,0]
	v_pk_mul_f32 v[142:143], v[244:245], v[64:65] op_sel_hi:[1,0]
	v_pk_fma_f32 v[140:141], v[238:239], v[64:65], v[140:141] op_sel:[0,1,0]
	v_pk_fma_f32 v[142:143], v[246:247], v[64:65], v[142:143] op_sel:[0,1,0]
	v_pk_fma_f32 v[140:141], v[240:241], v[66:67], v[140:141] op_sel_hi:[1,0,1]
	v_pk_fma_f32 v[142:143], v[248:249], v[66:67], v[142:143] op_sel_hi:[1,0,1]
	v_pk_fma_f32 v[140:141], v[242:243], v[66:67], v[140:141] op_sel:[0,1,0]
	v_pk_fma_f32 v[142:143], v[250:251], v[66:67], v[142:143] op_sel:[0,1,0]
	v_add_f32_dpp v92, v94, v93 row_ror:8 row_mask:0xf bank_mask:0xf
	v_add_f32_dpp v68, v252, v252 quad_perm:[1,0,3,2] row_mask:0xf bank_mask:0xf
	v_add_f32_dpp v69, v253, v253 quad_perm:[1,0,3,2] row_mask:0xf bank_mask:0xf
	v_add_f32_dpp v70, v254, v254 quad_perm:[1,0,3,2] row_mask:0xf bank_mask:0xf
	v_add_f32_dpp v71, v255, v255 quad_perm:[1,0,3,2] row_mask:0xf bank_mask:0xf
	v_cndmask_b32_e32 v68, v70, v68, vcc
	v_cndmask_b32_e32 v69, v71, v69, vcc
	v_add_f32_dpp v74, v72, v72 quad_perm:[2,3,0,1] row_mask:0xf bank_mask:0xf
	v_add_f32_dpp v75, v73, v73 quad_perm:[2,3,0,1] row_mask:0xf bank_mask:0xf
	v_cndmask_b32_e64 v72, v75, v74, s[4:5]
	v_cndmask_b32_e64 v77, v72, v76, s[6:7]
	v_cndmask_b32_e64 v78, v76, v72, s[6:7]
	s_waitcnt vmcnt(15)
	v_pk_mul_f32 v[252:253], v[236:237], v[60:61] op_sel_hi:[1,0]
	v_pk_mul_f32 v[254:255], v[244:245], v[60:61] op_sel_hi:[1,0]
	v_pk_fma_f32 v[252:253], v[238:239], v[60:61], v[252:253] op_sel:[0,1,0]
	v_pk_fma_f32 v[254:255], v[246:247], v[60:61], v[254:255] op_sel:[0,1,0]
	v_pk_fma_f32 v[252:253], v[240:241], v[62:63], v[252:253] op_sel_hi:[1,0,1]
	v_pk_fma_f32 v[254:255], v[248:249], v[62:63], v[254:255] op_sel_hi:[1,0,1]
	v_pk_fma_f32 v[252:253], v[242:243], v[62:63], v[252:253] op_sel:[0,1,0]
	v_pk_fma_f32 v[254:255], v[250:251], v[62:63], v[254:255] op_sel:[0,1,0]
	v_add_f32_dpp v76, v78, v77 row_ror:4 row_mask:0xf bank_mask:0xf
	v_add_f32_dpp v64, v140, v140 quad_perm:[1,0,3,2] row_mask:0xf bank_mask:0xf
	v_add_f32_dpp v65, v141, v141 quad_perm:[1,0,3,2] row_mask:0xf bank_mask:0xf
	v_add_f32_dpp v66, v142, v142 quad_perm:[1,0,3,2] row_mask:0xf bank_mask:0xf
	v_add_f32_dpp v67, v143, v143 quad_perm:[1,0,3,2] row_mask:0xf bank_mask:0xf
	v_cndmask_b32_e32 v64, v66, v64, vcc
	v_cndmask_b32_e32 v65, v67, v65, vcc
	v_add_f32_dpp v70, v68, v68 quad_perm:[2,3,0,1] row_mask:0xf bank_mask:0xf
	v_add_f32_dpp v71, v69, v69 quad_perm:[2,3,0,1] row_mask:0xf bank_mask:0xf
	v_cndmask_b32_e64 v68, v71, v70, s[4:5]
	s_waitcnt vmcnt(14)
; DI void attn_sample_item(const Params& p, int item, ldsp lds, int tid_) {
;     ...
;   SC_SCORE(kvA, 0)
;   SC_SCORE(kvB, 1)
	v_pk_mul_f32 v[140:141], v[236:237], v[56:57] op_sel_hi:[1,0]
	v_pk_mul_f32 v[142:143], v[244:245], v[56:57] op_sel_hi:[1,0]
	v_pk_fma_f32 v[140:141], v[238:239], v[56:57], v[140:141] op_sel:[0,1,0]
	v_pk_fma_f32 v[142:143], v[246:247], v[56:57], v[142:143] op_sel:[0,1,0]
	v_pk_fma_f32 v[140:141], v[240:241], v[58:59], v[140:141] op_sel_hi:[1,0,1]
	v_pk_fma_f32 v[142:143], v[248:249], v[58:59], v[142:143] op_sel_hi:[1,0,1]
	v_pk_fma_f32 v[140:141], v[242:243], v[58:59], v[140:141] op_sel:[0,1,0]
	v_pk_fma_f32 v[142:143], v[250:251], v[58:59], v[142:143] op_sel:[0,1,0]
	v_add_f32_dpp v60, v252, v252 quad_perm:[1,0,3,2] row_mask:0xf bank_mask:0xf
	v_add_f32_dpp v61, v253, v253 quad_perm:[1,0,3,2] row_mask:0xf bank_mask:0xf
	v_add_f32_dpp v62, v254, v254 quad_perm:[1,0,3,2] row_mask:0xf bank_mask:0xf
	v_add_f32_dpp v63, v255, v255 quad_perm:[1,0,3,2] row_mask:0xf bank_mask:0xf
	v_cndmask_b32_e32 v60, v62, v60, vcc
	v_cndmask_b32_e32 v61, v63, v61, vcc
	v_add_f32_dpp v66, v64, v64 quad_perm:[2,3,0,1] row_mask:0xf bank_mask:0xf
	v_add_f32_dpp v67, v65, v65 quad_perm:[2,3,0,1] row_mask:0xf bank_mask:0xf
	v_cndmask_b32_e64 v64, v67, v66, s[4:5]
	v_cndmask_b32_e64 v69, v64, v68, s[6:7]
	v_cndmask_b32_e64 v70, v68, v64, s[6:7]
	s_waitcnt vmcnt(13)
	v_pk_mul_f32 v[252:253], v[236:237], v[52:53] op_sel_hi:[1,0]
	v_pk_mul_f32 v[254:255], v[244:245], v[52:53] op_sel_hi:[1,0]
	v_pk_fma_f32 v[252:253], v[238:239], v[52:53], v[252:253] op_sel:[0,1,0]
	v_pk_fma_f32 v[254:255], v[246:247], v[52:53], v[254:255] op_sel:[0,1,0]
	v_pk_fma_f32 v[252:253], v[240:241], v[54:55], v[252:253] op_sel_hi:[1,0,1]
	v_pk_fma_f32 v[254:255], v[248:249], v[54:55], v[254:255] op_sel_hi:[1,0,1]
	v_pk_fma_f32 v[252:253], v[242:243], v[54:55], v[252:253] op_sel:[0,1,0]
	v_pk_fma_f32 v[254:255], v[250:251], v[54:55], v[254:255] op_sel:[0,1,0]
	v_add_f32_dpp v68, v70, v69 row_ror:4 row_mask:0xf bank_mask:0xf
	v_cndmask_b32_e64 v77, v68, v76, s[64:65]
	v_cndmask_b32_e64 v78, v76, v68, s[64:65]
	v_add_f32_dpp v56, v140, v140 quad_perm:[1,0,3,2] row_mask:0xf bank_mask:0xf
	v_add_f32_dpp v57, v141, v141 quad_perm:[1,0,3,2] row_mask:0xf bank_mask:0xf
	v_add_f32_dpp v58, v142, v142 quad_perm:[1,0,3,2] row_mask:0xf bank_mask:0xf
	v_add_f32_dpp v59, v143, v143 quad_perm:[1,0,3,2] row_mask:0xf bank_mask:0xf
	v_cndmask_b32_e32 v56, v58, v56, vcc
	v_cndmask_b32_e32 v57, v59, v57, vcc
	v_add_f32_dpp v62, v60, v60 quad_perm:[2,3,0,1] row_mask:0xf bank_mask:0xf
	v_add_f32_dpp v63, v61, v61 quad_perm:[2,3,0,1] row_mask:0xf bank_mask:0xf
	v_cndmask_b32_e64 v60, v63, v62, s[4:5]
	s_waitcnt vmcnt(12)
	v_pk_mul_f32 v[140:141], v[236:237], v[48:49] op_sel_hi:[1,0]
	v_pk_mul_f32 v[142:143], v[244:245], v[48:49] op_sel_hi:[1,0]
	v_pk_fma_f32 v[140:141], v[238:239], v[48:49], v[140:141] op_sel:[0,1,0]
	v_pk_fma_f32 v[142:143], v[246:247], v[48:49], v[142:143] op_sel:[0,1,0]
	v_pk_fma_f32 v[140:141], v[240:241], v[50:51], v[140:141] op_sel_hi:[1,0,1]
	v_pk_fma_f32 v[142:143], v[248:249], v[50:51], v[142:143] op_sel_hi:[1,0,1]
	v_pk_fma_f32 v[140:141], v[242:243], v[50:51], v[140:141] op_sel:[0,1,0]
	v_pk_fma_f32 v[142:143], v[250:251], v[50:51], v[142:143] op_sel:[0,1,0]
	v_add_f32_dpp v76, v78, v77 row_ror:8 row_mask:0xf bank_mask:0xf
	v_add_f32_dpp v52, v252, v252 quad_perm:[1,0,3,2] row_mask:0xf bank_mask:0xf
	v_add_f32_dpp v53, v253, v253 quad_perm:[1,0,3,2] row_mask:0xf bank_mask:0xf
	v_add_f32_dpp v54, v254, v254 quad_perm:[1,0,3,2] row_mask:0xf bank_mask:0xf
	v_add_f32_dpp v55, v255, v255 quad_perm:[1,0,3,2] row_mask:0xf bank_mask:0xf
	v_cndmask_b32_e32 v52, v54, v52, vcc
	v_cndmask_b32_e32 v53, v55, v53, vcc
	v_add_f32_dpp v58, v56, v56 quad_perm:[2,3,0,1] row_mask:0xf bank_mask:0xf
	v_add_f32_dpp v59, v57, v57 quad_perm:[2,3,0,1] row_mask:0xf bank_mask:0xf
	v_cndmask_b32_e64 v56, v59, v58, s[4:5]
	v_cndmask_b32_e64 v61, v56, v60, s[6:7]
	v_cndmask_b32_e64 v62, v60, v56, s[6:7]
	s_waitcnt vmcnt(11)
	v_pk_mul_f32 v[252:253], v[236:237], v[44:45] op_sel_hi:[1,0]
	v_pk_mul_f32 v[254:255], v[244:245], v[44:45] op_sel_hi:[1,0]
	v_pk_fma_f32 v[252:253], v[238:239], v[44:45], v[252:253] op_sel:[0,1,0]
	v_pk_fma_f32 v[254:255], v[246:247], v[44:45], v[254:255] op_sel:[0,1,0]
	v_pk_fma_f32 v[252:253], v[240:241], v[46:47], v[252:253] op_sel_hi:[1,0,1]
	v_pk_fma_f32 v[254:255], v[248:249], v[46:47], v[254:255] op_sel_hi:[1,0,1]
	v_pk_fma_f32 v[252:253], v[242:243], v[46:47], v[252:253] op_sel:[0,1,0]
	v_pk_fma_f32 v[254:255], v[250:251], v[46:47], v[254:255] op_sel:[0,1,0]
	v_permlane16_swap_b32_e32 v92, v76
	v_add_f32_e32 v92, v92, v76
	v_add_f32_dpp v60, v62, v61 row_ror:4 row_mask:0xf bank_mask:0xf
	v_add_f32_dpp v48, v140, v140 quad_perm:[1,0,3,2] row_mask:0xf bank_mask:0xf
	v_add_f32_dpp v49, v141, v141 quad_perm:[1,0,3,2] row_mask:0xf bank_mask:0xf
	v_add_f32_dpp v50, v142, v142 quad_perm:[1,0,3,2] row_mask:0xf bank_mask:0xf
	v_add_f32_dpp v51, v143, v143 quad_perm:[1,0,3,2] row_mask:0xf bank_mask:0xf
	v_cndmask_b32_e32 v48, v50, v48, vcc
	v_cndmask_b32_e32 v49, v51, v49, vcc
	v_add_f32_dpp v54, v52, v52 quad_perm:[2,3,0,1] row_mask:0xf bank_mask:0xf
	v_add_f32_dpp v55, v53, v53 quad_perm:[2,3,0,1] row_mask:0xf bank_mask:0xf
	v_cndmask_b32_e64 v52, v55, v54, s[4:5]
	s_waitcnt vmcnt(10)
; DI void attn_sample_item(const Params& p, int item, ldsp lds, int tid_) {
;     ...
;   SC_SCORE(kvA, 0)
;   SC_SCORE(kvB, 1)
	v_pk_mul_f32 v[140:141], v[236:237], v[40:41] op_sel_hi:[1,0]
	v_pk_mul_f32 v[142:143], v[244:245], v[40:41] op_sel_hi:[1,0]
	v_pk_fma_f32 v[140:141], v[238:239], v[40:41], v[140:141] op_sel:[0,1,0]
	v_pk_fma_f32 v[142:143], v[246:247], v[40:41], v[142:143] op_sel:[0,1,0]
	v_pk_fma_f32 v[140:141], v[240:241], v[42:43], v[140:141] op_sel_hi:[1,0,1]
	v_pk_fma_f32 v[142:143], v[248:249], v[42:43], v[142:143] op_sel_hi:[1,0,1]
	v_pk_fma_f32 v[140:141], v[242:243], v[42:43], v[140:141] op_sel:[0,1,0]
	v_pk_fma_f32 v[142:143], v[250:251], v[42:43], v[142:143] op_sel:[0,1,0]
	v_permlane32_swap_b32_e32 v124, v92
	v_add_f32_e32 v124, v124, v92
	ds_write_b32 v235, v124
	v_add_f32_dpp v44, v252, v252 quad_perm:[1,0,3,2] row_mask:0xf bank_mask:0xf
	v_add_f32_dpp v45, v253, v253 quad_perm:[1,0,3,2] row_mask:0xf bank_mask:0xf
	v_add_f32_dpp v46, v254, v254 quad_perm:[1,0,3,2] row_mask:0xf bank_mask:0xf
	v_add_f32_dpp v47, v255, v255 quad_perm:[1,0,3,2] row_mask:0xf bank_mask:0xf
	v_cndmask_b32_e32 v44, v46, v44, vcc
	v_cndmask_b32_e32 v45, v47, v45, vcc
	v_add_f32_dpp v50, v48, v48 quad_perm:[2,3,0,1] row_mask:0xf bank_mask:0xf
	v_add_f32_dpp v51, v49, v49 quad_perm:[2,3,0,1] row_mask:0xf bank_mask:0xf
	v_cndmask_b32_e64 v48, v51, v50, s[4:5]
	v_cndmask_b32_e64 v53, v48, v52, s[6:7]
	v_cndmask_b32_e64 v54, v52, v48, s[6:7]
	s_waitcnt vmcnt(9)
	v_pk_mul_f32 v[252:253], v[236:237], v[36:37] op_sel_hi:[1,0]
	v_pk_mul_f32 v[254:255], v[244:245], v[36:37] op_sel_hi:[1,0]
	v_pk_fma_f32 v[252:253], v[238:239], v[36:37], v[252:253] op_sel:[0,1,0]
	v_pk_fma_f32 v[254:255], v[246:247], v[36:37], v[254:255] op_sel:[0,1,0]
	v_pk_fma_f32 v[252:253], v[240:241], v[38:39], v[252:253] op_sel_hi:[1,0,1]
	v_pk_fma_f32 v[254:255], v[248:249], v[38:39], v[254:255] op_sel_hi:[1,0,1]
	v_pk_fma_f32 v[252:253], v[242:243], v[38:39], v[252:253] op_sel:[0,1,0]
	v_pk_fma_f32 v[254:255], v[250:251], v[38:39], v[254:255] op_sel:[0,1,0]
	v_add_f32_dpp v52, v54, v53 row_ror:4 row_mask:0xf bank_mask:0xf
	v_cndmask_b32_e64 v61, v52, v60, s[64:65]
	v_cndmask_b32_e64 v62, v60, v52, s[64:65]
	v_add_f32_dpp v40, v140, v140 quad_perm:[1,0,3,2] row_mask:0xf bank_mask:0xf
	v_add_f32_dpp v41, v141, v141 quad_perm:[1,0,3,2] row_mask:0xf bank_mask:0xf
	v_add_f32_dpp v42, v142, v142 quad_perm:[1,0,3,2] row_mask:0xf bank_mask:0xf
	v_add_f32_dpp v43, v143, v143 quad_perm:[1,0,3,2] row_mask:0xf bank_mask:0xf
	v_cndmask_b32_e32 v40, v42, v40, vcc
	v_cndmask_b32_e32 v41, v43, v41, vcc
	v_add_f32_dpp v46, v44, v44 quad_perm:[2,3,0,1] row_mask:0xf bank_mask:0xf
	v_add_f32_dpp v47, v45, v45 quad_perm:[2,3,0,1] row_mask:0xf bank_mask:0xf
	v_cndmask_b32_e64 v44, v47, v46, s[4:5]
	s_waitcnt vmcnt(8)
	v_pk_mul_f32 v[140:141], v[236:237], v[32:33] op_sel_hi:[1,0]
	v_pk_mul_f32 v[142:143], v[244:245], v[32:33] op_sel_hi:[1,0]
	v_pk_fma_f32 v[140:141], v[238:239], v[32:33], v[140:141] op_sel:[0,1,0]
	v_pk_fma_f32 v[142:143], v[246:247], v[32:33], v[142:143] op_sel:[0,1,0]
	v_pk_fma_f32 v[140:141], v[240:241], v[34:35], v[140:141] op_sel_hi:[1,0,1]
	v_pk_fma_f32 v[142:143], v[248:249], v[34:35], v[142:143] op_sel_hi:[1,0,1]
	v_pk_fma_f32 v[140:141], v[242:243], v[34:35], v[140:141] op_sel:[0,1,0]
	v_pk_fma_f32 v[142:143], v[250:251], v[34:35], v[142:143] op_sel:[0,1,0]
	v_add_f32_dpp v60, v62, v61 row_ror:8 row_mask:0xf bank_mask:0xf
	v_add_f32_dpp v36, v252, v252 quad_perm:[1,0,3,2] row_mask:0xf bank_mask:0xf
	v_add_f32_dpp v37, v253, v253 quad_perm:[1,0,3,2] row_mask:0xf bank_mask:0xf
	v_add_f32_dpp v38, v254, v254 quad_perm:[1,0,3,2] row_mask:0xf bank_mask:0xf
	v_add_f32_dpp v39, v255, v255 quad_perm:[1,0,3,2] row_mask:0xf bank_mask:0xf
	v_cndmask_b32_e32 v36, v38, v36, vcc
	v_cndmask_b32_e32 v37, v39, v37, vcc
	v_add_f32_dpp v42, v40, v40 quad_perm:[2,3,0,1] row_mask:0xf bank_mask:0xf
	v_add_f32_dpp v43, v41, v41 quad_perm:[2,3,0,1] row_mask:0xf bank_mask:0xf
	v_cndmask_b32_e64 v40, v43, v42, s[4:5]
	v_cndmask_b32_e64 v45, v40, v44, s[6:7]
	v_cndmask_b32_e64 v46, v44, v40, s[6:7]
	s_waitcnt vmcnt(7)
	v_pk_mul_f32 v[252:253], v[236:237], v[28:29] op_sel_hi:[1,0]
	v_pk_mul_f32 v[254:255], v[244:245], v[28:29] op_sel_hi:[1,0]
	v_pk_fma_f32 v[252:253], v[238:239], v[28:29], v[252:253] op_sel:[0,1,0]
	v_pk_fma_f32 v[254:255], v[246:247], v[28:29], v[254:255] op_sel:[0,1,0]
	v_pk_fma_f32 v[252:253], v[240:241], v[30:31], v[252:253] op_sel_hi:[1,0,1]
	v_pk_fma_f32 v[254:255], v[248:249], v[30:31], v[254:255] op_sel_hi:[1,0,1]
	v_pk_fma_f32 v[252:253], v[242:243], v[30:31], v[252:253] op_sel:[0,1,0]
	v_pk_fma_f32 v[254:255], v[250:251], v[30:31], v[254:255] op_sel:[0,1,0]
	v_add_f32_dpp v44, v46, v45 row_ror:4 row_mask:0xf bank_mask:0xf
	v_add_f32_dpp v32, v140, v140 quad_perm:[1,0,3,2] row_mask:0xf bank_mask:0xf
	v_add_f32_dpp v33, v141, v141 quad_perm:[1,0,3,2] row_mask:0xf bank_mask:0xf
	v_add_f32_dpp v34, v142, v142 quad_perm:[1,0,3,2] row_mask:0xf bank_mask:0xf
	v_add_f32_dpp v35, v143, v143 quad_perm:[1,0,3,2] row_mask:0xf bank_mask:0xf
	v_cndmask_b32_e32 v32, v34, v32, vcc
	v_cndmask_b32_e32 v33, v35, v33, vcc
	v_add_f32_dpp v38, v36, v36 quad_perm:[2,3,0,1] row_mask:0xf bank_mask:0xf
	v_add_f32_dpp v39, v37, v37 quad_perm:[2,3,0,1] row_mask:0xf bank_mask:0xf
	v_cndmask_b32_e64 v36, v39, v38, s[4:5]
	s_waitcnt vmcnt(6)
; DI void attn_sample_item(const Params& p, int item, ldsp lds, int tid_) {
;     ...
;   SC_SCORE(kvA, 0)
;   SC_SCORE(kvB, 1)
	v_pk_mul_f32 v[140:141], v[236:237], v[24:25] op_sel_hi:[1,0]
	v_pk_mul_f32 v[142:143], v[244:245], v[24:25] op_sel_hi:[1,0]
	v_pk_fma_f32 v[140:141], v[238:239], v[24:25], v[140:141] op_sel:[0,1,0]
	v_pk_fma_f32 v[142:143], v[246:247], v[24:25], v[142:143] op_sel:[0,1,0]
	v_pk_fma_f32 v[140:141], v[240:241], v[26:27], v[140:141] op_sel_hi:[1,0,1]
	v_pk_fma_f32 v[142:143], v[248:249], v[26:27], v[142:143] op_sel_hi:[1,0,1]
	v_pk_fma_f32 v[140:141], v[242:243], v[26:27], v[140:141] op_sel:[0,1,0]
	v_pk_fma_f32 v[142:143], v[250:251], v[26:27], v[142:143] op_sel:[0,1,0]
	v_add_f32_dpp v28, v252, v252 quad_perm:[1,0,3,2] row_mask:0xf bank_mask:0xf
	v_add_f32_dpp v29, v253, v253 quad_perm:[1,0,3,2] row_mask:0xf bank_mask:0xf
	v_add_f32_dpp v30, v254, v254 quad_perm:[1,0,3,2] row_mask:0xf bank_mask:0xf
	v_add_f32_dpp v31, v255, v255 quad_perm:[1,0,3,2] row_mask:0xf bank_mask:0xf
	v_cndmask_b32_e32 v28, v30, v28, vcc
	v_cndmask_b32_e32 v29, v31, v29, vcc
	v_add_f32_dpp v34, v32, v32 quad_perm:[2,3,0,1] row_mask:0xf bank_mask:0xf
	v_add_f32_dpp v35, v33, v33 quad_perm:[2,3,0,1] row_mask:0xf bank_mask:0xf
	v_cndmask_b32_e64 v32, v35, v34, s[4:5]
	v_cndmask_b32_e64 v37, v32, v36, s[6:7]
	v_cndmask_b32_e64 v38, v36, v32, s[6:7]
	s_waitcnt vmcnt(5)
	v_pk_mul_f32 v[252:253], v[236:237], v[20:21] op_sel_hi:[1,0]
	v_pk_mul_f32 v[254:255], v[244:245], v[20:21] op_sel_hi:[1,0]
	v_pk_fma_f32 v[252:253], v[238:239], v[20:21], v[252:253] op_sel:[0,1,0]
	v_pk_fma_f32 v[254:255], v[246:247], v[20:21], v[254:255] op_sel:[0,1,0]
	v_pk_fma_f32 v[252:253], v[240:241], v[22:23], v[252:253] op_sel_hi:[1,0,1]
	v_pk_fma_f32 v[254:255], v[248:249], v[22:23], v[254:255] op_sel_hi:[1,0,1]
	v_pk_fma_f32 v[252:253], v[242:243], v[22:23], v[252:253] op_sel:[0,1,0]
	v_pk_fma_f32 v[254:255], v[250:251], v[22:23], v[254:255] op_sel:[0,1,0]
	v_add_f32_dpp v36, v38, v37 row_ror:4 row_mask:0xf bank_mask:0xf
	v_cndmask_b32_e64 v45, v36, v44, s[64:65]
	v_cndmask_b32_e64 v46, v44, v36, s[64:65]
	v_add_f32_dpp v24, v140, v140 quad_perm:[1,0,3,2] row_mask:0xf bank_mask:0xf
	v_add_f32_dpp v25, v141, v141 quad_perm:[1,0,3,2] row_mask:0xf bank_mask:0xf
	v_add_f32_dpp v26, v142, v142 quad_perm:[1,0,3,2] row_mask:0xf bank_mask:0xf
	v_add_f32_dpp v27, v143, v143 quad_perm:[1,0,3,2] row_mask:0xf bank_mask:0xf
	v_cndmask_b32_e32 v24, v26, v24, vcc
	v_cndmask_b32_e32 v25, v27, v25, vcc
	v_add_f32_dpp v30, v28, v28 quad_perm:[2,3,0,1] row_mask:0xf bank_mask:0xf
	v_add_f32_dpp v31, v29, v29 quad_perm:[2,3,0,1] row_mask:0xf bank_mask:0xf
	v_cndmask_b32_e64 v28, v31, v30, s[4:5]
	s_waitcnt vmcnt(4)
	v_pk_mul_f32 v[140:141], v[236:237], v[16:17] op_sel_hi:[1,0]
	v_pk_mul_f32 v[142:143], v[244:245], v[16:17] op_sel_hi:[1,0]
	v_pk_fma_f32 v[140:141], v[238:239], v[16:17], v[140:141] op_sel:[0,1,0]
	v_pk_fma_f32 v[142:143], v[246:247], v[16:17], v[142:143] op_sel:[0,1,0]
	v_pk_fma_f32 v[140:141], v[240:241], v[18:19], v[140:141] op_sel_hi:[1,0,1]
	v_pk_fma_f32 v[142:143], v[248:249], v[18:19], v[142:143] op_sel_hi:[1,0,1]
	v_pk_fma_f32 v[140:141], v[242:243], v[18:19], v[140:141] op_sel:[0,1,0]
	v_pk_fma_f32 v[142:143], v[250:251], v[18:19], v[142:143] op_sel:[0,1,0]
	v_add_f32_dpp v44, v46, v45 row_ror:8 row_mask:0xf bank_mask:0xf
	v_add_f32_dpp v20, v252, v252 quad_perm:[1,0,3,2] row_mask:0xf bank_mask:0xf
	v_add_f32_dpp v21, v253, v253 quad_perm:[1,0,3,2] row_mask:0xf bank_mask:0xf
	v_add_f32_dpp v22, v254, v254 quad_perm:[1,0,3,2] row_mask:0xf bank_mask:0xf
	v_add_f32_dpp v23, v255, v255 quad_perm:[1,0,3,2] row_mask:0xf bank_mask:0xf
	v_cndmask_b32_e32 v20, v22, v20, vcc
	v_cndmask_b32_e32 v21, v23, v21, vcc
	v_add_f32_dpp v26, v24, v24 quad_perm:[2,3,0,1] row_mask:0xf bank_mask:0xf
	v_add_f32_dpp v27, v25, v25 quad_perm:[2,3,0,1] row_mask:0xf bank_mask:0xf
	v_cndmask_b32_e64 v24, v27, v26, s[4:5]
	v_cndmask_b32_e64 v29, v24, v28, s[6:7]
	v_cndmask_b32_e64 v30, v28, v24, s[6:7]
	s_waitcnt vmcnt(3)
	v_pk_mul_f32 v[252:253], v[236:237], v[12:13] op_sel_hi:[1,0]
	v_pk_mul_f32 v[254:255], v[244:245], v[12:13] op_sel_hi:[1,0]
	v_pk_fma_f32 v[252:253], v[238:239], v[12:13], v[252:253] op_sel:[0,1,0]
	v_pk_fma_f32 v[254:255], v[246:247], v[12:13], v[254:255] op_sel:[0,1,0]
	v_pk_fma_f32 v[252:253], v[240:241], v[14:15], v[252:253] op_sel_hi:[1,0,1]
	v_pk_fma_f32 v[254:255], v[248:249], v[14:15], v[254:255] op_sel_hi:[1,0,1]
	v_pk_fma_f32 v[252:253], v[242:243], v[14:15], v[252:253] op_sel:[0,1,0]
	v_pk_fma_f32 v[254:255], v[250:251], v[14:15], v[254:255] op_sel:[0,1,0]
	v_permlane16_swap_b32_e32 v60, v44
	v_add_f32_e32 v60, v60, v44
	v_add_f32_dpp v28, v30, v29 row_ror:4 row_mask:0xf bank_mask:0xf
	v_add_f32_dpp v16, v140, v140 quad_perm:[1,0,3,2] row_mask:0xf bank_mask:0xf
	v_add_f32_dpp v17, v141, v141 quad_perm:[1,0,3,2] row_mask:0xf bank_mask:0xf
	v_add_f32_dpp v18, v142, v142 quad_perm:[1,0,3,2] row_mask:0xf bank_mask:0xf
	v_add_f32_dpp v19, v143, v143 quad_perm:[1,0,3,2] row_mask:0xf bank_mask:0xf
	v_cndmask_b32_e32 v16, v18, v16, vcc
	v_cndmask_b32_e32 v17, v19, v17, vcc
	v_add_f32_dpp v22, v20, v20 quad_perm:[2,3,0,1] row_mask:0xf bank_mask:0xf
	v_add_f32_dpp v23, v21, v21 quad_perm:[2,3,0,1] row_mask:0xf bank_mask:0xf
	v_cndmask_b32_e64 v20, v23, v22, s[4:5]
	s_waitcnt vmcnt(2)
; DI void attn_sample_item(const Params& p, int item, ldsp lds, int tid_) {
;     ...
;   SC_SCORE(kvA, 0)
;   SC_SCORE(kvB, 1)
	v_pk_mul_f32 v[140:141], v[236:237], v[8:9] op_sel_hi:[1,0]
	v_pk_mul_f32 v[142:143], v[244:245], v[8:9] op_sel_hi:[1,0]
	v_pk_fma_f32 v[140:141], v[238:239], v[8:9], v[140:141] op_sel:[0,1,0]
	v_pk_fma_f32 v[142:143], v[246:247], v[8:9], v[142:143] op_sel:[0,1,0]
	v_pk_fma_f32 v[140:141], v[240:241], v[10:11], v[140:141] op_sel_hi:[1,0,1]
	v_pk_fma_f32 v[142:143], v[248:249], v[10:11], v[142:143] op_sel_hi:[1,0,1]
	v_pk_fma_f32 v[140:141], v[242:243], v[10:11], v[140:141] op_sel:[0,1,0]
	v_pk_fma_f32 v[142:143], v[250:251], v[10:11], v[142:143] op_sel:[0,1,0]
	v_add_f32_dpp v12, v252, v252 quad_perm:[1,0,3,2] row_mask:0xf bank_mask:0xf
	v_add_f32_dpp v13, v253, v253 quad_perm:[1,0,3,2] row_mask:0xf bank_mask:0xf
	v_add_f32_dpp v14, v254, v254 quad_perm:[1,0,3,2] row_mask:0xf bank_mask:0xf
	v_add_f32_dpp v15, v255, v255 quad_perm:[1,0,3,2] row_mask:0xf bank_mask:0xf
	v_cndmask_b32_e32 v12, v14, v12, vcc
	v_cndmask_b32_e32 v13, v15, v13, vcc
	v_add_f32_dpp v18, v16, v16 quad_perm:[2,3,0,1] row_mask:0xf bank_mask:0xf
	v_add_f32_dpp v19, v17, v17 quad_perm:[2,3,0,1] row_mask:0xf bank_mask:0xf
	v_cndmask_b32_e64 v16, v19, v18, s[4:5]
	v_cndmask_b32_e64 v21, v16, v20, s[6:7]
	v_cndmask_b32_e64 v22, v20, v16, s[6:7]
	s_waitcnt vmcnt(1)
	v_pk_mul_f32 v[252:253], v[236:237], v[4:5] op_sel_hi:[1,0]
	v_pk_mul_f32 v[254:255], v[244:245], v[4:5] op_sel_hi:[1,0]
	v_pk_fma_f32 v[252:253], v[238:239], v[4:5], v[252:253] op_sel:[0,1,0]
	v_pk_fma_f32 v[254:255], v[246:247], v[4:5], v[254:255] op_sel:[0,1,0]
	v_pk_fma_f32 v[252:253], v[240:241], v[6:7], v[252:253] op_sel_hi:[1,0,1]
	v_pk_fma_f32 v[254:255], v[248:249], v[6:7], v[254:255] op_sel_hi:[1,0,1]
	v_pk_fma_f32 v[252:253], v[242:243], v[6:7], v[252:253] op_sel:[0,1,0]
	v_pk_fma_f32 v[254:255], v[250:251], v[6:7], v[254:255] op_sel:[0,1,0]
	v_add_f32_dpp v20, v22, v21 row_ror:4 row_mask:0xf bank_mask:0xf
	v_cndmask_b32_e64 v29, v20, v28, s[64:65]
	v_cndmask_b32_e64 v30, v28, v20, s[64:65]
	v_add_f32_dpp v8, v140, v140 quad_perm:[1,0,3,2] row_mask:0xf bank_mask:0xf
	v_add_f32_dpp v9, v141, v141 quad_perm:[1,0,3,2] row_mask:0xf bank_mask:0xf
	v_add_f32_dpp v10, v142, v142 quad_perm:[1,0,3,2] row_mask:0xf bank_mask:0xf
	v_add_f32_dpp v11, v143, v143 quad_perm:[1,0,3,2] row_mask:0xf bank_mask:0xf
	v_cndmask_b32_e32 v8, v10, v8, vcc
	v_cndmask_b32_e32 v9, v11, v9, vcc
	v_add_f32_dpp v14, v12, v12 quad_perm:[2,3,0,1] row_mask:0xf bank_mask:0xf
	v_add_f32_dpp v15, v13, v13 quad_perm:[2,3,0,1] row_mask:0xf bank_mask:0xf
	v_cndmask_b32_e64 v12, v15, v14, s[4:5]
	s_waitcnt vmcnt(0)
; DI void lbar() { asm volatile("s_waitcnt lgkmcnt(0)" ::: "memory"); __builtin_amdgcn_s_barrier(); asm volatile("" ::: "memory"); }
; DI void attn_sample_item(const Params& p, int item, ldsp lds, int tid_) {
;     ...
;   SC_SCORE(kvA, 0)
;   SC_SCORE(kvB, 1)
;     ...
;   f32x4 vvA[16], vvB[16];
; #pragma unroll
;   for (int j = 0; j < 16; ++j) vvA[j] = __builtin_nontemporal_load((const f32x4*)(cv + (size_t)(wid * 32 + j) * 1024 + lane * 4));
;   lbar();
;     ...
; #pragma unroll
;   for (int j = 0; j < 16; ++j) vvB[j] = __builtin_nontemporal_load((const f32x4*)(cv + (size_t)(wid * 32 + 16 + j) * 1024 + lane * 4));
	v_pk_mul_f32 v[140:141], v[236:237], v[0:1] op_sel_hi:[1,0]
	v_pk_mul_f32 v[142:143], v[244:245], v[0:1] op_sel_hi:[1,0]
	v_pk_fma_f32 v[140:141], v[238:239], v[0:1], v[140:141] op_sel:[0,1,0]
	v_pk_fma_f32 v[142:143], v[246:247], v[0:1], v[142:143] op_sel:[0,1,0]
	v_pk_fma_f32 v[140:141], v[240:241], v[2:3], v[140:141] op_sel_hi:[1,0,1]
	v_pk_fma_f32 v[142:143], v[248:249], v[2:3], v[142:143] op_sel_hi:[1,0,1]
	v_pk_fma_f32 v[140:141], v[242:243], v[2:3], v[140:141] op_sel:[0,1,0]
	v_pk_fma_f32 v[142:143], v[250:251], v[2:3], v[142:143] op_sel:[0,1,0]
	v_add_f32_dpp v28, v30, v29 row_ror:8 row_mask:0xf bank_mask:0xf
	v_add_f32_dpp v4, v252, v252 quad_perm:[1,0,3,2] row_mask:0xf bank_mask:0xf
	v_add_f32_dpp v5, v253, v253 quad_perm:[1,0,3,2] row_mask:0xf bank_mask:0xf
	v_add_f32_dpp v6, v254, v254 quad_perm:[1,0,3,2] row_mask:0xf bank_mask:0xf
	v_add_f32_dpp v7, v255, v255 quad_perm:[1,0,3,2] row_mask:0xf bank_mask:0xf
	v_cndmask_b32_e32 v4, v6, v4, vcc
	v_cndmask_b32_e32 v5, v7, v5, vcc
	v_add_f32_dpp v10, v8, v8 quad_perm:[2,3,0,1] row_mask:0xf bank_mask:0xf
	v_add_f32_dpp v11, v9, v9 quad_perm:[2,3,0,1] row_mask:0xf bank_mask:0xf
	v_cndmask_b32_e64 v8, v11, v10, s[4:5]
	v_cndmask_b32_e64 v13, v8, v12, s[6:7]
	v_cndmask_b32_e64 v14, v12, v8, s[6:7]
	s_nop 1
	v_add_f32_dpp v12, v14, v13 row_ror:4 row_mask:0xf bank_mask:0xf
	v_add_f32_dpp v0, v140, v140 quad_perm:[1,0,3,2] row_mask:0xf bank_mask:0xf
	v_add_f32_dpp v1, v141, v141 quad_perm:[1,0,3,2] row_mask:0xf bank_mask:0xf
	v_add_f32_dpp v2, v142, v142 quad_perm:[1,0,3,2] row_mask:0xf bank_mask:0xf
	v_add_f32_dpp v3, v143, v143 quad_perm:[1,0,3,2] row_mask:0xf bank_mask:0xf
	v_cndmask_b32_e32 v0, v2, v0, vcc
	v_cndmask_b32_e32 v1, v3, v1, vcc
	v_add_f32_dpp v6, v4, v4 quad_perm:[2,3,0,1] row_mask:0xf bank_mask:0xf
	v_add_f32_dpp v7, v5, v5 quad_perm:[2,3,0,1] row_mask:0xf bank_mask:0xf
	v_cndmask_b32_e64 v4, v7, v6, s[4:5]
	v_add_f32_dpp v2, v0, v0 quad_perm:[2,3,0,1] row_mask:0xf bank_mask:0xf
	v_add_f32_dpp v3, v1, v1 quad_perm:[2,3,0,1] row_mask:0xf bank_mask:0xf
	v_cndmask_b32_e64 v0, v3, v2, s[4:5]
	v_cndmask_b32_e64 v5, v0, v4, s[6:7]
	v_cndmask_b32_e64 v6, v4, v0, s[6:7]
	s_nop 1
	v_add_f32_dpp v4, v6, v5 row_ror:4 row_mask:0xf bank_mask:0xf
	v_cndmask_b32_e64 v13, v4, v12, s[64:65]
	v_cndmask_b32_e64 v14, v12, v4, s[64:65]
	s_nop 1
	v_add_f32_dpp v12, v14, v13 row_ror:8 row_mask:0xf bank_mask:0xf
	s_nop 1
	v_permlane16_swap_b32_e32 v28, v12
	v_add_f32_e32 v28, v28, v12
	s_nop 1
	v_permlane32_swap_b32_e32 v60, v28
	v_add_f32_e32 v60, v60, v28
	ds_write_b32 v235, v60 offset:64
	v_add_u32_e32 v100, v162, v144
	global_load_dwordx4 v[100:103], v100, s[66:67] nt
	v_add_u32_e32 v92, v166, v144
	global_load_dwordx4 v[92:95], v92, s[66:67] nt
	v_add_u32_e32 v112, v168, v144
	global_load_dwordx4 v[112:115], v112, s[66:67] nt
	v_add_u32_e32 v108, v172, v144
	global_load_dwordx4 v[108:111], v108, s[66:67] nt
	v_add_u32_e32 v120, v176, v144
	global_load_dwordx4 v[120:123], v120, s[66:67] nt
	v_add_u32_e32 v116, v180, v144
	global_load_dwordx4 v[116:119], v116, s[66:67] nt
	v_add_u32_e32 v124, v182, v144
	global_load_dwordx4 v[124:127], v124, s[66:67] nt
	v_add_u32_e32 v104, v186, v144
	global_load_dwordx4 v[104:107], v104, s[66:67] nt
	v_add_u32_e32 v68, v190, v144
	global_load_dwordx4 v[68:71], v68, s[66:67] nt
	v_add_u32_e32 v64, v194, v144
	global_load_dwordx4 v[64:67], v64, s[66:67] nt
	v_add_u32_e32 v80, v198, v144
	global_load_dwordx4 v[80:83], v80, s[66:67] nt
	v_add_u32_e32 v76, v200, v144
	global_load_dwordx4 v[76:79], v76, s[66:67] nt
	v_add_u32_e32 v88, v202, v144
	global_load_dwordx4 v[88:91], v88, s[66:67] nt
	v_add_u32_e32 v84, v204, v144
	global_load_dwordx4 v[84:87], v84, s[66:67] nt
	v_add_u32_e32 v96, v206, v144
	global_load_dwordx4 v[96:99], v96, s[66:67] nt
	v_add_u32_e32 v72, v208, v144
	global_load_dwordx4 v[72:75], v72, s[66:67] nt
	v_add_u32_e32 v40, v146, v144
	global_load_dwordx4 v[40:43], v40, s[66:67] nt
	v_add_u32_e32 v36, v148, v144
	global_load_dwordx4 v[36:39], v36, s[66:67] nt
	v_add_u32_e32 v48, v150, v144
	global_load_dwordx4 v[48:51], v48, s[66:67] nt
	v_add_u32_e32 v44, v152, v144
	global_load_dwordx4 v[44:47], v44, s[66:67] nt
	v_add_u32_e32 v56, v154, v144
	global_load_dwordx4 v[56:59], v56, s[66:67] nt
	v_add_u32_e32 v52, v156, v144
	global_load_dwordx4 v[52:55], v52, s[66:67] nt
	v_add_u32_e32 v60, v158, v144
	global_load_dwordx4 v[60:63], v60, s[66:67] nt
	v_add_u32_e32 v32, v160, v144
	global_load_dwordx4 v[32:35], v32, s[66:67] nt
	v_add_u32_e32 v12, v164, v144
	global_load_dwordx4 v[12:15], v12, s[66:67] nt
	v_add_u32_e32 v4, v170, v144
	global_load_dwordx4 v[4:7], v4, s[66:67] nt
	v_add_u32_e32 v20, v174, v144
	global_load_dwordx4 v[20:23], v20, s[66:67] nt
	v_add_u32_e32 v8, v178, v144
	global_load_dwordx4 v[8:11], v8, s[66:67] nt
	v_add_u32_e32 v24, v184, v144
	global_load_dwordx4 v[24:27], v24, s[66:67] nt
	v_add_u32_e32 v16, v188, v144
	global_load_dwordx4 v[16:19], v16, s[66:67] nt
	v_add_u32_e32 v28, v192, v144
	global_load_dwordx4 v[28:31], v28, s[66:67] nt
	v_add_u32_e32 v0, v196, v144
	global_load_dwordx4 v[0:3], v0, s[66:67] nt
	v_lshlrev_b32_e32 v240, 2, v223
	s_waitcnt lgkmcnt(0)
	s_barrier
	v_cmp_gt_i32_e32 vcc, 4, v210
	s_and_saveexec_b64 s[4:5], vcc
	s_cbranch_execz .LBB0_1603

; DI float wave_sum(float v) { for (int o = 32; o >= 1; o >>= 1) v += __shfl_xor(v, o); return v; }
; DI void attn_sample_item(const Params& p, int item, ldsp lds, int tid_) {
;     ...
;   if (wid < 4) {
;     float v[4]; float mx = -1e30f;
; #pragma unroll
;     for (int j = 0; j < 4; ++j) { v[j] = SC[wid * 256 + j * 64 + lane]; mx = fmaxf(mx, v[j]); }
;     for (int o = 32; o >= 1; o >>= 1) mx = fmaxf(mx, __shfl_xor(mx, o));
;     float s = 0.f;
; #pragma unroll
;     for (int j = 0; j < 4; ++j) { v[j] = __expf(v[j] - mx); s += v[j]; }
;     s = wave_sum(s); const float inv = 1.f / s;
; #pragma unroll
;     for (int j = 0; j < 4; ++j) SC[wid * 256 + j * 64 + lane] = v[j] * inv;
;   }
	v_lshlrev_b32_e32 v241, 10, v210
	v_add3_u32 v244, 16, v241, v240
	ds_read2st64_b32 v[240:241], v244 offset1:1
	ds_read2st64_b32 v[242:243], v244 offset0:2 offset1:3
	s_waitcnt lgkmcnt(1)
	v_max3_f32 v245, v240, s39, v241
	s_waitcnt lgkmcnt(0)
	v_max3_f32 v245, v245, v242, v243
	ds_bpermute_b32 v246, v133, v245
	s_waitcnt lgkmcnt(0)
	v_max_f32_e32 v246, v246, v246
	v_max_f32_e32 v245, v245, v246
	ds_bpermute_b32 v246, v132, v245
	s_waitcnt lgkmcnt(0)
	v_max_f32_e32 v246, v246, v246
	v_max_f32_e32 v245, v245, v246
	ds_bpermute_b32 v246, v131, v245
	s_waitcnt lgkmcnt(0)
	v_max_f32_e32 v246, v246, v246
	v_max_f32_e32 v245, v245, v246
	ds_bpermute_b32 v246, v130, v245
	s_waitcnt lgkmcnt(0)
	v_max_f32_e32 v246, v246, v246
	v_max_f32_e32 v245, v245, v246
	ds_bpermute_b32 v246, v129, v245
	s_waitcnt lgkmcnt(0)
	v_max_f32_e32 v246, v246, v246
	v_max_f32_e32 v245, v245, v246
	ds_bpermute_b32 v246, v128, v245
	s_waitcnt lgkmcnt(0)
	v_max_f32_e32 v246, v246, v246
	v_max_f32_e32 v245, v245, v246
	v_sub_f32_e32 v240, v240, v245
	v_sub_f32_e32 v241, v241, v245
	v_mul_f32_e32 v240, 0x3fb8aa3b, v240
	v_sub_f32_e32 v242, v242, v245
	v_mul_f32_e32 v241, 0x3fb8aa3b, v241
	v_exp_f32_e32 v240, v240
	v_sub_f32_e32 v243, v243, v245
	v_mul_f32_e32 v242, 0x3fb8aa3b, v242
	v_exp_f32_e32 v241, v241
	v_mul_f32_e32 v243, 0x3fb8aa3b, v243
	v_exp_f32_e32 v242, v242
	v_exp_f32_e32 v243, v243
	v_add_f32_e32 v245, 0, v240
	v_add_f32_e32 v245, v241, v245
	v_add_f32_e32 v245, v242, v245
	v_add_f32_e32 v245, v243, v245
	ds_bpermute_b32 v246, v133, v245
	s_waitcnt lgkmcnt(0)
	v_add_f32_e32 v245, v245, v246
	ds_bpermute_b32 v246, v132, v245
	s_waitcnt lgkmcnt(0)
	v_add_f32_e32 v245, v245, v246
	ds_bpermute_b32 v246, v131, v245
	s_waitcnt lgkmcnt(0)
	v_add_f32_e32 v245, v245, v246
	ds_bpermute_b32 v246, v130, v245
	s_waitcnt lgkmcnt(0)
	v_add_f32_e32 v245, v245, v246
	ds_bpermute_b32 v246, v129, v245
	s_waitcnt lgkmcnt(0)
	v_add_f32_e32 v245, v245, v246
	ds_bpermute_b32 v246, v128, v245
	s_waitcnt lgkmcnt(0)
	v_add_f32_e32 v245, v245, v246
	v_div_scale_f32 v246, s[6:7], v245, v245, 1.0
	v_rcp_f32_e32 v247, v246
	v_div_scale_f32 v248, vcc, 1.0, v245, 1.0
	v_fma_f32 v249, -v246, v247, 1.0
	v_fmac_f32_e32 v247, v249, v247
	v_mul_f32_e32 v249, v248, v247
	v_fma_f32 v250, -v246, v249, v248
	v_fmac_f32_e32 v249, v250, v247
	v_fma_f32 v246, -v246, v249, v248
	v_div_fmas_f32 v246, v246, v247, v249
	v_div_fixup_f32 v245, v246, v245, 1.0
	v_mul_f32_e32 v240, v240, v245
	v_mul_f32_e32 v241, v241, v245
	v_mul_f32_e32 v242, v242, v245
	v_mul_f32_e32 v243, v243, v245
	ds_write2st64_b32 v244, v240, v241 offset1:1
	ds_write2st64_b32 v244, v242, v243 offset0:2 offset1:3
	s_branch .LBB0_1603

; DI void attn_sample_item(const Params& p, int item, ldsp lds, int tid_) {
;     ...
;   for (int t = 0; t < 4; ++t) { f32x4 a = {0.f, 0.f, 0.f, 0.f}; const float* pp = (const float*)(p.ws + B_PART) + (size_t)(b * 4 + t) * 1024 + h * 256 + lane * 4;
; #pragma unroll
;     for (int kp = 0; kp < 4; ++kp) a += *(const f32x4*)(pp + (size_t)kp * 512 * 1024);
;     q[t][0] = a[0] * 0.0625f; q[t][1] = a[1] * 0.0625f; q[t][2] = a[2] * 0.0625f; q[t][3] = a[3] * 0.0625f; }
;   const bool b0 = lane & 1, b1 = lane & 2;
;   f32x4 kvA[16], kvB[16];
; #pragma unroll
;   for (int j = 0; j < 16; ++j) kvA[j] = __builtin_nontemporal_load((const f32x4*)(ck + (size_t)(wid * 32 + j) * 1024 + lane * 4));
; #pragma unroll
;   for (int j = 0; j < 16; ++j) kvB[j] = __builtin_nontemporal_load((const f32x4*)(ck + (size_t)(wid * 32 + 16 + j) * 1024 + lane * 4));
.LBB0_1676:
	s_ashr_i32 s4, s38, 2
	s_ashr_i32 s5, s4, 31
	s_lshl_b64 s[4:5], s[4:5], 18
	s_and_b32 s24, s0, 0x300
	v_mov_b32_e32 v222, v212
	s_or_b32 s4, s4, s24
	s_and_b32 s26, s38, -4
	s_lshl_b32 s6, s24, 2
	s_add_u32 s6, s36, s6
	v_and_b32_e32 v223, 63, v222
	s_addc_u32 s7, s37, 0
	v_lshlrev_b32_e32 v144, 4, v223
	s_lshl_b64 s[60:61], s[4:5], 2
	s_add_u32 s60, s12, s60
	s_addc_u32 s61, s13, s61
	v_ashrrev_i32_e32 v244, 6, v222
	v_lshlrev_b32_e32 v236, 5, v244
	v_lshlrev_b32_e32 v158, 12, v236
	v_mov_b32_e32 v159, 0
	v_add_u32_e32 v124, v158, v144
	global_load_dwordx4 v[124:127], v124, s[60:61] nt
	v_or_b32_e32 v240, 1, v236
	v_lshlrev_b32_e32 v162, 12, v240
	v_mov_b32_e32 v163, 0
	v_add_u32_e32 v120, v162, v144
	global_load_dwordx4 v[120:123], v120, s[60:61] nt
	v_or_b32_e32 v240, 2, v236
	v_lshlrev_b32_e32 v164, 12, v240
	v_mov_b32_e32 v165, 0
	v_add_u32_e32 v116, v164, v144
	global_load_dwordx4 v[116:119], v116, s[60:61] nt
	v_or_b32_e32 v240, 3, v236
	v_lshlrev_b32_e32 v168, 12, v240
	v_mov_b32_e32 v169, 0
	v_add_u32_e32 v112, v168, v144
	global_load_dwordx4 v[112:115], v112, s[60:61] nt
	v_or_b32_e32 v240, 4, v236
	v_lshlrev_b32_e32 v172, 12, v240
	v_mov_b32_e32 v173, 0
	v_add_u32_e32 v108, v172, v144
	global_load_dwordx4 v[108:111], v108, s[60:61] nt
	v_or_b32_e32 v240, 5, v236
	v_lshlrev_b32_e32 v176, 12, v240
	v_mov_b32_e32 v177, 0
	v_add_u32_e32 v104, v176, v144
	global_load_dwordx4 v[104:107], v104, s[60:61] nt
	v_or_b32_e32 v240, 6, v236
	v_lshlrev_b32_e32 v180, 12, v240
	v_mov_b32_e32 v181, 0
	v_add_u32_e32 v100, v180, v144
	global_load_dwordx4 v[100:103], v100, s[60:61] nt
	v_or_b32_e32 v240, 7, v236
	v_lshlrev_b32_e32 v184, 12, v240
	v_mov_b32_e32 v185, 0
	v_add_u32_e32 v96, v184, v144
	global_load_dwordx4 v[96:99], v96, s[60:61] nt
	v_or_b32_e32 v240, 8, v236
	v_lshlrev_b32_e32 v188, 12, v240
	v_mov_b32_e32 v189, 0
	v_add_u32_e32 v92, v188, v144
	global_load_dwordx4 v[92:95], v92, s[60:61] nt
	v_or_b32_e32 v240, 9, v236
	v_lshlrev_b32_e32 v192, 12, v240
	v_mov_b32_e32 v193, 0
	v_add_u32_e32 v88, v192, v144
	global_load_dwordx4 v[88:91], v88, s[60:61] nt
	v_or_b32_e32 v240, 10, v236
	v_lshlrev_b32_e32 v196, 12, v240
	v_mov_b32_e32 v197, 0
	v_add_u32_e32 v84, v196, v144
	global_load_dwordx4 v[84:87], v84, s[60:61] nt
	v_or_b32_e32 v240, 11, v236
	v_lshlrev_b32_e32 v200, 12, v240
	v_mov_b32_e32 v201, 0
	v_add_u32_e32 v80, v200, v144
	global_load_dwordx4 v[80:83], v80, s[60:61] nt
	v_or_b32_e32 v240, 12, v236
	v_lshlrev_b32_e32 v202, 12, v240
	v_mov_b32_e32 v203, 0
	v_add_u32_e32 v76, v202, v144
	global_load_dwordx4 v[76:79], v76, s[60:61] nt
	v_or_b32_e32 v240, 13, v236
	v_lshlrev_b32_e32 v204, 12, v240
	v_mov_b32_e32 v205, 0
	v_add_u32_e32 v72, v204, v144
	global_load_dwordx4 v[72:75], v72, s[60:61] nt
	v_or_b32_e32 v240, 14, v236
	v_lshlrev_b32_e32 v206, 12, v240
	v_mov_b32_e32 v207, 0
	v_add_u32_e32 v68, v206, v144
	global_load_dwordx4 v[68:71], v68, s[60:61] nt
	v_or_b32_e32 v240, 15, v236
	v_lshlrev_b32_e32 v208, 12, v240
	v_mov_b32_e32 v209, 0
	v_add_u32_e32 v64, v208, v144
	global_load_dwordx4 v[64:67], v64, s[60:61] nt
	v_or_b32_e32 v240, 16, v236
	v_lshlrev_b32_e32 v146, 12, v240
	v_mov_b32_e32 v147, 0
	v_add_u32_e32 v60, v146, v144
	global_load_dwordx4 v[60:63], v60, s[60:61] nt
	v_or_b32_e32 v240, 17, v236
	v_lshlrev_b32_e32 v148, 12, v240
	v_mov_b32_e32 v149, 0
	v_add_u32_e32 v56, v148, v144
	global_load_dwordx4 v[56:59], v56, s[60:61] nt
	v_or_b32_e32 v240, 18, v236
	v_lshlrev_b32_e32 v150, 12, v240
	v_mov_b32_e32 v151, 0
	v_add_u32_e32 v52, v150, v144
	global_load_dwordx4 v[52:55], v52, s[60:61] nt
	s_ashr_i32 s27, s26, 31
	v_lshl_add_u64 v[48:49], s[6:7], 0, v[144:145]
	s_lshl_b64 s[6:7], s[26:27], 12
	v_lshl_add_u64 v[8:9], v[48:49], 0, s[6:7]
	v_add_co_u32_e32 v10, vcc, s3, v8
	s_or_b32 s6, s26, 1
	s_nop 0
	v_addc_co_u32_e32 v11, vcc, 0, v9, vcc
	global_load_dwordx4 v[0:3], v[8:9], off
	global_load_dwordx4 v[4:7], v[10:11], off
	v_add_co_u32_e32 v10, vcc, s33, v8
	s_ashr_i32 s7, s6, 31
	s_nop 0
	v_addc_co_u32_e32 v11, vcc, 0, v9, vcc
	v_add_co_u32_e32 v12, vcc, s34, v8
	s_lshl_b64 s[6:7], s[6:7], 12
	s_nop 0
	v_addc_co_u32_e32 v13, vcc, 0, v9, vcc
	v_lshl_add_u64 v[24:25], v[48:49], 0, s[6:7]
	v_add_co_u32_e32 v20, vcc, s3, v24
	s_or_b32 s6, s26, 2
	s_nop 0
	v_addc_co_u32_e32 v21, vcc, 0, v25, vcc
	v_add_co_u32_e32 v26, vcc, s33, v24
	s_ashr_i32 s7, s6, 31
	s_nop 0
	v_addc_co_u32_e32 v27, vcc, 0, v25, vcc
	v_add_co_u32_e32 v28, vcc, s34, v24
	s_lshl_b64 s[6:7], s[6:7], 12
	s_nop 0
	v_addc_co_u32_e32 v29, vcc, 0, v25, vcc
	v_lshl_add_u64 v[44:45], v[48:49], 0, s[6:7]
	global_load_dwordx4 v[8:11], v[10:11], off
	s_nop 0
	global_load_dwordx4 v[12:15], v[12:13], off
	s_nop 0
	global_load_dwordx4 v[16:19], v[24:25], off
	s_nop 0
	global_load_dwordx4 v[20:23], v[20:21], off
	v_add_co_u32_e32 v36, vcc, s3, v44
	global_load_dwordx4 v[24:27], v[26:27], off
	s_nop 0
	global_load_dwordx4 v[28:31], v[28:29], off
	v_addc_co_u32_e32 v37, vcc, 0, v45, vcc
	v_add_co_u32_e32 v40, vcc, s33, v44
	global_load_dwordx4 v[32:35], v[44:45], off
	s_nop 0
	global_load_dwordx4 v[36:39], v[36:37], off
	v_addc_co_u32_e32 v41, vcc, 0, v45, vcc
	v_add_co_u32_e32 v44, vcc, s34, v44
	global_load_dwordx4 v[40:43], v[40:41], off
	s_nop 0
	v_addc_co_u32_e32 v45, vcc, 0, v45, vcc
	global_load_dwordx4 v[44:47], v[44:45], off
	s_or_b32 s6, s38, 3
	s_ashr_i32 s7, s6, 31
	s_lshl_b64 s[6:7], s[6:7], 12
	s_lshl_b64 s[28:29], s[4:5], 2
	s_add_u32 s4, s12, s28
	s_addc_u32 s5, s13, s29
	s_waitcnt vmcnt(11)
	v_pk_add_f32 v[2:3], v[2:3], 0 op_sel_hi:[1,0]
	v_pk_add_f32 v[0:1], v[0:1], 0 op_sel_hi:[1,0]
	s_waitcnt vmcnt(10)
; DI void attn_sample_item(const Params& p, int item, ldsp lds, int tid_) {
;     ...
;   for (int t = 0; t < 4; ++t) { f32x4 a = {0.f, 0.f, 0.f, 0.f}; const float* pp = (const float*)(p.ws + B_PART) + (size_t)(b * 4 + t) * 1024 + h * 256 + lane * 4;
; #pragma unroll
;     for (int kp = 0; kp < 4; ++kp) a += *(const f32x4*)(pp + (size_t)kp * 512 * 1024);
;     q[t][0] = a[0] * 0.0625f; q[t][1] = a[1] * 0.0625f; q[t][2] = a[2] * 0.0625f; q[t][3] = a[3] * 0.0625f; }
;   const bool b0 = lane & 1, b1 = lane & 2;
;   f32x4 kvA[16], kvB[16];
; #pragma unroll
;   for (int j = 0; j < 16; ++j) kvA[j] = __builtin_nontemporal_load((const f32x4*)(ck + (size_t)(wid * 32 + j) * 1024 + lane * 4));
; #pragma unroll
;   for (int j = 0; j < 16; ++j) kvB[j] = __builtin_nontemporal_load((const f32x4*)(ck + (size_t)(wid * 32 + 16 + j) * 1024 + lane * 4));
	v_pk_add_f32 v[2:3], v[2:3], v[6:7]
	v_pk_add_f32 v[0:1], v[0:1], v[4:5]
	s_waitcnt vmcnt(9)
	v_pk_add_f32 v[2:3], v[2:3], v[10:11]
	s_waitcnt vmcnt(7)
	v_pk_add_f32 v[4:5], v[18:19], 0 op_sel_hi:[1,0]
	v_pk_add_f32 v[6:7], v[16:17], 0 op_sel_hi:[1,0]
	v_pk_add_f32 v[0:1], v[0:1], v[8:9]
	s_waitcnt vmcnt(6)
	v_pk_add_f32 v[4:5], v[4:5], v[22:23]
	v_pk_add_f32 v[6:7], v[6:7], v[20:21]
	v_pk_add_f32 v[2:3], v[2:3], v[14:15]
	v_pk_add_f32 v[0:1], v[0:1], v[12:13]
	s_waitcnt vmcnt(5)
	v_pk_add_f32 v[4:5], v[4:5], v[26:27]
	v_pk_add_f32 v[6:7], v[6:7], v[24:25]
	v_mul_f32_e32 v228, 0x3d800000, v0
	v_mul_f32_e32 v231, 0x3d800000, v1
	v_mul_f32_e32 v229, 0x3d800000, v2
	v_mul_f32_e32 v225, 0x3d800000, v3
	s_waitcnt vmcnt(4)
	v_pk_add_f32 v[0:1], v[4:5], v[30:31]
	v_pk_add_f32 v[2:3], v[6:7], v[28:29]
	v_mul_f32_e32 v227, 0x3d800000, v0
	v_mul_f32_e32 v226, 0x3d800000, v2
	v_mul_f32_e32 v230, 0x3d800000, v3
	v_mul_f32_e32 v224, 0x3d800000, v1
	s_waitcnt vmcnt(3)
	v_pk_add_f32 v[0:1], v[34:35], 0 op_sel_hi:[1,0]
	v_pk_add_f32 v[2:3], v[32:33], 0 op_sel_hi:[1,0]
	s_waitcnt vmcnt(2)
	v_pk_add_f32 v[0:1], v[0:1], v[38:39]
	v_pk_add_f32 v[2:3], v[2:3], v[36:37]
	s_waitcnt vmcnt(1)
	v_pk_add_f32 v[0:1], v[0:1], v[42:43]
	v_pk_add_f32 v[2:3], v[2:3], v[40:41]
	s_waitcnt vmcnt(0)
	v_pk_add_f32 v[210:211], v[0:1], v[46:47]
	v_pk_add_f32 v[0:1], v[2:3], v[44:45]
	v_mul_f32_e32 v233, 0x3d800000, v210
	v_mul_f32_e32 v232, 0x3d800000, v0
	v_mul_f32_e32 v234, 0x3d800000, v1
	v_lshl_add_u64 v[0:1], v[48:49], 0, s[6:7]
	v_add_co_u32_e32 v2, vcc, s3, v0
	v_ashrrev_i32_e32 v210, 6, v222
	s_nop 0
	v_addc_co_u32_e32 v3, vcc, 0, v1, vcc
	global_load_dwordx4 v[128:131], v[0:1], off
	global_load_dwordx4 v[132:135], v[2:3], off
	v_add_co_u32_e32 v2, vcc, s33, v0
	v_mul_f32_e32 v211, 0x3d800000, v211
	s_nop 0
	v_addc_co_u32_e32 v3, vcc, 0, v1, vcc
	v_add_co_u32_e32 v0, vcc, s34, v0
	v_cmp_lt_i32_e64 s[6:7], v218, v216
	s_nop 0
	v_addc_co_u32_e32 v1, vcc, 0, v1, vcc
	global_load_dwordx4 v[136:139], v[2:3], off
	global_load_dwordx4 v[140:143], v[0:1], off
	v_or_b32_e32 v240, 19, v236
	v_lshlrev_b32_e32 v152, 12, v240
	v_mov_b32_e32 v153, 0
	v_add_u32_e32 v48, v152, v144
	global_load_dwordx4 v[48:51], v48, s[60:61] nt
	v_or_b32_e32 v240, 20, v236
	v_lshlrev_b32_e32 v154, 12, v240
	v_mov_b32_e32 v155, 0
	v_add_u32_e32 v44, v154, v144
	global_load_dwordx4 v[44:47], v44, s[60:61] nt
	v_or_b32_e32 v240, 21, v236
	v_lshlrev_b32_e32 v156, 12, v240
	v_mov_b32_e32 v157, 0
	v_add_u32_e32 v40, v156, v144
	global_load_dwordx4 v[40:43], v40, s[60:61] nt
	v_or_b32_e32 v240, 22, v236
	v_lshlrev_b32_e32 v160, 12, v240
	v_mov_b32_e32 v161, 0
	v_add_u32_e32 v36, v160, v144
	global_load_dwordx4 v[36:39], v36, s[60:61] nt
	v_or_b32_e32 v240, 23, v236
	v_lshlrev_b32_e32 v166, 12, v240
	v_mov_b32_e32 v167, 0
	v_add_u32_e32 v32, v166, v144
	global_load_dwordx4 v[32:35], v32, s[60:61] nt
	v_or_b32_e32 v240, 24, v236
	v_lshlrev_b32_e32 v170, 12, v240
	v_mov_b32_e32 v171, 0
	v_add_u32_e32 v28, v170, v144
	global_load_dwordx4 v[28:31], v28, s[60:61] nt
	v_or_b32_e32 v240, 25, v236
	v_lshlrev_b32_e32 v174, 12, v240
	v_mov_b32_e32 v175, 0
	v_add_u32_e32 v24, v174, v144
	global_load_dwordx4 v[24:27], v24, s[60:61] nt
	v_or_b32_e32 v240, 26, v236
	v_lshlrev_b32_e32 v178, 12, v240
	v_mov_b32_e32 v179, 0
	v_add_u32_e32 v20, v178, v144
	global_load_dwordx4 v[20:23], v20, s[60:61] nt
	v_or_b32_e32 v240, 27, v236
	v_lshlrev_b32_e32 v182, 12, v240
	v_mov_b32_e32 v183, 0
	v_add_u32_e32 v16, v182, v144
	global_load_dwordx4 v[16:19], v16, s[60:61] nt
	v_or_b32_e32 v240, 28, v236
	v_lshlrev_b32_e32 v186, 12, v240
	v_mov_b32_e32 v187, 0
	v_add_u32_e32 v12, v186, v144
	global_load_dwordx4 v[12:15], v12, s[60:61] nt
	v_or_b32_e32 v240, 29, v236
	v_lshlrev_b32_e32 v190, 12, v240
	v_mov_b32_e32 v191, 0
	v_add_u32_e32 v8, v190, v144
	global_load_dwordx4 v[8:11], v8, s[60:61] nt
	v_or_b32_e32 v240, 30, v236
	v_lshlrev_b32_e32 v194, 12, v240
	v_mov_b32_e32 v195, 0
	v_add_u32_e32 v4, v194, v144
	global_load_dwordx4 v[4:7], v4, s[60:61] nt
	v_or_b32_e32 v240, 31, v236
	v_lshlrev_b32_e32 v198, 12, v240
	v_mov_b32_e32 v199, 0
	v_add_u32_e32 v0, v198, v144
	global_load_dwordx4 v[0:3], v0, s[60:61] nt
	s_waitcnt vmcnt(16)
	v_pk_add_f32 v[128:129], v[128:129], 0 op_sel_hi:[1,0]
	v_pk_add_f32 v[130:131], v[130:131], 0 op_sel_hi:[1,0]
	s_waitcnt vmcnt(15)
	v_pk_add_f32 v[128:129], v[128:129], v[132:133]
	v_pk_add_f32 v[130:131], v[130:131], v[134:135]
	s_waitcnt vmcnt(14)
	v_pk_add_f32 v[128:129], v[128:129], v[136:137]
	v_pk_add_f32 v[130:131], v[130:131], v[138:139]
	s_waitcnt vmcnt(13)
	v_pk_add_f32 v[128:129], v[128:129], v[140:141]
	v_pk_add_f32 v[130:131], v[130:131], v[142:143]
	v_mul_f32_e32 v138, 0x3d800000, v129
	v_mul_f32_e32 v135, 0x3d800000, v128
	v_mul_f32_e32 v134, 0x3d800000, v131
	s_add_u32 s66, s14, s28
	s_addc_u32 s67, s15, s29
	v_mul_f32_e32 v137, 0x3d800000, v130
	v_lshlrev_b32_e32 v128, 2, v215
	v_lshlrev_b32_e32 v129, 2, v217
	v_lshlrev_b32_e32 v130, 2, v218
	v_lshlrev_b32_e32 v131, 2, v219
	v_lshlrev_b32_e32 v132, 2, v220
	v_lshlrev_b32_e32 v133, 2, v221
	v_lshl_add_u32 v136, v210, 7, 16
	v_and_b32_e32 v139, 3, v223
	v_bfrev_b32_e32 v139, v139
	v_lshrrev_b32_e32 v139, 20, v139
	v_and_b32_e32 v235, -4, v223
	v_add3_u32 v235, v136, v139, v235
	v_mov_b32_e32 v236, v228
	v_mov_b32_e32 v237, v226
	v_mov_b32_e32 v238, v231
	v_mov_b32_e32 v239, v230
	v_mov_b32_e32 v240, v229
	v_mov_b32_e32 v241, v227
	v_mov_b32_e32 v242, v225
	v_mov_b32_e32 v243, v224
	v_mov_b32_e32 v244, v232
	v_mov_b32_e32 v245, v135
	v_mov_b32_e32 v246, v234
	v_mov_b32_e32 v247, v138
	v_mov_b32_e32 v248, v233
	v_mov_b32_e32 v249, v137
	v_mov_b32_e32 v250, v211
	v_mov_b32_e32 v251, v134
	s_mov_b32 vcc_lo, 0x55555555
	s_mov_b32 vcc_hi, 0x55555555
	s_mov_b32 s4, 0x33333333
	s_mov_b32 s5, 0x33333333
	s_mov_b32 s6, 0x0f0f0f0f
	s_mov_b32 s7, 0x0f0f0f0f
	s_mov_b32 s64, 0x00ff00ff
	s_mov_b32 s65, 0x00ff00ff
	s_waitcnt vmcnt(31)
; DI void attn_sample_item(const Params& p, int item, ldsp lds, int tid_) {
;     ...
;   SC_SCORE(kvA, 0)
;   SC_SCORE(kvB, 1)
	v_pk_mul_f32 v[252:253], v[236:237], v[124:125] op_sel_hi:[1,0]
	v_pk_mul_f32 v[254:255], v[244:245], v[124:125] op_sel_hi:[1,0]
	v_pk_fma_f32 v[252:253], v[238:239], v[124:125], v[252:253] op_sel:[0,1,0]
	v_pk_fma_f32 v[254:255], v[246:247], v[124:125], v[254:255] op_sel:[0,1,0]
	v_pk_fma_f32 v[252:253], v[240:241], v[126:127], v[252:253] op_sel_hi:[1,0,1]
	v_pk_fma_f32 v[254:255], v[248:249], v[126:127], v[254:255] op_sel_hi:[1,0,1]
	v_pk_fma_f32 v[252:253], v[242:243], v[126:127], v[252:253] op_sel:[0,1,0]
	v_pk_fma_f32 v[254:255], v[250:251], v[126:127], v[254:255] op_sel:[0,1,0]
	s_waitcnt vmcnt(30)
	v_pk_mul_f32 v[140:141], v[236:237], v[120:121] op_sel_hi:[1,0]
	v_pk_mul_f32 v[142:143], v[244:245], v[120:121] op_sel_hi:[1,0]
	v_pk_fma_f32 v[140:141], v[238:239], v[120:121], v[140:141] op_sel:[0,1,0]
	v_pk_fma_f32 v[142:143], v[246:247], v[120:121], v[142:143] op_sel:[0,1,0]
	v_pk_fma_f32 v[140:141], v[240:241], v[122:123], v[140:141] op_sel_hi:[1,0,1]
	v_pk_fma_f32 v[142:143], v[248:249], v[122:123], v[142:143] op_sel_hi:[1,0,1]
	v_pk_fma_f32 v[140:141], v[242:243], v[122:123], v[140:141] op_sel:[0,1,0]
	v_pk_fma_f32 v[142:143], v[250:251], v[122:123], v[142:143] op_sel:[0,1,0]
	v_add_f32_dpp v124, v252, v252 quad_perm:[1,0,3,2] row_mask:0xf bank_mask:0xf
	v_add_f32_dpp v125, v253, v253 quad_perm:[1,0,3,2] row_mask:0xf bank_mask:0xf
	v_add_f32_dpp v126, v254, v254 quad_perm:[1,0,3,2] row_mask:0xf bank_mask:0xf
	v_add_f32_dpp v127, v255, v255 quad_perm:[1,0,3,2] row_mask:0xf bank_mask:0xf
	v_cndmask_b32_e32 v124, v126, v124, vcc
	v_cndmask_b32_e32 v125, v127, v125, vcc
	s_waitcnt vmcnt(29)
	v_pk_mul_f32 v[252:253], v[236:237], v[116:117] op_sel_hi:[1,0]
	v_pk_mul_f32 v[254:255], v[244:245], v[116:117] op_sel_hi:[1,0]
	v_pk_fma_f32 v[252:253], v[238:239], v[116:117], v[252:253] op_sel:[0,1,0]
	v_pk_fma_f32 v[254:255], v[246:247], v[116:117], v[254:255] op_sel:[0,1,0]
	v_pk_fma_f32 v[252:253], v[240:241], v[118:119], v[252:253] op_sel_hi:[1,0,1]
	v_pk_fma_f32 v[254:255], v[248:249], v[118:119], v[254:255] op_sel_hi:[1,0,1]
	v_pk_fma_f32 v[252:253], v[242:243], v[118:119], v[252:253] op_sel:[0,1,0]
	v_pk_fma_f32 v[254:255], v[250:251], v[118:119], v[254:255] op_sel:[0,1,0]
	v_add_f32_dpp v120, v140, v140 quad_perm:[1,0,3,2] row_mask:0xf bank_mask:0xf
	v_add_f32_dpp v121, v141, v141 quad_perm:[1,0,3,2] row_mask:0xf bank_mask:0xf
	v_add_f32_dpp v122, v142, v142 quad_perm:[1,0,3,2] row_mask:0xf bank_mask:0xf
	v_add_f32_dpp v123, v143, v143 quad_perm:[1,0,3,2] row_mask:0xf bank_mask:0xf
	v_cndmask_b32_e32 v120, v122, v120, vcc
	v_cndmask_b32_e32 v121, v123, v121, vcc
	v_add_f32_dpp v126, v124, v124 quad_perm:[2,3,0,1] row_mask:0xf bank_mask:0xf
	v_add_f32_dpp v127, v125, v125 quad_perm:[2,3,0,1] row_mask:0xf bank_mask:0xf
	v_cndmask_b32_e64 v124, v127, v126, s[4:5]
	s_waitcnt vmcnt(28)
	v_pk_mul_f32 v[140:141], v[236:237], v[112:113] op_sel_hi:[1,0]
	v_pk_mul_f32 v[142:143], v[244:245], v[112:113] op_sel_hi:[1,0]
	v_pk_fma_f32 v[140:141], v[238:239], v[112:113], v[140:141] op_sel:[0,1,0]
	v_pk_fma_f32 v[142:143], v[246:247], v[112:113], v[142:143] op_sel:[0,1,0]
	v_pk_fma_f32 v[140:141], v[240:241], v[114:115], v[140:141] op_sel_hi:[1,0,1]
	v_pk_fma_f32 v[142:143], v[248:249], v[114:115], v[142:143] op_sel_hi:[1,0,1]
	v_pk_fma_f32 v[140:141], v[242:243], v[114:115], v[140:141] op_sel:[0,1,0]
	v_pk_fma_f32 v[142:143], v[250:251], v[114:115], v[142:143] op_sel:[0,1,0]
	v_add_f32_dpp v116, v252, v252 quad_perm:[1,0,3,2] row_mask:0xf bank_mask:0xf
	v_add_f32_dpp v117, v253, v253 quad_perm:[1,0,3,2] row_mask:0xf bank_mask:0xf
	v_add_f32_dpp v118, v254, v254 quad_perm:[1,0,3,2] row_mask:0xf bank_mask:0xf
	v_add_f32_dpp v119, v255, v255 quad_perm:[1,0,3,2] row_mask:0xf bank_mask:0xf
	v_cndmask_b32_e32 v116, v118, v116, vcc
	v_cndmask_b32_e32 v117, v119, v117, vcc
	v_add_f32_dpp v122, v120, v120 quad_perm:[2,3,0,1] row_mask:0xf bank_mask:0xf
	v_add_f32_dpp v123, v121, v121 quad_perm:[2,3,0,1] row_mask:0xf bank_mask:0xf
	v_cndmask_b32_e64 v120, v123, v122, s[4:5]
	v_cndmask_b32_e64 v125, v120, v124, s[6:7]
	v_cndmask_b32_e64 v126, v124, v120, s[6:7]
	s_waitcnt vmcnt(27)
	v_pk_mul_f32 v[252:253], v[236:237], v[108:109] op_sel_hi:[1,0]
	v_pk_mul_f32 v[254:255], v[244:245], v[108:109] op_sel_hi:[1,0]
	v_pk_fma_f32 v[252:253], v[238:239], v[108:109], v[252:253] op_sel:[0,1,0]
	v_pk_fma_f32 v[254:255], v[246:247], v[108:109], v[254:255] op_sel:[0,1,0]
	v_pk_fma_f32 v[252:253], v[240:241], v[110:111], v[252:253] op_sel_hi:[1,0,1]
	v_pk_fma_f32 v[254:255], v[248:249], v[110:111], v[254:255] op_sel_hi:[1,0,1]
	v_pk_fma_f32 v[252:253], v[242:243], v[110:111], v[252:253] op_sel:[0,1,0]
	v_pk_fma_f32 v[254:255], v[250:251], v[110:111], v[254:255] op_sel:[0,1,0]
	v_add_f32_dpp v124, v126, v125 row_ror:4 row_mask:0xf bank_mask:0xf
	v_add_f32_dpp v112, v140, v140 quad_perm:[1,0,3,2] row_mask:0xf bank_mask:0xf
	v_add_f32_dpp v113, v141, v141 quad_perm:[1,0,3,2] row_mask:0xf bank_mask:0xf
	v_add_f32_dpp v114, v142, v142 quad_perm:[1,0,3,2] row_mask:0xf bank_mask:0xf
	v_add_f32_dpp v115, v143, v143 quad_perm:[1,0,3,2] row_mask:0xf bank_mask:0xf
	v_cndmask_b32_e32 v112, v114, v112, vcc
	v_cndmask_b32_e32 v113, v115, v113, vcc
	v_add_f32_dpp v118, v116, v116 quad_perm:[2,3,0,1] row_mask:0xf bank_mask:0xf
	v_add_f32_dpp v119, v117, v117 quad_perm:[2,3,0,1] row_mask:0xf bank_mask:0xf
	v_cndmask_b32_e64 v116, v119, v118, s[4:5]
	s_waitcnt vmcnt(26)
; DI void attn_sample_item(const Params& p, int item, ldsp lds, int tid_) {
;     ...
;   SC_SCORE(kvA, 0)
;   SC_SCORE(kvB, 1)
	v_pk_mul_f32 v[140:141], v[236:237], v[104:105] op_sel_hi:[1,0]
	v_pk_mul_f32 v[142:143], v[244:245], v[104:105] op_sel_hi:[1,0]
	v_pk_fma_f32 v[140:141], v[238:239], v[104:105], v[140:141] op_sel:[0,1,0]
	v_pk_fma_f32 v[142:143], v[246:247], v[104:105], v[142:143] op_sel:[0,1,0]
	v_pk_fma_f32 v[140:141], v[240:241], v[106:107], v[140:141] op_sel_hi:[1,0,1]
	v_pk_fma_f32 v[142:143], v[248:249], v[106:107], v[142:143] op_sel_hi:[1,0,1]
	v_pk_fma_f32 v[140:141], v[242:243], v[106:107], v[140:141] op_sel:[0,1,0]
	v_pk_fma_f32 v[142:143], v[250:251], v[106:107], v[142:143] op_sel:[0,1,0]
	v_add_f32_dpp v108, v252, v252 quad_perm:[1,0,3,2] row_mask:0xf bank_mask:0xf
	v_add_f32_dpp v109, v253, v253 quad_perm:[1,0,3,2] row_mask:0xf bank_mask:0xf
	v_add_f32_dpp v110, v254, v254 quad_perm:[1,0,3,2] row_mask:0xf bank_mask:0xf
	v_add_f32_dpp v111, v255, v255 quad_perm:[1,0,3,2] row_mask:0xf bank_mask:0xf
	v_cndmask_b32_e32 v108, v110, v108, vcc
	v_cndmask_b32_e32 v109, v111, v109, vcc
	v_add_f32_dpp v114, v112, v112 quad_perm:[2,3,0,1] row_mask:0xf bank_mask:0xf
	v_add_f32_dpp v115, v113, v113 quad_perm:[2,3,0,1] row_mask:0xf bank_mask:0xf
	v_cndmask_b32_e64 v112, v115, v114, s[4:5]
	v_cndmask_b32_e64 v117, v112, v116, s[6:7]
	v_cndmask_b32_e64 v118, v116, v112, s[6:7]
	s_waitcnt vmcnt(25)
	v_pk_mul_f32 v[252:253], v[236:237], v[100:101] op_sel_hi:[1,0]
	v_pk_mul_f32 v[254:255], v[244:245], v[100:101] op_sel_hi:[1,0]
	v_pk_fma_f32 v[252:253], v[238:239], v[100:101], v[252:253] op_sel:[0,1,0]
	v_pk_fma_f32 v[254:255], v[246:247], v[100:101], v[254:255] op_sel:[0,1,0]
	v_pk_fma_f32 v[252:253], v[240:241], v[102:103], v[252:253] op_sel_hi:[1,0,1]
	v_pk_fma_f32 v[254:255], v[248:249], v[102:103], v[254:255] op_sel_hi:[1,0,1]
	v_pk_fma_f32 v[252:253], v[242:243], v[102:103], v[252:253] op_sel:[0,1,0]
	v_pk_fma_f32 v[254:255], v[250:251], v[102:103], v[254:255] op_sel:[0,1,0]
	v_add_f32_dpp v116, v118, v117 row_ror:4 row_mask:0xf bank_mask:0xf
	v_cndmask_b32_e64 v125, v116, v124, s[64:65]
	v_cndmask_b32_e64 v126, v124, v116, s[64:65]
	v_add_f32_dpp v104, v140, v140 quad_perm:[1,0,3,2] row_mask:0xf bank_mask:0xf
	v_add_f32_dpp v105, v141, v141 quad_perm:[1,0,3,2] row_mask:0xf bank_mask:0xf
	v_add_f32_dpp v106, v142, v142 quad_perm:[1,0,3,2] row_mask:0xf bank_mask:0xf
	v_add_f32_dpp v107, v143, v143 quad_perm:[1,0,3,2] row_mask:0xf bank_mask:0xf
	v_cndmask_b32_e32 v104, v106, v104, vcc
	v_cndmask_b32_e32 v105, v107, v105, vcc
	v_add_f32_dpp v110, v108, v108 quad_perm:[2,3,0,1] row_mask:0xf bank_mask:0xf
	v_add_f32_dpp v111, v109, v109 quad_perm:[2,3,0,1] row_mask:0xf bank_mask:0xf
	v_cndmask_b32_e64 v108, v111, v110, s[4:5]
	s_waitcnt vmcnt(24)
	v_pk_mul_f32 v[140:141], v[236:237], v[96:97] op_sel_hi:[1,0]
	v_pk_mul_f32 v[142:143], v[244:245], v[96:97] op_sel_hi:[1,0]
	v_pk_fma_f32 v[140:141], v[238:239], v[96:97], v[140:141] op_sel:[0,1,0]
	v_pk_fma_f32 v[142:143], v[246:247], v[96:97], v[142:143] op_sel:[0,1,0]
	v_pk_fma_f32 v[140:141], v[240:241], v[98:99], v[140:141] op_sel_hi:[1,0,1]
	v_pk_fma_f32 v[142:143], v[248:249], v[98:99], v[142:143] op_sel_hi:[1,0,1]
	v_pk_fma_f32 v[140:141], v[242:243], v[98:99], v[140:141] op_sel:[0,1,0]
	v_pk_fma_f32 v[142:143], v[250:251], v[98:99], v[142:143] op_sel:[0,1,0]
	v_add_f32_dpp v124, v126, v125 row_ror:8 row_mask:0xf bank_mask:0xf
	v_add_f32_dpp v100, v252, v252 quad_perm:[1,0,3,2] row_mask:0xf bank_mask:0xf
	v_add_f32_dpp v101, v253, v253 quad_perm:[1,0,3,2] row_mask:0xf bank_mask:0xf
	v_add_f32_dpp v102, v254, v254 quad_perm:[1,0,3,2] row_mask:0xf bank_mask:0xf
	v_add_f32_dpp v103, v255, v255 quad_perm:[1,0,3,2] row_mask:0xf bank_mask:0xf
	v_cndmask_b32_e32 v100, v102, v100, vcc
	v_cndmask_b32_e32 v101, v103, v101, vcc
	v_add_f32_dpp v106, v104, v104 quad_perm:[2,3,0,1] row_mask:0xf bank_mask:0xf
	v_add_f32_dpp v107, v105, v105 quad_perm:[2,3,0,1] row_mask:0xf bank_mask:0xf
	v_cndmask_b32_e64 v104, v107, v106, s[4:5]
	v_cndmask_b32_e64 v109, v104, v108, s[6:7]
	v_cndmask_b32_e64 v110, v108, v104, s[6:7]
	s_waitcnt vmcnt(23)
	v_pk_mul_f32 v[252:253], v[236:237], v[92:93] op_sel_hi:[1,0]
	v_pk_mul_f32 v[254:255], v[244:245], v[92:93] op_sel_hi:[1,0]
	v_pk_fma_f32 v[252:253], v[238:239], v[92:93], v[252:253] op_sel:[0,1,0]
	v_pk_fma_f32 v[254:255], v[246:247], v[92:93], v[254:255] op_sel:[0,1,0]
	v_pk_fma_f32 v[252:253], v[240:241], v[94:95], v[252:253] op_sel_hi:[1,0,1]
	v_pk_fma_f32 v[254:255], v[248:249], v[94:95], v[254:255] op_sel_hi:[1,0,1]
	v_pk_fma_f32 v[252:253], v[242:243], v[94:95], v[252:253] op_sel:[0,1,0]
	v_pk_fma_f32 v[254:255], v[250:251], v[94:95], v[254:255] op_sel:[0,1,0]
	v_add_f32_dpp v108, v110, v109 row_ror:4 row_mask:0xf bank_mask:0xf
	v_add_f32_dpp v96, v140, v140 quad_perm:[1,0,3,2] row_mask:0xf bank_mask:0xf
	v_add_f32_dpp v97, v141, v141 quad_perm:[1,0,3,2] row_mask:0xf bank_mask:0xf
	v_add_f32_dpp v98, v142, v142 quad_perm:[1,0,3,2] row_mask:0xf bank_mask:0xf
	v_add_f32_dpp v99, v143, v143 quad_perm:[1,0,3,2] row_mask:0xf bank_mask:0xf
	v_cndmask_b32_e32 v96, v98, v96, vcc
	v_cndmask_b32_e32 v97, v99, v97, vcc
	v_add_f32_dpp v102, v100, v100 quad_perm:[2,3,0,1] row_mask:0xf bank_mask:0xf
	v_add_f32_dpp v103, v101, v101 quad_perm:[2,3,0,1] row_mask:0xf bank_mask:0xf
	v_cndmask_b32_e64 v100, v103, v102, s[4:5]
	s_waitcnt vmcnt(22)
; DI void attn_sample_item(const Params& p, int item, ldsp lds, int tid_) {
;     ...
;   SC_SCORE(kvA, 0)
;   SC_SCORE(kvB, 1)
	v_pk_mul_f32 v[140:141], v[236:237], v[88:89] op_sel_hi:[1,0]
	v_pk_mul_f32 v[142:143], v[244:245], v[88:89] op_sel_hi:[1,0]
	v_pk_fma_f32 v[140:141], v[238:239], v[88:89], v[140:141] op_sel:[0,1,0]
	v_pk_fma_f32 v[142:143], v[246:247], v[88:89], v[142:143] op_sel:[0,1,0]
	v_pk_fma_f32 v[140:141], v[240:241], v[90:91], v[140:141] op_sel_hi:[1,0,1]
	v_pk_fma_f32 v[142:143], v[248:249], v[90:91], v[142:143] op_sel_hi:[1,0,1]
	v_pk_fma_f32 v[140:141], v[242:243], v[90:91], v[140:141] op_sel:[0,1,0]
	v_pk_fma_f32 v[142:143], v[250:251], v[90:91], v[142:143] op_sel:[0,1,0]
	v_add_f32_dpp v92, v252, v252 quad_perm:[1,0,3,2] row_mask:0xf bank_mask:0xf
	v_add_f32_dpp v93, v253, v253 quad_perm:[1,0,3,2] row_mask:0xf bank_mask:0xf
	v_add_f32_dpp v94, v254, v254 quad_perm:[1,0,3,2] row_mask:0xf bank_mask:0xf
	v_add_f32_dpp v95, v255, v255 quad_perm:[1,0,3,2] row_mask:0xf bank_mask:0xf
	v_cndmask_b32_e32 v92, v94, v92, vcc
	v_cndmask_b32_e32 v93, v95, v93, vcc
	v_add_f32_dpp v98, v96, v96 quad_perm:[2,3,0,1] row_mask:0xf bank_mask:0xf
	v_add_f32_dpp v99, v97, v97 quad_perm:[2,3,0,1] row_mask:0xf bank_mask:0xf
	v_cndmask_b32_e64 v96, v99, v98, s[4:5]
	v_cndmask_b32_e64 v101, v96, v100, s[6:7]
	v_cndmask_b32_e64 v102, v100, v96, s[6:7]
	s_waitcnt vmcnt(21)
	v_pk_mul_f32 v[252:253], v[236:237], v[84:85] op_sel_hi:[1,0]
	v_pk_mul_f32 v[254:255], v[244:245], v[84:85] op_sel_hi:[1,0]
	v_pk_fma_f32 v[252:253], v[238:239], v[84:85], v[252:253] op_sel:[0,1,0]
	v_pk_fma_f32 v[254:255], v[246:247], v[84:85], v[254:255] op_sel:[0,1,0]
	v_pk_fma_f32 v[252:253], v[240:241], v[86:87], v[252:253] op_sel_hi:[1,0,1]
	v_pk_fma_f32 v[254:255], v[248:249], v[86:87], v[254:255] op_sel_hi:[1,0,1]
	v_pk_fma_f32 v[252:253], v[242:243], v[86:87], v[252:253] op_sel:[0,1,0]
	v_pk_fma_f32 v[254:255], v[250:251], v[86:87], v[254:255] op_sel:[0,1,0]
	v_add_f32_dpp v100, v102, v101 row_ror:4 row_mask:0xf bank_mask:0xf
	v_cndmask_b32_e64 v109, v100, v108, s[64:65]
	v_cndmask_b32_e64 v110, v108, v100, s[64:65]
	v_add_f32_dpp v88, v140, v140 quad_perm:[1,0,3,2] row_mask:0xf bank_mask:0xf
	v_add_f32_dpp v89, v141, v141 quad_perm:[1,0,3,2] row_mask:0xf bank_mask:0xf
	v_add_f32_dpp v90, v142, v142 quad_perm:[1,0,3,2] row_mask:0xf bank_mask:0xf
	v_add_f32_dpp v91, v143, v143 quad_perm:[1,0,3,2] row_mask:0xf bank_mask:0xf
	v_cndmask_b32_e32 v88, v90, v88, vcc
	v_cndmask_b32_e32 v89, v91, v89, vcc
	v_add_f32_dpp v94, v92, v92 quad_perm:[2,3,0,1] row_mask:0xf bank_mask:0xf
	v_add_f32_dpp v95, v93, v93 quad_perm:[2,3,0,1] row_mask:0xf bank_mask:0xf
	v_cndmask_b32_e64 v92, v95, v94, s[4:5]
	s_waitcnt vmcnt(20)
	v_pk_mul_f32 v[140:141], v[236:237], v[80:81] op_sel_hi:[1,0]
	v_pk_mul_f32 v[142:143], v[244:245], v[80:81] op_sel_hi:[1,0]
	v_pk_fma_f32 v[140:141], v[238:239], v[80:81], v[140:141] op_sel:[0,1,0]
	v_pk_fma_f32 v[142:143], v[246:247], v[80:81], v[142:143] op_sel:[0,1,0]
	v_pk_fma_f32 v[140:141], v[240:241], v[82:83], v[140:141] op_sel_hi:[1,0,1]
	v_pk_fma_f32 v[142:143], v[248:249], v[82:83], v[142:143] op_sel_hi:[1,0,1]
	v_pk_fma_f32 v[140:141], v[242:243], v[82:83], v[140:141] op_sel:[0,1,0]
	v_pk_fma_f32 v[142:143], v[250:251], v[82:83], v[142:143] op_sel:[0,1,0]
	v_add_f32_dpp v108, v110, v109 row_ror:8 row_mask:0xf bank_mask:0xf
	v_add_f32_dpp v84, v252, v252 quad_perm:[1,0,3,2] row_mask:0xf bank_mask:0xf
	v_add_f32_dpp v85, v253, v253 quad_perm:[1,0,3,2] row_mask:0xf bank_mask:0xf
	v_add_f32_dpp v86, v254, v254 quad_perm:[1,0,3,2] row_mask:0xf bank_mask:0xf
	v_add_f32_dpp v87, v255, v255 quad_perm:[1,0,3,2] row_mask:0xf bank_mask:0xf
	v_cndmask_b32_e32 v84, v86, v84, vcc
	v_cndmask_b32_e32 v85, v87, v85, vcc
	v_add_f32_dpp v90, v88, v88 quad_perm:[2,3,0,1] row_mask:0xf bank_mask:0xf
	v_add_f32_dpp v91, v89, v89 quad_perm:[2,3,0,1] row_mask:0xf bank_mask:0xf
	v_cndmask_b32_e64 v88, v91, v90, s[4:5]
	v_cndmask_b32_e64 v93, v88, v92, s[6:7]
	v_cndmask_b32_e64 v94, v92, v88, s[6:7]
	s_waitcnt vmcnt(19)
	v_pk_mul_f32 v[252:253], v[236:237], v[76:77] op_sel_hi:[1,0]
	v_pk_mul_f32 v[254:255], v[244:245], v[76:77] op_sel_hi:[1,0]
	v_pk_fma_f32 v[252:253], v[238:239], v[76:77], v[252:253] op_sel:[0,1,0]
	v_pk_fma_f32 v[254:255], v[246:247], v[76:77], v[254:255] op_sel:[0,1,0]
	v_pk_fma_f32 v[252:253], v[240:241], v[78:79], v[252:253] op_sel_hi:[1,0,1]
	v_pk_fma_f32 v[254:255], v[248:249], v[78:79], v[254:255] op_sel_hi:[1,0,1]
	v_pk_fma_f32 v[252:253], v[242:243], v[78:79], v[252:253] op_sel:[0,1,0]
	v_pk_fma_f32 v[254:255], v[250:251], v[78:79], v[254:255] op_sel:[0,1,0]
	v_permlane16_swap_b32_e32 v124, v108
	v_add_f32_e32 v124, v124, v108
	v_add_f32_dpp v92, v94, v93 row_ror:4 row_mask:0xf bank_mask:0xf
	v_add_f32_dpp v80, v140, v140 quad_perm:[1,0,3,2] row_mask:0xf bank_mask:0xf
	v_add_f32_dpp v81, v141, v141 quad_perm:[1,0,3,2] row_mask:0xf bank_mask:0xf
	v_add_f32_dpp v82, v142, v142 quad_perm:[1,0,3,2] row_mask:0xf bank_mask:0xf
	v_add_f32_dpp v83, v143, v143 quad_perm:[1,0,3,2] row_mask:0xf bank_mask:0xf
	v_cndmask_b32_e32 v80, v82, v80, vcc
	v_cndmask_b32_e32 v81, v83, v81, vcc
	v_add_f32_dpp v86, v84, v84 quad_perm:[2,3,0,1] row_mask:0xf bank_mask:0xf
	v_add_f32_dpp v87, v85, v85 quad_perm:[2,3,0,1] row_mask:0xf bank_mask:0xf
	v_cndmask_b32_e64 v84, v87, v86, s[4:5]
	s_waitcnt vmcnt(18)
; DI void attn_sample_item(const Params& p, int item, ldsp lds, int tid_) {
;     ...
;   SC_SCORE(kvA, 0)
;   SC_SCORE(kvB, 1)
	v_pk_mul_f32 v[140:141], v[236:237], v[72:73] op_sel_hi:[1,0]
	v_pk_mul_f32 v[142:143], v[244:245], v[72:73] op_sel_hi:[1,0]
	v_pk_fma_f32 v[140:141], v[238:239], v[72:73], v[140:141] op_sel:[0,1,0]
	v_pk_fma_f32 v[142:143], v[246:247], v[72:73], v[142:143] op_sel:[0,1,0]
	v_pk_fma_f32 v[140:141], v[240:241], v[74:75], v[140:141] op_sel_hi:[1,0,1]
	v_pk_fma_f32 v[142:143], v[248:249], v[74:75], v[142:143] op_sel_hi:[1,0,1]
	v_pk_fma_f32 v[140:141], v[242:243], v[74:75], v[140:141] op_sel:[0,1,0]
	v_pk_fma_f32 v[142:143], v[250:251], v[74:75], v[142:143] op_sel:[0,1,0]
	v_add_f32_dpp v76, v252, v252 quad_perm:[1,0,3,2] row_mask:0xf bank_mask:0xf
	v_add_f32_dpp v77, v253, v253 quad_perm:[1,0,3,2] row_mask:0xf bank_mask:0xf
	v_add_f32_dpp v78, v254, v254 quad_perm:[1,0,3,2] row_mask:0xf bank_mask:0xf
	v_add_f32_dpp v79, v255, v255 quad_perm:[1,0,3,2] row_mask:0xf bank_mask:0xf
	v_cndmask_b32_e32 v76, v78, v76, vcc
	v_cndmask_b32_e32 v77, v79, v77, vcc
	v_add_f32_dpp v82, v80, v80 quad_perm:[2,3,0,1] row_mask:0xf bank_mask:0xf
	v_add_f32_dpp v83, v81, v81 quad_perm:[2,3,0,1] row_mask:0xf bank_mask:0xf
	v_cndmask_b32_e64 v80, v83, v82, s[4:5]
	v_cndmask_b32_e64 v85, v80, v84, s[6:7]
	v_cndmask_b32_e64 v86, v84, v80, s[6:7]
	s_waitcnt vmcnt(17)
	v_pk_mul_f32 v[252:253], v[236:237], v[68:69] op_sel_hi:[1,0]
	v_pk_mul_f32 v[254:255], v[244:245], v[68:69] op_sel_hi:[1,0]
	v_pk_fma_f32 v[252:253], v[238:239], v[68:69], v[252:253] op_sel:[0,1,0]
	v_pk_fma_f32 v[254:255], v[246:247], v[68:69], v[254:255] op_sel:[0,1,0]
	v_pk_fma_f32 v[252:253], v[240:241], v[70:71], v[252:253] op_sel_hi:[1,0,1]
	v_pk_fma_f32 v[254:255], v[248:249], v[70:71], v[254:255] op_sel_hi:[1,0,1]
	v_pk_fma_f32 v[252:253], v[242:243], v[70:71], v[252:253] op_sel:[0,1,0]
	v_pk_fma_f32 v[254:255], v[250:251], v[70:71], v[254:255] op_sel:[0,1,0]
	v_add_f32_dpp v84, v86, v85 row_ror:4 row_mask:0xf bank_mask:0xf
	v_cndmask_b32_e64 v93, v84, v92, s[64:65]
	v_cndmask_b32_e64 v94, v92, v84, s[64:65]
	v_add_f32_dpp v72, v140, v140 quad_perm:[1,0,3,2] row_mask:0xf bank_mask:0xf
	v_add_f32_dpp v73, v141, v141 quad_perm:[1,0,3,2] row_mask:0xf bank_mask:0xf
	v_add_f32_dpp v74, v142, v142 quad_perm:[1,0,3,2] row_mask:0xf bank_mask:0xf
	v_add_f32_dpp v75, v143, v143 quad_perm:[1,0,3,2] row_mask:0xf bank_mask:0xf
	v_cndmask_b32_e32 v72, v74, v72, vcc
	v_cndmask_b32_e32 v73, v75, v73, vcc
	v_add_f32_dpp v78, v76, v76 quad_perm:[2,3,0,1] row_mask:0xf bank_mask:0xf
	v_add_f32_dpp v79, v77, v77 quad_perm:[2,3,0,1] row_mask:0xf bank_mask:0xf
	v_cndmask_b32_e64 v76, v79, v78, s[4:5]
	s_waitcnt vmcnt(16)
	v_pk_mul_f32 v[140:141], v[236:237], v[64:65] op_sel_hi:[1,0]
	v_pk_mul_f32 v[142:143], v[244:245], v[64:65] op_sel_hi:[1,0]
	v_pk_fma_f32 v[140:141], v[238:239], v[64:65], v[140:141] op_sel:[0,1,0]
	v_pk_fma_f32 v[142:143], v[246:247], v[64:65], v[142:143] op_sel:[0,1,0]
	v_pk_fma_f32 v[140:141], v[240:241], v[66:67], v[140:141] op_sel_hi:[1,0,1]
	v_pk_fma_f32 v[142:143], v[248:249], v[66:67], v[142:143] op_sel_hi:[1,0,1]
	v_pk_fma_f32 v[140:141], v[242:243], v[66:67], v[140:141] op_sel:[0,1,0]
	v_pk_fma_f32 v[142:143], v[250:251], v[66:67], v[142:143] op_sel:[0,1,0]
	v_add_f32_dpp v92, v94, v93 row_ror:8 row_mask:0xf bank_mask:0xf
	v_add_f32_dpp v68, v252, v252 quad_perm:[1,0,3,2] row_mask:0xf bank_mask:0xf
	v_add_f32_dpp v69, v253, v253 quad_perm:[1,0,3,2] row_mask:0xf bank_mask:0xf
	v_add_f32_dpp v70, v254, v254 quad_perm:[1,0,3,2] row_mask:0xf bank_mask:0xf
	v_add_f32_dpp v71, v255, v255 quad_perm:[1,0,3,2] row_mask:0xf bank_mask:0xf
	v_cndmask_b32_e32 v68, v70, v68, vcc
	v_cndmask_b32_e32 v69, v71, v69, vcc
	v_add_f32_dpp v74, v72, v72 quad_perm:[2,3,0,1] row_mask:0xf bank_mask:0xf
	v_add_f32_dpp v75, v73, v73 quad_perm:[2,3,0,1] row_mask:0xf bank_mask:0xf
	v_cndmask_b32_e64 v72, v75, v74, s[4:5]
	v_cndmask_b32_e64 v77, v72, v76, s[6:7]
	v_cndmask_b32_e64 v78, v76, v72, s[6:7]
	s_waitcnt vmcnt(15)
	v_pk_mul_f32 v[252:253], v[236:237], v[60:61] op_sel_hi:[1,0]
	v_pk_mul_f32 v[254:255], v[244:245], v[60:61] op_sel_hi:[1,0]
	v_pk_fma_f32 v[252:253], v[238:239], v[60:61], v[252:253] op_sel:[0,1,0]
	v_pk_fma_f32 v[254:255], v[246:247], v[60:61], v[254:255] op_sel:[0,1,0]
	v_pk_fma_f32 v[252:253], v[240:241], v[62:63], v[252:253] op_sel_hi:[1,0,1]
	v_pk_fma_f32 v[254:255], v[248:249], v[62:63], v[254:255] op_sel_hi:[1,0,1]
	v_pk_fma_f32 v[252:253], v[242:243], v[62:63], v[252:253] op_sel:[0,1,0]
	v_pk_fma_f32 v[254:255], v[250:251], v[62:63], v[254:255] op_sel:[0,1,0]
	v_add_f32_dpp v76, v78, v77 row_ror:4 row_mask:0xf bank_mask:0xf
	v_add_f32_dpp v64, v140, v140 quad_perm:[1,0,3,2] row_mask:0xf bank_mask:0xf
	v_add_f32_dpp v65, v141, v141 quad_perm:[1,0,3,2] row_mask:0xf bank_mask:0xf
	v_add_f32_dpp v66, v142, v142 quad_perm:[1,0,3,2] row_mask:0xf bank_mask:0xf
	v_add_f32_dpp v67, v143, v143 quad_perm:[1,0,3,2] row_mask:0xf bank_mask:0xf
	v_cndmask_b32_e32 v64, v66, v64, vcc
	v_cndmask_b32_e32 v65, v67, v65, vcc
	v_add_f32_dpp v70, v68, v68 quad_perm:[2,3,0,1] row_mask:0xf bank_mask:0xf
	v_add_f32_dpp v71, v69, v69 quad_perm:[2,3,0,1] row_mask:0xf bank_mask:0xf
	v_cndmask_b32_e64 v68, v71, v70, s[4:5]
	s_waitcnt vmcnt(14)
; DI void attn_sample_item(const Params& p, int item, ldsp lds, int tid_) {
;     ...
;   SC_SCORE(kvA, 0)
;   SC_SCORE(kvB, 1)
	v_pk_mul_f32 v[140:141], v[236:237], v[56:57] op_sel_hi:[1,0]
	v_pk_mul_f32 v[142:143], v[244:245], v[56:57] op_sel_hi:[1,0]
	v_pk_fma_f32 v[140:141], v[238:239], v[56:57], v[140:141] op_sel:[0,1,0]
	v_pk_fma_f32 v[142:143], v[246:247], v[56:57], v[142:143] op_sel:[0,1,0]
	v_pk_fma_f32 v[140:141], v[240:241], v[58:59], v[140:141] op_sel_hi:[1,0,1]
	v_pk_fma_f32 v[142:143], v[248:249], v[58:59], v[142:143] op_sel_hi:[1,0,1]
	v_pk_fma_f32 v[140:141], v[242:243], v[58:59], v[140:141] op_sel:[0,1,0]
	v_pk_fma_f32 v[142:143], v[250:251], v[58:59], v[142:143] op_sel:[0,1,0]
	v_add_f32_dpp v60, v252, v252 quad_perm:[1,0,3,2] row_mask:0xf bank_mask:0xf
	v_add_f32_dpp v61, v253, v253 quad_perm:[1,0,3,2] row_mask:0xf bank_mask:0xf
	v_add_f32_dpp v62, v254, v254 quad_perm:[1,0,3,2] row_mask:0xf bank_mask:0xf
	v_add_f32_dpp v63, v255, v255 quad_perm:[1,0,3,2] row_mask:0xf bank_mask:0xf
	v_cndmask_b32_e32 v60, v62, v60, vcc
	v_cndmask_b32_e32 v61, v63, v61, vcc
	v_add_f32_dpp v66, v64, v64 quad_perm:[2,3,0,1] row_mask:0xf bank_mask:0xf
	v_add_f32_dpp v67, v65, v65 quad_perm:[2,3,0,1] row_mask:0xf bank_mask:0xf
	v_cndmask_b32_e64 v64, v67, v66, s[4:5]
	v_cndmask_b32_e64 v69, v64, v68, s[6:7]
	v_cndmask_b32_e64 v70, v68, v64, s[6:7]
	s_waitcnt vmcnt(13)
	v_pk_mul_f32 v[252:253], v[236:237], v[52:53] op_sel_hi:[1,0]
	v_pk_mul_f32 v[254:255], v[244:245], v[52:53] op_sel_hi:[1,0]
	v_pk_fma_f32 v[252:253], v[238:239], v[52:53], v[252:253] op_sel:[0,1,0]
	v_pk_fma_f32 v[254:255], v[246:247], v[52:53], v[254:255] op_sel:[0,1,0]
	v_pk_fma_f32 v[252:253], v[240:241], v[54:55], v[252:253] op_sel_hi:[1,0,1]
	v_pk_fma_f32 v[254:255], v[248:249], v[54:55], v[254:255] op_sel_hi:[1,0,1]
	v_pk_fma_f32 v[252:253], v[242:243], v[54:55], v[252:253] op_sel:[0,1,0]
	v_pk_fma_f32 v[254:255], v[250:251], v[54:55], v[254:255] op_sel:[0,1,0]
	v_add_f32_dpp v68, v70, v69 row_ror:4 row_mask:0xf bank_mask:0xf
	v_cndmask_b32_e64 v77, v68, v76, s[64:65]
	v_cndmask_b32_e64 v78, v76, v68, s[64:65]
	v_add_f32_dpp v56, v140, v140 quad_perm:[1,0,3,2] row_mask:0xf bank_mask:0xf
	v_add_f32_dpp v57, v141, v141 quad_perm:[1,0,3,2] row_mask:0xf bank_mask:0xf
	v_add_f32_dpp v58, v142, v142 quad_perm:[1,0,3,2] row_mask:0xf bank_mask:0xf
	v_add_f32_dpp v59, v143, v143 quad_perm:[1,0,3,2] row_mask:0xf bank_mask:0xf
	v_cndmask_b32_e32 v56, v58, v56, vcc
	v_cndmask_b32_e32 v57, v59, v57, vcc
	v_add_f32_dpp v62, v60, v60 quad_perm:[2,3,0,1] row_mask:0xf bank_mask:0xf
	v_add_f32_dpp v63, v61, v61 quad_perm:[2,3,0,1] row_mask:0xf bank_mask:0xf
	v_cndmask_b32_e64 v60, v63, v62, s[4:5]
	s_waitcnt vmcnt(12)
	v_pk_mul_f32 v[140:141], v[236:237], v[48:49] op_sel_hi:[1,0]
	v_pk_mul_f32 v[142:143], v[244:245], v[48:49] op_sel_hi:[1,0]
	v_pk_fma_f32 v[140:141], v[238:239], v[48:49], v[140:141] op_sel:[0,1,0]
	v_pk_fma_f32 v[142:143], v[246:247], v[48:49], v[142:143] op_sel:[0,1,0]
	v_pk_fma_f32 v[140:141], v[240:241], v[50:51], v[140:141] op_sel_hi:[1,0,1]
	v_pk_fma_f32 v[142:143], v[248:249], v[50:51], v[142:143] op_sel_hi:[1,0,1]
	v_pk_fma_f32 v[140:141], v[242:243], v[50:51], v[140:141] op_sel:[0,1,0]
	v_pk_fma_f32 v[142:143], v[250:251], v[50:51], v[142:143] op_sel:[0,1,0]
	v_add_f32_dpp v76, v78, v77 row_ror:8 row_mask:0xf bank_mask:0xf
	v_add_f32_dpp v52, v252, v252 quad_perm:[1,0,3,2] row_mask:0xf bank_mask:0xf
	v_add_f32_dpp v53, v253, v253 quad_perm:[1,0,3,2] row_mask:0xf bank_mask:0xf
	v_add_f32_dpp v54, v254, v254 quad_perm:[1,0,3,2] row_mask:0xf bank_mask:0xf
	v_add_f32_dpp v55, v255, v255 quad_perm:[1,0,3,2] row_mask:0xf bank_mask:0xf
	v_cndmask_b32_e32 v52, v54, v52, vcc
	v_cndmask_b32_e32 v53, v55, v53, vcc
	v_add_f32_dpp v58, v56, v56 quad_perm:[2,3,0,1] row_mask:0xf bank_mask:0xf
	v_add_f32_dpp v59, v57, v57 quad_perm:[2,3,0,1] row_mask:0xf bank_mask:0xf
	v_cndmask_b32_e64 v56, v59, v58, s[4:5]
	v_cndmask_b32_e64 v61, v56, v60, s[6:7]
	v_cndmask_b32_e64 v62, v60, v56, s[6:7]
	s_waitcnt vmcnt(11)
	v_pk_mul_f32 v[252:253], v[236:237], v[44:45] op_sel_hi:[1,0]
	v_pk_mul_f32 v[254:255], v[244:245], v[44:45] op_sel_hi:[1,0]
	v_pk_fma_f32 v[252:253], v[238:239], v[44:45], v[252:253] op_sel:[0,1,0]
	v_pk_fma_f32 v[254:255], v[246:247], v[44:45], v[254:255] op_sel:[0,1,0]
	v_pk_fma_f32 v[252:253], v[240:241], v[46:47], v[252:253] op_sel_hi:[1,0,1]
	v_pk_fma_f32 v[254:255], v[248:249], v[46:47], v[254:255] op_sel_hi:[1,0,1]
	v_pk_fma_f32 v[252:253], v[242:243], v[46:47], v[252:253] op_sel:[0,1,0]
	v_pk_fma_f32 v[254:255], v[250:251], v[46:47], v[254:255] op_sel:[0,1,0]
	v_permlane16_swap_b32_e32 v92, v76
	v_add_f32_e32 v92, v92, v76
	v_add_f32_dpp v60, v62, v61 row_ror:4 row_mask:0xf bank_mask:0xf
	v_add_f32_dpp v48, v140, v140 quad_perm:[1,0,3,2] row_mask:0xf bank_mask:0xf
	v_add_f32_dpp v49, v141, v141 quad_perm:[1,0,3,2] row_mask:0xf bank_mask:0xf
	v_add_f32_dpp v50, v142, v142 quad_perm:[1,0,3,2] row_mask:0xf bank_mask:0xf
	v_add_f32_dpp v51, v143, v143 quad_perm:[1,0,3,2] row_mask:0xf bank_mask:0xf
	v_cndmask_b32_e32 v48, v50, v48, vcc
	v_cndmask_b32_e32 v49, v51, v49, vcc
	v_add_f32_dpp v54, v52, v52 quad_perm:[2,3,0,1] row_mask:0xf bank_mask:0xf
	v_add_f32_dpp v55, v53, v53 quad_perm:[2,3,0,1] row_mask:0xf bank_mask:0xf
	v_cndmask_b32_e64 v52, v55, v54, s[4:5]
	s_waitcnt vmcnt(10)
; DI void attn_sample_item(const Params& p, int item, ldsp lds, int tid_) {
;     ...
;   SC_SCORE(kvA, 0)
;   SC_SCORE(kvB, 1)
	v_pk_mul_f32 v[140:141], v[236:237], v[40:41] op_sel_hi:[1,0]
	v_pk_mul_f32 v[142:143], v[244:245], v[40:41] op_sel_hi:[1,0]
	v_pk_fma_f32 v[140:141], v[238:239], v[40:41], v[140:141] op_sel:[0,1,0]
	v_pk_fma_f32 v[142:143], v[246:247], v[40:41], v[142:143] op_sel:[0,1,0]
	v_pk_fma_f32 v[140:141], v[240:241], v[42:43], v[140:141] op_sel_hi:[1,0,1]
	v_pk_fma_f32 v[142:143], v[248:249], v[42:43], v[142:143] op_sel_hi:[1,0,1]
	v_pk_fma_f32 v[140:141], v[242:243], v[42:43], v[140:141] op_sel:[0,1,0]
	v_pk_fma_f32 v[142:143], v[250:251], v[42:43], v[142:143] op_sel:[0,1,0]
	v_permlane32_swap_b32_e32 v124, v92
	v_add_f32_e32 v124, v124, v92
	ds_write_b32 v235, v124
	v_add_f32_dpp v44, v252, v252 quad_perm:[1,0,3,2] row_mask:0xf bank_mask:0xf
	v_add_f32_dpp v45, v253, v253 quad_perm:[1,0,3,2] row_mask:0xf bank_mask:0xf
	v_add_f32_dpp v46, v254, v254 quad_perm:[1,0,3,2] row_mask:0xf bank_mask:0xf
	v_add_f32_dpp v47, v255, v255 quad_perm:[1,0,3,2] row_mask:0xf bank_mask:0xf
	v_cndmask_b32_e32 v44, v46, v44, vcc
	v_cndmask_b32_e32 v45, v47, v45, vcc
	v_add_f32_dpp v50, v48, v48 quad_perm:[2,3,0,1] row_mask:0xf bank_mask:0xf
	v_add_f32_dpp v51, v49, v49 quad_perm:[2,3,0,1] row_mask:0xf bank_mask:0xf
	v_cndmask_b32_e64 v48, v51, v50, s[4:5]
	v_cndmask_b32_e64 v53, v48, v52, s[6:7]
	v_cndmask_b32_e64 v54, v52, v48, s[6:7]
	s_waitcnt vmcnt(9)
	v_pk_mul_f32 v[252:253], v[236:237], v[36:37] op_sel_hi:[1,0]
	v_pk_mul_f32 v[254:255], v[244:245], v[36:37] op_sel_hi:[1,0]
	v_pk_fma_f32 v[252:253], v[238:239], v[36:37], v[252:253] op_sel:[0,1,0]
	v_pk_fma_f32 v[254:255], v[246:247], v[36:37], v[254:255] op_sel:[0,1,0]
	v_pk_fma_f32 v[252:253], v[240:241], v[38:39], v[252:253] op_sel_hi:[1,0,1]
	v_pk_fma_f32 v[254:255], v[248:249], v[38:39], v[254:255] op_sel_hi:[1,0,1]
	v_pk_fma_f32 v[252:253], v[242:243], v[38:39], v[252:253] op_sel:[0,1,0]
	v_pk_fma_f32 v[254:255], v[250:251], v[38:39], v[254:255] op_sel:[0,1,0]
	v_add_f32_dpp v52, v54, v53 row_ror:4 row_mask:0xf bank_mask:0xf
	v_cndmask_b32_e64 v61, v52, v60, s[64:65]
	v_cndmask_b32_e64 v62, v60, v52, s[64:65]
	v_add_f32_dpp v40, v140, v140 quad_perm:[1,0,3,2] row_mask:0xf bank_mask:0xf
	v_add_f32_dpp v41, v141, v141 quad_perm:[1,0,3,2] row_mask:0xf bank_mask:0xf
	v_add_f32_dpp v42, v142, v142 quad_perm:[1,0,3,2] row_mask:0xf bank_mask:0xf
	v_add_f32_dpp v43, v143, v143 quad_perm:[1,0,3,2] row_mask:0xf bank_mask:0xf
	v_cndmask_b32_e32 v40, v42, v40, vcc
	v_cndmask_b32_e32 v41, v43, v41, vcc
	v_add_f32_dpp v46, v44, v44 quad_perm:[2,3,0,1] row_mask:0xf bank_mask:0xf
	v_add_f32_dpp v47, v45, v45 quad_perm:[2,3,0,1] row_mask:0xf bank_mask:0xf
	v_cndmask_b32_e64 v44, v47, v46, s[4:5]
	s_waitcnt vmcnt(8)
	v_pk_mul_f32 v[140:141], v[236:237], v[32:33] op_sel_hi:[1,0]
	v_pk_mul_f32 v[142:143], v[244:245], v[32:33] op_sel_hi:[1,0]
	v_pk_fma_f32 v[140:141], v[238:239], v[32:33], v[140:141] op_sel:[0,1,0]
	v_pk_fma_f32 v[142:143], v[246:247], v[32:33], v[142:143] op_sel:[0,1,0]
	v_pk_fma_f32 v[140:141], v[240:241], v[34:35], v[140:141] op_sel_hi:[1,0,1]
	v_pk_fma_f32 v[142:143], v[248:249], v[34:35], v[142:143] op_sel_hi:[1,0,1]
	v_pk_fma_f32 v[140:141], v[242:243], v[34:35], v[140:141] op_sel:[0,1,0]
	v_pk_fma_f32 v[142:143], v[250:251], v[34:35], v[142:143] op_sel:[0,1,0]
	v_add_f32_dpp v60, v62, v61 row_ror:8 row_mask:0xf bank_mask:0xf
	v_add_f32_dpp v36, v252, v252 quad_perm:[1,0,3,2] row_mask:0xf bank_mask:0xf
	v_add_f32_dpp v37, v253, v253 quad_perm:[1,0,3,2] row_mask:0xf bank_mask:0xf
	v_add_f32_dpp v38, v254, v254 quad_perm:[1,0,3,2] row_mask:0xf bank_mask:0xf
	v_add_f32_dpp v39, v255, v255 quad_perm:[1,0,3,2] row_mask:0xf bank_mask:0xf
	v_cndmask_b32_e32 v36, v38, v36, vcc
	v_cndmask_b32_e32 v37, v39, v37, vcc
	v_add_f32_dpp v42, v40, v40 quad_perm:[2,3,0,1] row_mask:0xf bank_mask:0xf
	v_add_f32_dpp v43, v41, v41 quad_perm:[2,3,0,1] row_mask:0xf bank_mask:0xf
	v_cndmask_b32_e64 v40, v43, v42, s[4:5]
	v_cndmask_b32_e64 v45, v40, v44, s[6:7]
	v_cndmask_b32_e64 v46, v44, v40, s[6:7]
	s_waitcnt vmcnt(7)
	v_pk_mul_f32 v[252:253], v[236:237], v[28:29] op_sel_hi:[1,0]
	v_pk_mul_f32 v[254:255], v[244:245], v[28:29] op_sel_hi:[1,0]
	v_pk_fma_f32 v[252:253], v[238:239], v[28:29], v[252:253] op_sel:[0,1,0]
	v_pk_fma_f32 v[254:255], v[246:247], v[28:29], v[254:255] op_sel:[0,1,0]
	v_pk_fma_f32 v[252:253], v[240:241], v[30:31], v[252:253] op_sel_hi:[1,0,1]
	v_pk_fma_f32 v[254:255], v[248:249], v[30:31], v[254:255] op_sel_hi:[1,0,1]
	v_pk_fma_f32 v[252:253], v[242:243], v[30:31], v[252:253] op_sel:[0,1,0]
	v_pk_fma_f32 v[254:255], v[250:251], v[30:31], v[254:255] op_sel:[0,1,0]
	v_add_f32_dpp v44, v46, v45 row_ror:4 row_mask:0xf bank_mask:0xf
	v_add_f32_dpp v32, v140, v140 quad_perm:[1,0,3,2] row_mask:0xf bank_mask:0xf
	v_add_f32_dpp v33, v141, v141 quad_perm:[1,0,3,2] row_mask:0xf bank_mask:0xf
	v_add_f32_dpp v34, v142, v142 quad_perm:[1,0,3,2] row_mask:0xf bank_mask:0xf
	v_add_f32_dpp v35, v143, v143 quad_perm:[1,0,3,2] row_mask:0xf bank_mask:0xf
	v_cndmask_b32_e32 v32, v34, v32, vcc
	v_cndmask_b32_e32 v33, v35, v33, vcc
	v_add_f32_dpp v38, v36, v36 quad_perm:[2,3,0,1] row_mask:0xf bank_mask:0xf
	v_add_f32_dpp v39, v37, v37 quad_perm:[2,3,0,1] row_mask:0xf bank_mask:0xf
	v_cndmask_b32_e64 v36, v39, v38, s[4:5]
	s_waitcnt vmcnt(6)
; DI void attn_sample_item(const Params& p, int item, ldsp lds, int tid_) {
;     ...
;   SC_SCORE(kvA, 0)
;   SC_SCORE(kvB, 1)
	v_pk_mul_f32 v[140:141], v[236:237], v[24:25] op_sel_hi:[1,0]
	v_pk_mul_f32 v[142:143], v[244:245], v[24:25] op_sel_hi:[1,0]
	v_pk_fma_f32 v[140:141], v[238:239], v[24:25], v[140:141] op_sel:[0,1,0]
	v_pk_fma_f32 v[142:143], v[246:247], v[24:25], v[142:143] op_sel:[0,1,0]
	v_pk_fma_f32 v[140:141], v[240:241], v[26:27], v[140:141] op_sel_hi:[1,0,1]
	v_pk_fma_f32 v[142:143], v[248:249], v[26:27], v[142:143] op_sel_hi:[1,0,1]
	v_pk_fma_f32 v[140:141], v[242:243], v[26:27], v[140:141] op_sel:[0,1,0]
	v_pk_fma_f32 v[142:143], v[250:251], v[26:27], v[142:143] op_sel:[0,1,0]
	v_add_f32_dpp v28, v252, v252 quad_perm:[1,0,3,2] row_mask:0xf bank_mask:0xf
	v_add_f32_dpp v29, v253, v253 quad_perm:[1,0,3,2] row_mask:0xf bank_mask:0xf
	v_add_f32_dpp v30, v254, v254 quad_perm:[1,0,3,2] row_mask:0xf bank_mask:0xf
	v_add_f32_dpp v31, v255, v255 quad_perm:[1,0,3,2] row_mask:0xf bank_mask:0xf
	v_cndmask_b32_e32 v28, v30, v28, vcc
	v_cndmask_b32_e32 v29, v31, v29, vcc
	v_add_f32_dpp v34, v32, v32 quad_perm:[2,3,0,1] row_mask:0xf bank_mask:0xf
	v_add_f32_dpp v35, v33, v33 quad_perm:[2,3,0,1] row_mask:0xf bank_mask:0xf
	v_cndmask_b32_e64 v32, v35, v34, s[4:5]
	v_cndmask_b32_e64 v37, v32, v36, s[6:7]
	v_cndmask_b32_e64 v38, v36, v32, s[6:7]
	s_waitcnt vmcnt(5)
	v_pk_mul_f32 v[252:253], v[236:237], v[20:21] op_sel_hi:[1,0]
	v_pk_mul_f32 v[254:255], v[244:245], v[20:21] op_sel_hi:[1,0]
	v_pk_fma_f32 v[252:253], v[238:239], v[20:21], v[252:253] op_sel:[0,1,0]
	v_pk_fma_f32 v[254:255], v[246:247], v[20:21], v[254:255] op_sel:[0,1,0]
	v_pk_fma_f32 v[252:253], v[240:241], v[22:23], v[252:253] op_sel_hi:[1,0,1]
	v_pk_fma_f32 v[254:255], v[248:249], v[22:23], v[254:255] op_sel_hi:[1,0,1]
	v_pk_fma_f32 v[252:253], v[242:243], v[22:23], v[252:253] op_sel:[0,1,0]
	v_pk_fma_f32 v[254:255], v[250:251], v[22:23], v[254:255] op_sel:[0,1,0]
	v_add_f32_dpp v36, v38, v37 row_ror:4 row_mask:0xf bank_mask:0xf
	v_cndmask_b32_e64 v45, v36, v44, s[64:65]
	v_cndmask_b32_e64 v46, v44, v36, s[64:65]
	v_add_f32_dpp v24, v140, v140 quad_perm:[1,0,3,2] row_mask:0xf bank_mask:0xf
	v_add_f32_dpp v25, v141, v141 quad_perm:[1,0,3,2] row_mask:0xf bank_mask:0xf
	v_add_f32_dpp v26, v142, v142 quad_perm:[1,0,3,2] row_mask:0xf bank_mask:0xf
	v_add_f32_dpp v27, v143, v143 quad_perm:[1,0,3,2] row_mask:0xf bank_mask:0xf
	v_cndmask_b32_e32 v24, v26, v24, vcc
	v_cndmask_b32_e32 v25, v27, v25, vcc
	v_add_f32_dpp v30, v28, v28 quad_perm:[2,3,0,1] row_mask:0xf bank_mask:0xf
	v_add_f32_dpp v31, v29, v29 quad_perm:[2,3,0,1] row_mask:0xf bank_mask:0xf
	v_cndmask_b32_e64 v28, v31, v30, s[4:5]
	s_waitcnt vmcnt(4)
	v_pk_mul_f32 v[140:141], v[236:237], v[16:17] op_sel_hi:[1,0]
	v_pk_mul_f32 v[142:143], v[244:245], v[16:17] op_sel_hi:[1,0]
	v_pk_fma_f32 v[140:141], v[238:239], v[16:17], v[140:141] op_sel:[0,1,0]
	v_pk_fma_f32 v[142:143], v[246:247], v[16:17], v[142:143] op_sel:[0,1,0]
	v_pk_fma_f32 v[140:141], v[240:241], v[18:19], v[140:141] op_sel_hi:[1,0,1]
	v_pk_fma_f32 v[142:143], v[248:249], v[18:19], v[142:143] op_sel_hi:[1,0,1]
	v_pk_fma_f32 v[140:141], v[242:243], v[18:19], v[140:141] op_sel:[0,1,0]
	v_pk_fma_f32 v[142:143], v[250:251], v[18:19], v[142:143] op_sel:[0,1,0]
	v_add_f32_dpp v44, v46, v45 row_ror:8 row_mask:0xf bank_mask:0xf
	v_add_f32_dpp v20, v252, v252 quad_perm:[1,0,3,2] row_mask:0xf bank_mask:0xf
	v_add_f32_dpp v21, v253, v253 quad_perm:[1,0,3,2] row_mask:0xf bank_mask:0xf
	v_add_f32_dpp v22, v254, v254 quad_perm:[1,0,3,2] row_mask:0xf bank_mask:0xf
	v_add_f32_dpp v23, v255, v255 quad_perm:[1,0,3,2] row_mask:0xf bank_mask:0xf
	v_cndmask_b32_e32 v20, v22, v20, vcc
	v_cndmask_b32_e32 v21, v23, v21, vcc
	v_add_f32_dpp v26, v24, v24 quad_perm:[2,3,0,1] row_mask:0xf bank_mask:0xf
	v_add_f32_dpp v27, v25, v25 quad_perm:[2,3,0,1] row_mask:0xf bank_mask:0xf
	v_cndmask_b32_e64 v24, v27, v26, s[4:5]
	v_cndmask_b32_e64 v29, v24, v28, s[6:7]
	v_cndmask_b32_e64 v30, v28, v24, s[6:7]
	s_waitcnt vmcnt(3)
	v_pk_mul_f32 v[252:253], v[236:237], v[12:13] op_sel_hi:[1,0]
	v_pk_mul_f32 v[254:255], v[244:245], v[12:13] op_sel_hi:[1,0]
	v_pk_fma_f32 v[252:253], v[238:239], v[12:13], v[252:253] op_sel:[0,1,0]
	v_pk_fma_f32 v[254:255], v[246:247], v[12:13], v[254:255] op_sel:[0,1,0]
	v_pk_fma_f32 v[252:253], v[240:241], v[14:15], v[252:253] op_sel_hi:[1,0,1]
	v_pk_fma_f32 v[254:255], v[248:249], v[14:15], v[254:255] op_sel_hi:[1,0,1]
	v_pk_fma_f32 v[252:253], v[242:243], v[14:15], v[252:253] op_sel:[0,1,0]
	v_pk_fma_f32 v[254:255], v[250:251], v[14:15], v[254:255] op_sel:[0,1,0]
	v_permlane16_swap_b32_e32 v60, v44
	v_add_f32_e32 v60, v60, v44
	v_add_f32_dpp v28, v30, v29 row_ror:4 row_mask:0xf bank_mask:0xf
	v_add_f32_dpp v16, v140, v140 quad_perm:[1,0,3,2] row_mask:0xf bank_mask:0xf
	v_add_f32_dpp v17, v141, v141 quad_perm:[1,0,3,2] row_mask:0xf bank_mask:0xf
	v_add_f32_dpp v18, v142, v142 quad_perm:[1,0,3,2] row_mask:0xf bank_mask:0xf
	v_add_f32_dpp v19, v143, v143 quad_perm:[1,0,3,2] row_mask:0xf bank_mask:0xf
	v_cndmask_b32_e32 v16, v18, v16, vcc
	v_cndmask_b32_e32 v17, v19, v17, vcc
	v_add_f32_dpp v22, v20, v20 quad_perm:[2,3,0,1] row_mask:0xf bank_mask:0xf
	v_add_f32_dpp v23, v21, v21 quad_perm:[2,3,0,1] row_mask:0xf bank_mask:0xf
	v_cndmask_b32_e64 v20, v23, v22, s[4:5]
	s_waitcnt vmcnt(2)
; DI void attn_sample_item(const Params& p, int item, ldsp lds, int tid_) {
;     ...
;   SC_SCORE(kvA, 0)
;   SC_SCORE(kvB, 1)
	v_pk_mul_f32 v[140:141], v[236:237], v[8:9] op_sel_hi:[1,0]
	v_pk_mul_f32 v[142:143], v[244:245], v[8:9] op_sel_hi:[1,0]
	v_pk_fma_f32 v[140:141], v[238:239], v[8:9], v[140:141] op_sel:[0,1,0]
	v_pk_fma_f32 v[142:143], v[246:247], v[8:9], v[142:143] op_sel:[0,1,0]
	v_pk_fma_f32 v[140:141], v[240:241], v[10:11], v[140:141] op_sel_hi:[1,0,1]
	v_pk_fma_f32 v[142:143], v[248:249], v[10:11], v[142:143] op_sel_hi:[1,0,1]
	v_pk_fma_f32 v[140:141], v[242:243], v[10:11], v[140:141] op_sel:[0,1,0]
	v_pk_fma_f32 v[142:143], v[250:251], v[10:11], v[142:143] op_sel:[0,1,0]
	v_add_f32_dpp v12, v252, v252 quad_perm:[1,0,3,2] row_mask:0xf bank_mask:0xf
	v_add_f32_dpp v13, v253, v253 quad_perm:[1,0,3,2] row_mask:0xf bank_mask:0xf
	v_add_f32_dpp v14, v254, v254 quad_perm:[1,0,3,2] row_mask:0xf bank_mask:0xf
	v_add_f32_dpp v15, v255, v255 quad_perm:[1,0,3,2] row_mask:0xf bank_mask:0xf
	v_cndmask_b32_e32 v12, v14, v12, vcc
	v_cndmask_b32_e32 v13, v15, v13, vcc
	v_add_f32_dpp v18, v16, v16 quad_perm:[2,3,0,1] row_mask:0xf bank_mask:0xf
	v_add_f32_dpp v19, v17, v17 quad_perm:[2,3,0,1] row_mask:0xf bank_mask:0xf
	v_cndmask_b32_e64 v16, v19, v18, s[4:5]
	v_cndmask_b32_e64 v21, v16, v20, s[6:7]
	v_cndmask_b32_e64 v22, v20, v16, s[6:7]
	s_waitcnt vmcnt(1)
	v_pk_mul_f32 v[252:253], v[236:237], v[4:5] op_sel_hi:[1,0]
	v_pk_mul_f32 v[254:255], v[244:245], v[4:5] op_sel_hi:[1,0]
	v_pk_fma_f32 v[252:253], v[238:239], v[4:5], v[252:253] op_sel:[0,1,0]
	v_pk_fma_f32 v[254:255], v[246:247], v[4:5], v[254:255] op_sel:[0,1,0]
	v_pk_fma_f32 v[252:253], v[240:241], v[6:7], v[252:253] op_sel_hi:[1,0,1]
	v_pk_fma_f32 v[254:255], v[248:249], v[6:7], v[254:255] op_sel_hi:[1,0,1]
	v_pk_fma_f32 v[252:253], v[242:243], v[6:7], v[252:253] op_sel:[0,1,0]
	v_pk_fma_f32 v[254:255], v[250:251], v[6:7], v[254:255] op_sel:[0,1,0]
	v_add_f32_dpp v20, v22, v21 row_ror:4 row_mask:0xf bank_mask:0xf
	v_cndmask_b32_e64 v29, v20, v28, s[64:65]
	v_cndmask_b32_e64 v30, v28, v20, s[64:65]
	v_add_f32_dpp v8, v140, v140 quad_perm:[1,0,3,2] row_mask:0xf bank_mask:0xf
	v_add_f32_dpp v9, v141, v141 quad_perm:[1,0,3,2] row_mask:0xf bank_mask:0xf
	v_add_f32_dpp v10, v142, v142 quad_perm:[1,0,3,2] row_mask:0xf bank_mask:0xf
	v_add_f32_dpp v11, v143, v143 quad_perm:[1,0,3,2] row_mask:0xf bank_mask:0xf
	v_cndmask_b32_e32 v8, v10, v8, vcc
	v_cndmask_b32_e32 v9, v11, v9, vcc
	v_add_f32_dpp v14, v12, v12 quad_perm:[2,3,0,1] row_mask:0xf bank_mask:0xf
	v_add_f32_dpp v15, v13, v13 quad_perm:[2,3,0,1] row_mask:0xf bank_mask:0xf
	v_cndmask_b32_e64 v12, v15, v14, s[4:5]
	s_waitcnt vmcnt(0)
; DI void lbar() { asm volatile("s_waitcnt lgkmcnt(0)" ::: "memory"); __builtin_amdgcn_s_barrier(); asm volatile("" ::: "memory"); }
; DI void attn_sample_item(const Params& p, int item, ldsp lds, int tid_) {
;     ...
;   SC_SCORE(kvA, 0)
;   SC_SCORE(kvB, 1)
;     ...
;   f32x4 vvA[16], vvB[16];
; #pragma unroll
;   for (int j = 0; j < 16; ++j) vvA[j] = __builtin_nontemporal_load((const f32x4*)(cv + (size_t)(wid * 32 + j) * 1024 + lane * 4));
;   lbar();
;     ...
; #pragma unroll
;   for (int j = 0; j < 16; ++j) vvB[j] = __builtin_nontemporal_load((const f32x4*)(cv + (size_t)(wid * 32 + 16 + j) * 1024 + lane * 4));
	v_pk_mul_f32 v[140:141], v[236:237], v[0:1] op_sel_hi:[1,0]
	v_pk_mul_f32 v[142:143], v[244:245], v[0:1] op_sel_hi:[1,0]
	v_pk_fma_f32 v[140:141], v[238:239], v[0:1], v[140:141] op_sel:[0,1,0]
	v_pk_fma_f32 v[142:143], v[246:247], v[0:1], v[142:143] op_sel:[0,1,0]
	v_pk_fma_f32 v[140:141], v[240:241], v[2:3], v[140:141] op_sel_hi:[1,0,1]
	v_pk_fma_f32 v[142:143], v[248:249], v[2:3], v[142:143] op_sel_hi:[1,0,1]
	v_pk_fma_f32 v[140:141], v[242:243], v[2:3], v[140:141] op_sel:[0,1,0]
	v_pk_fma_f32 v[142:143], v[250:251], v[2:3], v[142:143] op_sel:[0,1,0]
	v_add_f32_dpp v28, v30, v29 row_ror:8 row_mask:0xf bank_mask:0xf
	v_add_f32_dpp v4, v252, v252 quad_perm:[1,0,3,2] row_mask:0xf bank_mask:0xf
	v_add_f32_dpp v5, v253, v253 quad_perm:[1,0,3,2] row_mask:0xf bank_mask:0xf
	v_add_f32_dpp v6, v254, v254 quad_perm:[1,0,3,2] row_mask:0xf bank_mask:0xf
	v_add_f32_dpp v7, v255, v255 quad_perm:[1,0,3,2] row_mask:0xf bank_mask:0xf
	v_cndmask_b32_e32 v4, v6, v4, vcc
	v_cndmask_b32_e32 v5, v7, v5, vcc
	v_add_f32_dpp v10, v8, v8 quad_perm:[2,3,0,1] row_mask:0xf bank_mask:0xf
	v_add_f32_dpp v11, v9, v9 quad_perm:[2,3,0,1] row_mask:0xf bank_mask:0xf
	v_cndmask_b32_e64 v8, v11, v10, s[4:5]
	v_cndmask_b32_e64 v13, v8, v12, s[6:7]
	v_cndmask_b32_e64 v14, v12, v8, s[6:7]
	s_nop 1
	v_add_f32_dpp v12, v14, v13 row_ror:4 row_mask:0xf bank_mask:0xf
	v_add_f32_dpp v0, v140, v140 quad_perm:[1,0,3,2] row_mask:0xf bank_mask:0xf
	v_add_f32_dpp v1, v141, v141 quad_perm:[1,0,3,2] row_mask:0xf bank_mask:0xf
	v_add_f32_dpp v2, v142, v142 quad_perm:[1,0,3,2] row_mask:0xf bank_mask:0xf
	v_add_f32_dpp v3, v143, v143 quad_perm:[1,0,3,2] row_mask:0xf bank_mask:0xf
	v_cndmask_b32_e32 v0, v2, v0, vcc
	v_cndmask_b32_e32 v1, v3, v1, vcc
	v_add_f32_dpp v6, v4, v4 quad_perm:[2,3,0,1] row_mask:0xf bank_mask:0xf
	v_add_f32_dpp v7, v5, v5 quad_perm:[2,3,0,1] row_mask:0xf bank_mask:0xf
	v_cndmask_b32_e64 v4, v7, v6, s[4:5]
	v_add_f32_dpp v2, v0, v0 quad_perm:[2,3,0,1] row_mask:0xf bank_mask:0xf
	v_add_f32_dpp v3, v1, v1 quad_perm:[2,3,0,1] row_mask:0xf bank_mask:0xf
	v_cndmask_b32_e64 v0, v3, v2, s[4:5]
	v_cndmask_b32_e64 v5, v0, v4, s[6:7]
	v_cndmask_b32_e64 v6, v4, v0, s[6:7]
	s_nop 1
	v_add_f32_dpp v4, v6, v5 row_ror:4 row_mask:0xf bank_mask:0xf
	v_cndmask_b32_e64 v13, v4, v12, s[64:65]
	v_cndmask_b32_e64 v14, v12, v4, s[64:65]
	s_nop 1
	v_add_f32_dpp v12, v14, v13 row_ror:8 row_mask:0xf bank_mask:0xf
	s_nop 1
	v_permlane16_swap_b32_e32 v28, v12
	v_add_f32_e32 v28, v28, v12
	s_nop 1
	v_permlane32_swap_b32_e32 v60, v28
	v_add_f32_e32 v60, v60, v28
	ds_write_b32 v235, v60 offset:64
	v_add_u32_e32 v100, v158, v144
	global_load_dwordx4 v[100:103], v100, s[66:67] nt
	v_add_u32_e32 v92, v162, v144
	global_load_dwordx4 v[92:95], v92, s[66:67] nt
	v_add_u32_e32 v112, v164, v144
	global_load_dwordx4 v[112:115], v112, s[66:67] nt
	v_add_u32_e32 v108, v168, v144
	global_load_dwordx4 v[108:111], v108, s[66:67] nt
	v_add_u32_e32 v120, v172, v144
	global_load_dwordx4 v[120:123], v120, s[66:67] nt
	v_add_u32_e32 v116, v176, v144
	global_load_dwordx4 v[116:119], v116, s[66:67] nt
	v_add_u32_e32 v124, v180, v144
	global_load_dwordx4 v[124:127], v124, s[66:67] nt
	v_add_u32_e32 v104, v184, v144
	global_load_dwordx4 v[104:107], v104, s[66:67] nt
	v_add_u32_e32 v68, v188, v144
	global_load_dwordx4 v[68:71], v68, s[66:67] nt
	v_add_u32_e32 v64, v192, v144
	global_load_dwordx4 v[64:67], v64, s[66:67] nt
	v_add_u32_e32 v80, v196, v144
	global_load_dwordx4 v[80:83], v80, s[66:67] nt
	v_add_u32_e32 v76, v200, v144
	global_load_dwordx4 v[76:79], v76, s[66:67] nt
	v_add_u32_e32 v88, v202, v144
	global_load_dwordx4 v[88:91], v88, s[66:67] nt
	v_add_u32_e32 v84, v204, v144
	global_load_dwordx4 v[84:87], v84, s[66:67] nt
	v_add_u32_e32 v96, v206, v144
	global_load_dwordx4 v[96:99], v96, s[66:67] nt
	v_add_u32_e32 v72, v208, v144
	global_load_dwordx4 v[72:75], v72, s[66:67] nt
	v_add_u32_e32 v40, v146, v144
	global_load_dwordx4 v[40:43], v40, s[66:67] nt
	v_add_u32_e32 v36, v148, v144
	global_load_dwordx4 v[36:39], v36, s[66:67] nt
	v_add_u32_e32 v48, v150, v144
	global_load_dwordx4 v[48:51], v48, s[66:67] nt
	v_add_u32_e32 v44, v152, v144
	global_load_dwordx4 v[44:47], v44, s[66:67] nt
	v_add_u32_e32 v56, v154, v144
	global_load_dwordx4 v[56:59], v56, s[66:67] nt
	v_add_u32_e32 v52, v156, v144
	global_load_dwordx4 v[52:55], v52, s[66:67] nt
	v_add_u32_e32 v60, v160, v144
	global_load_dwordx4 v[60:63], v60, s[66:67] nt
	v_add_u32_e32 v32, v166, v144
	global_load_dwordx4 v[32:35], v32, s[66:67] nt
	v_add_u32_e32 v12, v170, v144
	global_load_dwordx4 v[12:15], v12, s[66:67] nt
	v_add_u32_e32 v4, v174, v144
	global_load_dwordx4 v[4:7], v4, s[66:67] nt
	v_add_u32_e32 v20, v178, v144
	global_load_dwordx4 v[20:23], v20, s[66:67] nt
	v_add_u32_e32 v8, v182, v144
	global_load_dwordx4 v[8:11], v8, s[66:67] nt
	v_add_u32_e32 v24, v186, v144
	global_load_dwordx4 v[24:27], v24, s[66:67] nt
	v_add_u32_e32 v16, v190, v144
	global_load_dwordx4 v[16:19], v16, s[66:67] nt
	v_add_u32_e32 v28, v194, v144
	global_load_dwordx4 v[28:31], v28, s[66:67] nt
	v_add_u32_e32 v0, v198, v144
	global_load_dwordx4 v[0:3], v0, s[66:67] nt
	v_lshlrev_b32_e32 v240, 2, v223
	s_waitcnt lgkmcnt(0)
	s_barrier
	v_cmp_gt_i32_e32 vcc, 4, v210
	s_and_saveexec_b64 s[4:5], vcc
	s_cbranch_execz .LBB0_1675

; DI float wave_sum(float v) { for (int o = 32; o >= 1; o >>= 1) v += __shfl_xor(v, o); return v; }
; DI void attn_sample_item(const Params& p, int item, ldsp lds, int tid_) {
;     ...
;   if (wid < 4) {
;     float v[4]; float mx = -1e30f;
; #pragma unroll
;     for (int j = 0; j < 4; ++j) { v[j] = SC[wid * 256 + j * 64 + lane]; mx = fmaxf(mx, v[j]); }
;     for (int o = 32; o >= 1; o >>= 1) mx = fmaxf(mx, __shfl_xor(mx, o));
;     float s = 0.f;
; #pragma unroll
;     for (int j = 0; j < 4; ++j) { v[j] = __expf(v[j] - mx); s += v[j]; }
;     s = wave_sum(s); const float inv = 1.f / s;
; #pragma unroll
;     for (int j = 0; j < 4; ++j) SC[wid * 256 + j * 64 + lane] = v[j] * inv;
;   }
	v_lshlrev_b32_e32 v241, 10, v210
	v_add3_u32 v244, 16, v241, v240
	ds_read2st64_b32 v[240:241], v244 offset1:1
	ds_read2st64_b32 v[242:243], v244 offset0:2 offset1:3
	s_waitcnt lgkmcnt(1)
	v_max3_f32 v245, v240, s35, v241
	s_waitcnt lgkmcnt(0)
	v_max3_f32 v245, v245, v242, v243
	ds_bpermute_b32 v246, v133, v245
	s_waitcnt lgkmcnt(0)
	v_max_f32_e32 v246, v246, v246
	v_max_f32_e32 v245, v245, v246
	ds_bpermute_b32 v246, v132, v245
	s_waitcnt lgkmcnt(0)
	v_max_f32_e32 v246, v246, v246
	v_max_f32_e32 v245, v245, v246
	ds_bpermute_b32 v246, v131, v245
	s_waitcnt lgkmcnt(0)
	v_max_f32_e32 v246, v246, v246
	v_max_f32_e32 v245, v245, v246
	ds_bpermute_b32 v246, v130, v245
	s_waitcnt lgkmcnt(0)
	v_max_f32_e32 v246, v246, v246
	v_max_f32_e32 v245, v245, v246
	ds_bpermute_b32 v246, v129, v245
	s_waitcnt lgkmcnt(0)
	v_max_f32_e32 v246, v246, v246
	v_max_f32_e32 v245, v245, v246
	ds_bpermute_b32 v246, v128, v245
	s_waitcnt lgkmcnt(0)
	v_max_f32_e32 v246, v246, v246
	v_max_f32_e32 v245, v245, v246
	v_sub_f32_e32 v240, v240, v245
	v_sub_f32_e32 v241, v241, v245
	v_mul_f32_e32 v240, 0x3fb8aa3b, v240
	v_sub_f32_e32 v242, v242, v245
	v_mul_f32_e32 v241, 0x3fb8aa3b, v241
	v_exp_f32_e32 v240, v240
	v_sub_f32_e32 v243, v243, v245
	v_mul_f32_e32 v242, 0x3fb8aa3b, v242
	v_exp_f32_e32 v241, v241
	v_mul_f32_e32 v243, 0x3fb8aa3b, v243
	v_exp_f32_e32 v242, v242
	v_exp_f32_e32 v243, v243
	v_add_f32_e32 v245, 0, v240
	v_add_f32_e32 v245, v241, v245
	v_add_f32_e32 v245, v242, v245
	v_add_f32_e32 v245, v243, v245
	ds_bpermute_b32 v246, v133, v245
	s_waitcnt lgkmcnt(0)
	v_add_f32_e32 v245, v245, v246
	ds_bpermute_b32 v246, v132, v245
	s_waitcnt lgkmcnt(0)
	v_add_f32_e32 v245, v245, v246
	ds_bpermute_b32 v246, v131, v245
	s_waitcnt lgkmcnt(0)
	v_add_f32_e32 v245, v245, v246
	ds_bpermute_b32 v246, v130, v245
	s_waitcnt lgkmcnt(0)
	v_add_f32_e32 v245, v245, v246
	ds_bpermute_b32 v246, v129, v245
	s_waitcnt lgkmcnt(0)
	v_add_f32_e32 v245, v245, v246
	ds_bpermute_b32 v246, v128, v245
	s_waitcnt lgkmcnt(0)
	v_add_f32_e32 v245, v245, v246
	v_div_scale_f32 v246, s[6:7], v245, v245, 1.0
	v_rcp_f32_e32 v247, v246
	v_div_scale_f32 v248, vcc, 1.0, v245, 1.0
	v_fma_f32 v249, -v246, v247, 1.0
	v_fmac_f32_e32 v247, v249, v247
	v_mul_f32_e32 v249, v248, v247
	v_fma_f32 v250, -v246, v249, v248
	v_fmac_f32_e32 v249, v250, v247
	v_fma_f32 v246, -v246, v249, v248
	v_div_fmas_f32 v246, v246, v247, v249
	v_div_fixup_f32 v245, v246, v245, 1.0
	v_mul_f32_e32 v240, v240, v245
	v_mul_f32_e32 v241, v241, v245
	v_mul_f32_e32 v242, v242, v245
	v_mul_f32_e32 v243, v243, v245
	ds_write2st64_b32 v244, v240, v241 offset1:1
	ds_write2st64_b32 v244, v242, v243 offset0:2 offset1:3
	s_branch .LBB0_1675
